# v4scan
# speedup vs baseline: 1.0290x; 1.0290x over previous
; #define LAS __attribute__((address_space(3)))
; __device__ __forceinline__ unsigned xb_add(unsigned* p, unsigned v) { return __hip_atomic_fetch_add(p, v, __ATOMIC_RELAXED, __HIP_MEMORY_SCOPE_AGENT); }
; __device__ __forceinline__ unsigned xb_xcc_id() { return (unsigned)__builtin_amdgcn_s_getreg((3 << 11) | 20) & 0xFu; }
; #define LOAD_PARAMS(q_) const __attribute__((address_space(4))) Params* kq_##q_ = (const __attribute__((address_space(4))) Params*)__builtin_amdgcn_kernarg_segment_ptr(); asm volatile("" : "+s"(kq_##q_)); \
;     const Params q_ = *kq_##q_
; __device__ __forceinline__ XcdBarrier xcd_barrier_post(unsigned* bar, volatile LAS unsigned* st) {
;     XcdBarrier b; b.bar = bar; b.x = xb_xcc_id(); b.st = st;
;     if (threadIdx.x == 0) (void)xb_add(&bar[XB_XCNT(b.x)], 1u);
;     return b;
; }
; __global__ void __launch_bounds__(NTHREADS, 2) mega_fwd(Params p_unused) {
;     extern __shared__ __attribute__((aligned(16))) unsigned char smem[];
;     LAS unsigned char* lds = (LAS unsigned char*)smem;
;     cg::grid_group grid = cg::this_grid();
;     ...
;     volatile LAS unsigned* xst = (volatile LAS unsigned*)(lds + LDS_BYTES - 16);
;     if (threadIdx.x < 4) xst[threadIdx.x] = 0u;
;     __syncthreads();
;     XcdBarrier gbar; { LOAD_PARAMS(p0_); gbar = xcd_barrier_post((unsigned*)(p0_.ws + O_BAR), xst); }
_Z8mega_fwd6Params:
	s_mov_b32 s101, 0
	v_readfirstlane_b32 s100, v0
	s_bfe_u32 s100, s100, 0x10008
	s_load_dwordx2 s[96:97], s[0:1], 0x98
	v_writelane_b32 v253, s2, 0
	s_add_u32 s2, s0, 0x98
	s_addc_u32 s3, s1, 0
	v_writelane_b32 v253, s2, 1
	v_and_b32_e32 v199, 0x3ff, v0
	v_cmp_gt_u32_e32 vcc, 4, v199
	v_writelane_b32 v253, s3, 2
	s_and_saveexec_b64 s[4:5], vcc
	v_lshl_add_u32 v1, v199, 2, 0
	v_add_u32_e32 v1, 0x22ff0, v1
	v_mov_b32_e32 v2, 0
	ds_write_b32 v1, v2
	s_or_b64 exec, exec, s[4:5]
	s_mov_b64 s[2:3], s[0:1]
	s_waitcnt lgkmcnt(0)
	s_barrier
	s_load_dwordx2 s[4:5], s[2:3], 0x90
	s_getreg_b32 s2, hwreg(HW_REG_XCC_ID, 0, 4)
	s_mov_b32 s29, 0
	s_waitcnt lgkmcnt(0)
	s_add_u32 s8, s4, 0x36aa0000
	v_writelane_b32 v253, s4, 3
	s_addc_u32 s9, s5, 0
	s_and_b32 s10, s2, 15
	v_writelane_b32 v253, s5, 4
	v_cmp_eq_u32_e64 s[2:3], 0, v199
	s_mov_b64 s[6:7], exec
	s_nop 0
	v_writelane_b32 v253, s2, 5
	s_nop 1
	v_writelane_b32 v253, s3, 6
	s_and_b64 s[2:3], s[6:7], s[2:3]
	s_mov_b64 exec, s[2:3]
	s_cbranch_execz .LBB0_5
	s_mov_b64 s[2:3], exec
	v_mbcnt_lo_u32_b32 v1, s2, 0
	v_mbcnt_hi_u32_b32 v1, s3, v1
	v_cmp_eq_u32_e32 vcc, 0, v1
	s_and_b64 s[4:5], exec, vcc
	s_mov_b64 exec, s[4:5]
	s_cbranch_execz .LBB0_5
	s_lshl_b32 s4, s10, 8
	s_bcnt1_i32_b64 s2, s[2:3]
	v_mov_b32_e32 v1, s4
	v_mov_b32_e32 v2, s2
	global_atomic_add v1, v2, s[8:9] offset:1024

; #define LAS __attribute__((address_space(3)))
; __device__ __forceinline__ int otid() { int t = threadIdx.x; asm volatile("" : "+v"(t)); return t; }
; __device__ __forceinline__ int obid() { int t = blockIdx.x; asm volatile("" : "+s"(t)); return t; }
; __device__ __forceinline__ int ogdim() { int t = gridDim.x; asm volatile("" : "+s"(t)); return t; }
; __device__ __forceinline__ void transpose_w(LAS unsigned char* lds, const float* __restrict__ src, int ld_src, int K, int Npad, bf16_t* __restrict__ dst, int mode, const float* __restrict__ scale) {
;     LAS float* t = (LAS float*)lds;
;     const int tid = otid(), ntn = Npad / 256, ntiles = ntn * (K / 64);
;     for (int id = obid(); id < ntiles; id += ogdim()) {
;         const int n0 = (id % ntn) * 256, k0 = (id / ntn) * 64;
;         const int n = tid & 255, kq = tid >> 8, col = src_col(mode, n0 + n);
;         float v[32];
;         const float* sp = src + (size_t)(k0 + kq) * ld_src + (col >= 0 ? col : 0);
; #pragma unroll
;         for (int i = 0; i < 32; ++i) v[i] = sp[(size_t)(2 * i) * ld_src];
; #pragma unroll
;         for (int i = 0; i < 32; ++i) { float x = col >= 0 ? v[i] : 0.f; if (scale) x *= scale[k0 + kq + 2 * i]; t[(kq + 2 * i) * 257 + n] = x; }
.LBB0_32:
	s_lshr_b32 s34, s23, 6
	v_mov_b32_e32 v6, v199
	s_mul_i32 s34, s34, s20
	v_readlane_b32 s35, v253, 0
	v_readlane_b32 s98, v253, 11
	v_readlane_b32 s99, v253, 12
	s_nop 4
	s_load_dword s98, s[98:99], 0x98
	s_waitcnt lgkmcnt(0)
	s_add_i32 s35, s35, s101
	s_cmp_ge_u32 s35, s98
	s_cselect_b32 s99, s98, 0
	s_sub_i32 s35, s35, s99
	s_add_i32 s101, s101, s34
.Lmy_rot0:
	s_cmp_lt_u32 s101, s98
	s_cbranch_scc1 .Lmy_rot0_done
	s_sub_i32 s101, s101, s98
	s_branch .Lmy_rot0
.Lmy_rot0_done:
	s_cmp_ge_i32 s35, s34
	s_cbranch_scc1 .LBB0_7
	v_cvt_f32_u32_e32 v15, s20
	v_add_u32_e32 v16, 0x400, v6
	s_lshl_b32 s28, s21, 1
	s_cmp_lg_u64 s[38:39], 0
	v_rcp_iflag_f32_e32 v17, v15
	v_ashrrev_i32_e32 v15, 3, v16
	v_lshlrev_b32_e32 v2, 3, v6
	v_and_b32_e32 v11, 0xff, v6
	v_mul_f32_e32 v16, 0x4f7ffffe, v17
	v_cvt_u32_f32_e32 v17, v16
	v_ashrrev_i32_e32 v12, 8, v6
	s_cselect_b64 s[40:41], -1, 0
	v_and_b32_e32 v8, 56, v2
	v_ashrrev_i32_e32 v13, 3, v6
	v_add_u32_e32 v14, 0x200, v6
	v_add_u32_e32 v6, 0x600, v6
	s_sub_i32 s0, 0, s20
	v_readfirstlane_b32 s1, v17
	v_lshlrev_b32_e32 v2, 1, v8
	v_ashrrev_i32_e32 v14, 3, v14
	v_ashrrev_i32_e32 v16, 3, v6
	s_mul_i32 s0, s0, s1
	v_lshl_add_u32 v7, v11, 2, 0
	v_lshl_add_u64 v[4:5], s[4:5], 0, v[2:3]
	v_mul_i32_i24_e32 v2, 0x404, v12
	v_mul_u32_u24_e32 v8, 0x404, v8
	v_lshl_add_u32 v9, v13, 2, 0
	v_lshl_add_u32 v18, v14, 2, 0
	v_lshl_add_u32 v19, v15, 2, 0
	v_lshl_add_u32 v6, v16, 2, 0
	s_mul_hi_u32 s0, s1, s0
	s_lshl_b32 s42, s21, 2
	s_mov_b32 s43, s29
	s_mul_i32 s44, s21, 6
	s_mov_b32 s45, s29
	s_lshl_b32 s46, s21, 3
	s_mov_b32 s47, s29
	s_mul_i32 s48, s21, 10
	s_mov_b32 s49, s29
	s_mul_i32 s50, s21, 12
	s_mov_b32 s51, s29
	s_mul_i32 s52, s21, 14
	s_mov_b32 s53, s29
	s_lshl_b32 s54, s21, 4
	s_mov_b32 s55, s29
	s_mul_i32 s56, s21, 18
	s_mov_b32 s57, s29
	s_mul_i32 s58, s21, 20
	s_mov_b32 s59, s29
	s_mul_i32 s60, s21, 22
	s_mov_b32 s61, s29
	s_mul_i32 s62, s21, 24
	s_mov_b32 s63, s29
	s_mul_i32 s64, s21, 26
	s_mov_b32 s65, s29
	s_mul_i32 s66, s21, 28
	s_mov_b32 s67, s29
	s_mul_i32 s68, s21, 30
	s_mov_b32 s69, s29
	s_lshl_b32 s70, s21, 5
	s_mov_b32 s71, s29
	s_mul_i32 s72, s21, 34
	s_mov_b32 s73, s29
	s_mul_i32 s74, s21, 36
	s_mov_b32 s75, s29
	s_mul_i32 s76, s21, 38
	s_mov_b32 s77, s29
	s_mul_i32 s78, s21, 40
	s_mov_b32 s79, s29
	s_mul_i32 s80, s21, 42
	s_mov_b32 s81, s29
	s_mul_i32 s82, s21, 44
	s_mov_b32 s83, s29
	s_mul_i32 s84, s21, 46
	s_mov_b32 s85, s29
	s_mul_i32 s86, s21, 48
	s_mov_b32 s87, s29
	s_mul_i32 s88, s21, 50
	s_mov_b32 s89, s29
	s_mul_i32 s90, s21, 52
	s_mov_b32 s91, s29
	s_mul_i32 s92, s21, 54
	s_mov_b32 s93, s29
	s_mul_i32 s94, s21, 56
	s_mov_b32 s95, s29
	s_waitcnt lgkmcnt(0)
	s_mul_i32 s96, s21, 58
	s_mov_b32 s97, s29
	s_mul_i32 s24, s21, 60
	s_mov_b32 s25, s29
	s_mul_i32 s2, s21, 62
	s_mov_b32 s3, s29
	s_add_i32 s26, s1, s0
	v_add_u32_e32 v17, v9, v8
	v_add_u32_e32 v18, v18, v8
	v_add_u32_e32 v19, v19, v8
	v_add_u32_e32 v20, v6, v8
	v_add_u32_e32 v21, v7, v2
	s_branch .LBB0_35

; #define LAS __attribute__((address_space(3)))
; __device__ __forceinline__ int otid() { int t = threadIdx.x; asm volatile("" : "+v"(t)); return t; }
; __device__ __forceinline__ int obid() { int t = blockIdx.x; asm volatile("" : "+s"(t)); return t; }
; __device__ __forceinline__ int ogdim() { int t = gridDim.x; asm volatile("" : "+s"(t)); return t; }
; __device__ __forceinline__ void transpose_w8(LAS unsigned char* lds, const float* __restrict__ src, int ld_src, int K, int N, int col0, unsigned char* __restrict__ dst8, const float* __restrict__ scale) {
;     LAS float* t = (LAS float*)lds;
;     const int tid = otid(), ntn = N / 256, ntiles = ntn * (K / 64);
;     for (int id = obid(); id < ntiles; id += ogdim()) {
;         const int n0 = (id % ntn) * 256, k0 = (id / ntn) * 64;
; __global__ void __launch_bounds__(NTHREADS, 2) mega_fwd(Params p_unused) {
;     ...
;                 for (int ll = 0; ll < DEPTH; ++ll) { int l2 = ll; asm volatile("" : "+s"(l2));
;                     transpose_w8(lds, p.w_in + (size_t)l2 * DM * N_IN, N_IN, DM, 2048, 0, ws + O_WG8 + (size_t)l2 * 8192 * 2048, p.norm_g + l2 * DM);
.LBB0_111:
	s_ashr_i32 s11, s10, 31
	s_mul_i32 s1, s10, 0x68a0000
	s_mul_hi_i32 s0, s10, 0x68a0000
	s_add_u32 s22, s26, s1
	s_addc_u32 s23, s27, s0
	s_lshl_b64 s[0:1], s[10:11], 24
	s_add_u32 s14, s24, s0
	s_addc_u32 s15, s25, s1
	s_lshl_b32 s0, s10, 11
	s_ashr_i32 s1, s0, 31
	s_lshl_b64 s[0:1], s[0:1], 2
	s_add_u32 s12, s18, s0
	s_addc_u32 s13, s19, s1
	v_mov_b32_e32 v4, v199
	v_readlane_b32 s2, v253, 0
	v_readlane_b32 s98, v253, 11
	v_readlane_b32 s99, v253, 12
	s_nop 4
	s_load_dword s98, s[98:99], 0x98
	s_waitcnt lgkmcnt(0)
	s_add_i32 s2, s2, s101
	s_cmp_ge_u32 s2, s98
	s_cselect_b32 s99, s98, 0
	s_sub_i32 s2, s2, s99
	s_add_i32 s101, s101, 0x100

; #define LAS __attribute__((address_space(3)))
; __device__ __forceinline__ int otid() { int t = threadIdx.x; asm volatile("" : "+v"(t)); return t; }
; __device__ __forceinline__ int obid() { int t = blockIdx.x; asm volatile("" : "+s"(t)); return t; }
; __device__ __forceinline__ int ogdim() { int t = gridDim.x; asm volatile("" : "+s"(t)); return t; }
; __device__ __forceinline__ void transpose_w8(LAS unsigned char* lds, const float* __restrict__ src, int ld_src, int K, int N, int col0, unsigned char* __restrict__ dst8, const float* __restrict__ scale) {
;     LAS float* t = (LAS float*)lds;
;     const int tid = otid(), ntn = N / 256, ntiles = ntn * (K / 64);
;     for (int id = obid(); id < ntiles; id += ogdim()) {
;         const int n0 = (id % ntn) * 256, k0 = (id / ntn) * 64;
;         const int n = tid & 255, kq = tid >> 8;
;         float v[32];
;         const float* sp = src + (size_t)(k0 + kq) * ld_src + col0 + n0 + n;
; #pragma unroll
;         for (int i = 0; i < 32; ++i) v[i] = sp[(size_t)(2 * i) * ld_src];
; #pragma unroll
;         for (int i = 0; i < 32; ++i) t[(kq + 2 * i) * 257 + n] = v[i] * (scale ? 32.f * scale[k0 + kq + 2 * i] : 16.f);
.Lmy_rot1_done:
	s_cmpk_gt_i32 s2, 0xff
	s_cbranch_scc1 .LBB0_178
	v_and_b32_e32 v6, 0xff, v4
	v_ashrrev_i32_e32 v46, 8, v4
	v_lshlrev_b32_e32 v2, 4, v4
	v_ashrrev_i32_e32 v47, 2, v4
	v_and_b32_e32 v5, -4, v4
	v_add_u32_e32 v4, 0x200, v4
	v_and_b32_e32 v10, 48, v2
	v_ashrrev_i32_e32 v48, 2, v4
	v_and_b32_e32 v4, -4, v4
	v_lshl_add_u32 v7, v6, 2, 0
	v_mul_i32_i24_e32 v8, 0x404, v46
	v_add_u32_e32 v9, 0, v5
	v_mul_u32_u24_e32 v12, 0x404, v10
	v_add_u32_e32 v14, 0, v4
	v_lshl_add_u64 v[2:3], s[14:15], 0, v[10:11]
	v_mov_b64_e32 v[4:5], s[22:23]
	v_lshlrev_b32_e32 v10, 2, v6
	v_add_u32_e32 v49, v9, v12
	v_add_u32_e32 v50, v14, v12
	v_add_u32_e32 v51, v7, v8
	s_branch .LBB0_115

; #define LAS __attribute__((address_space(3)))
; __device__ __forceinline__ int otid() { int t = threadIdx.x; asm volatile("" : "+v"(t)); return t; }
; __device__ __forceinline__ int obid() { int t = blockIdx.x; asm volatile("" : "+s"(t)); return t; }
; __device__ __forceinline__ int ogdim() { int t = gridDim.x; asm volatile("" : "+s"(t)); return t; }
; __device__ __forceinline__ void transpose_w8(LAS unsigned char* lds, const float* __restrict__ src, int ld_src, int K, int N, int col0, unsigned char* __restrict__ dst8, const float* __restrict__ scale) {
;     LAS float* t = (LAS float*)lds;
;     const int tid = otid(), ntn = N / 256, ntiles = ntn * (K / 64);
;     for (int id = obid(); id < ntiles; id += ogdim()) {
;         const int n0 = (id % ntn) * 256, k0 = (id / ntn) * 64;
; __global__ void __launch_bounds__(NTHREADS, 2) mega_fwd(Params p_unused) {
;     ...
;                 for (int ll = 0; ll < DEPTH; ++ll) { int l2 = ll; asm volatile("" : "+s"(l2));
;                     transpose_w8(lds, p.w_in + (size_t)l2 * DM * N_IN, N_IN, DM, 2048, 0, ws + O_WG8 + (size_t)l2 * 8192 * 2048, p.norm_g + l2 * DM);
;                     transpose_w8(lds, p.w_in + (size_t)l2 * DM * N_IN, N_IN, DM, 6144, NGATE_SRC, ws + O_WG8 + (size_t)l2 * 8192 * 2048 + (size_t)2048 * 2048, p.norm_g + l2 * DM);
.LBB0_178:
	v_mov_b32_e32 v4, v199
	v_readlane_b32 s2, v253, 0
	v_readlane_b32 s98, v253, 11
	v_readlane_b32 s99, v253, 12
	s_nop 4
	s_load_dword s98, s[98:99], 0x98
	s_waitcnt lgkmcnt(0)
	s_add_i32 s2, s2, s101
	s_cmp_ge_u32 s2, s98
	s_cselect_b32 s99, s98, 0
	s_sub_i32 s2, s2, s99
	s_add_i32 s101, s101, 0x300

; #define LAS __attribute__((address_space(3)))
; __device__ __forceinline__ int otid() { int t = threadIdx.x; asm volatile("" : "+v"(t)); return t; }
; __device__ __forceinline__ int obid() { int t = blockIdx.x; asm volatile("" : "+s"(t)); return t; }
; __device__ __forceinline__ int ogdim() { int t = gridDim.x; asm volatile("" : "+s"(t)); return t; }
; __device__ __forceinline__ void transpose_w8(LAS unsigned char* lds, const float* __restrict__ src, int ld_src, int K, int N, int col0, unsigned char* __restrict__ dst8, const float* __restrict__ scale) {
;     LAS float* t = (LAS float*)lds;
;     const int tid = otid(), ntn = N / 256, ntiles = ntn * (K / 64);
;     for (int id = obid(); id < ntiles; id += ogdim()) {
;         const int n0 = (id % ntn) * 256, k0 = (id / ntn) * 64;
;         const int n = tid & 255, kq = tid >> 8;
;         float v[32];
;         const float* sp = src + (size_t)(k0 + kq) * ld_src + col0 + n0 + n;
; #pragma unroll
;         for (int i = 0; i < 32; ++i) v[i] = sp[(size_t)(2 * i) * ld_src];
; #pragma unroll
;         for (int i = 0; i < 32; ++i) t[(kq + 2 * i) * 257 + n] = v[i] * (scale ? 32.f * scale[k0 + kq + 2 * i] : 16.f);
.Lmy_rot2_done:
	s_cmpk_gt_i32 s2, 0x2ff
	s_cbranch_scc1 .LBB0_245
	v_and_b32_e32 v6, 0xff, v4
	v_ashrrev_i32_e32 v44, 8, v4
	v_lshlrev_b32_e32 v2, 4, v4
	v_ashrrev_i32_e32 v45, 2, v4
	v_and_b32_e32 v8, -4, v4
	v_add_u32_e32 v4, 0x200, v4
	v_and_b32_e32 v10, 48, v2
	v_ashrrev_i32_e32 v46, 2, v4
	v_and_b32_e32 v4, -4, v4
	s_add_u32 s22, s22, 0x7140
	v_lshl_add_u32 v5, v6, 2, 0
	v_lshl_add_u64 v[2:3], s[14:15], 0, v[10:11]
	s_mov_b64 s[0:1], 0x400000
	v_mul_i32_i24_e32 v7, 0x404, v44
	v_add_u32_e32 v8, 0, v8
	v_mul_u32_u24_e32 v9, 0x404, v10
	v_add_u32_e32 v4, 0, v4
	s_addc_u32 s23, s23, 0
	v_lshl_add_u64 v[2:3], v[2:3], 0, s[0:1]
	v_lshlrev_b32_e32 v10, 2, v6
	v_add_u32_e32 v47, v8, v9
	v_add_u32_e32 v48, v4, v9
	v_add_u32_e32 v49, v5, v7
	s_branch .LBB0_182

; #define LAS __attribute__((address_space(3)))
; __device__ __forceinline__ int otid() { int t = threadIdx.x; asm volatile("" : "+v"(t)); return t; }
; __device__ __forceinline__ int obid() { int t = blockIdx.x; asm volatile("" : "+s"(t)); return t; }
; __device__ __forceinline__ int ogdim() { int t = gridDim.x; asm volatile("" : "+s"(t)); return t; }
; __device__ __forceinline__ void transpose_w8(LAS unsigned char* lds, const float* __restrict__ src, int ld_src, int K, int N, int col0, unsigned char* __restrict__ dst8, const float* __restrict__ scale) {
;     LAS float* t = (LAS float*)lds;
;     const int tid = otid(), ntn = N / 256, ntiles = ntn * (K / 64);
;     for (int id = obid(); id < ntiles; id += ogdim()) {
;         const int n0 = (id % ntn) * 256, k0 = (id / ntn) * 64;
; __global__ void __launch_bounds__(NTHREADS, 2) mega_fwd(Params p_unused) {
;     ...
;                 for (int ll = 0; ll < DEPTH; ++ll) { int l2 = ll; asm volatile("" : "+s"(l2));
;                     transpose_w8(lds, p.w_in + (size_t)l2 * DM * N_IN, N_IN, DM, 2048, 0, ws + O_WG8 + (size_t)l2 * 8192 * 2048, p.norm_g + l2 * DM);
;                     transpose_w8(lds, p.w_in + (size_t)l2 * DM * N_IN, N_IN, DM, 6144, NGATE_SRC, ws + O_WG8 + (size_t)l2 * 8192 * 2048 + (size_t)2048 * 2048, p.norm_g + l2 * DM);
;                     transpose_w8(lds, p.w_branch + (size_t)l2 * 3 * 1024 * 2048, 2048, 1024, 2048, 0, ws + O_WA8 + (size_t)l2 * 2048 * 1024, nullptr); }
.LBB0_245:
	v_mov_b32_e32 v2, v199
	v_readlane_b32 s0, v253, 0
	v_readlane_b32 s98, v253, 11
	v_readlane_b32 s99, v253, 12
	s_nop 4
	s_load_dword s98, s[98:99], 0x98
	s_waitcnt lgkmcnt(0)
	s_add_i32 s0, s0, s101
	s_cmp_ge_u32 s0, s98
	s_cselect_b32 s99, s98, 0
	s_sub_i32 s0, s0, s99
	s_add_i32 s101, s101, 0x80

; #define LAS __attribute__((address_space(3)))
; __device__ __forceinline__ int otid() { int t = threadIdx.x; asm volatile("" : "+v"(t)); return t; }
; __device__ __forceinline__ int obid() { int t = blockIdx.x; asm volatile("" : "+s"(t)); return t; }
; __device__ __forceinline__ int ogdim() { int t = gridDim.x; asm volatile("" : "+s"(t)); return t; }
; __device__ __forceinline__ void transpose_w8(LAS unsigned char* lds, const float* __restrict__ src, int ld_src, int K, int N, int col0, unsigned char* __restrict__ dst8, const float* __restrict__ scale) {
;     LAS float* t = (LAS float*)lds;
;     const int tid = otid(), ntn = N / 256, ntiles = ntn * (K / 64);
;     for (int id = obid(); id < ntiles; id += ogdim()) {
;         const int n0 = (id % ntn) * 256, k0 = (id / ntn) * 64;
;         const int n = tid & 255, kq = tid >> 8;
;         float v[32];
;         const float* sp = src + (size_t)(k0 + kq) * ld_src + col0 + n0 + n;
; #pragma unroll
;         for (int i = 0; i < 32; ++i) v[i] = sp[(size_t)(2 * i) * ld_src];
; #pragma unroll
;         for (int i = 0; i < 32; ++i) t[(kq + 2 * i) * 257 + n] = v[i] * (scale ? 32.f * scale[k0 + kq + 2 * i] : 16.f);
; __global__ void __launch_bounds__(NTHREADS, 2) mega_fwd(Params p_unused) {
;     ...
;                     transpose_w8(lds, p.w_branch + (size_t)l2 * 3 * 1024 * 2048, 2048, 1024, 2048, 0, ws + O_WA8 + (size_t)l2 * 2048 * 1024, nullptr); }
.Lmy_rot3_done:
	s_cmpk_gt_i32 s0, 0x7f
	s_cbranch_scc1 .LBB0_110
	v_readlane_b32 s12, v253, 15
	v_readlane_b32 s13, v253, 16
	s_mul_i32 s2, s10, 0x1800000
	s_mov_b64 s[4:5], s[12:13]
	s_mul_hi_i32 s1, s10, 0x1800000
	s_add_u32 s2, s4, s2
	s_addc_u32 s3, s5, s1
	s_lshl_b64 s[4:5], s[10:11], 21
	v_and_b32_e32 v4, 0xff, v2
	v_ashrrev_i32_e32 v12, 8, v2
	v_lshlrev_b32_e32 v5, 4, v2
	v_ashrrev_i32_e32 v16, 2, v2
	v_and_b32_e32 v6, -4, v2
	v_add_u32_e32 v2, 0x200, v2
	s_add_u32 s4, s34, s4
	v_and_b32_e32 v10, 48, v5
	v_ashrrev_i32_e32 v17, 2, v2
	v_and_b32_e32 v2, -4, v2
	s_addc_u32 s5, s35, s5
	v_lshl_add_u32 v3, v4, 2, 0
	v_mul_i32_i24_e32 v5, 0x404, v12
	v_add_u32_e32 v6, 0, v6
	v_mul_u32_u24_e32 v7, 0x404, v10
	v_add_u32_e32 v2, 0, v2
	v_lshl_add_u64 v[14:15], s[4:5], 0, v[10:11]
	v_lshlrev_b32_e32 v10, 2, v4
	v_add_u32_e32 v18, v3, v5
	v_add_u32_e32 v19, v6, v7
	v_add_u32_e32 v20, v2, v7
	v_readlane_b32 s14, v253, 17
	v_readlane_b32 s15, v253, 18

; #define LAS __attribute__((address_space(3)))
; __device__ __forceinline__ unsigned lds_addr(LAS unsigned char* p) { return (unsigned)(size_t)p; }
; #define SBAR() __builtin_amdgcn_sched_barrier(0)
; template <int k> __device__ __forceinline__ void fin_snip(f32x16& p0, f32x16& p1, float alpha, float& l_reg, float& ps, bf16x8& pa0, bf16x8& pa1, bf16x8& pa2, bf16x8& pa3) {
;     if constexpr (k < 8) { p1[2 * k] = __builtin_amdgcn_exp2f(p1[2 * k]); p1[2 * k + 1] = __builtin_amdgcn_exp2f(p1[2 * k + 1]); }
;     else if constexpr (k < 16) { constexpr int j = 2 * (k - 8); const float a = (p0[j] + p0[j + 1]) + (p1[j] + p1[j + 1]); ps = (k == 8) ? a : ps + a; }
;     else if constexpr (k == 16) { auto rr = __builtin_amdgcn_permlane32_swap(__float_as_uint(ps), __float_as_uint(ps), false, false);
;         ps = __uint_as_float(rr[0]) + __uint_as_float(rr[1]); l_reg = l_reg * alpha + ps; }
;     else if constexpr (k == 17) { PK4(p0, 0, pa0); }
;     else if constexpr (k == 18) { PK4(p0, 8, pa1); }
;     else if constexpr (k == 19) { PK4(p1, 0, pa2); }
;     else if constexpr (k == 20) { PK4(p1, 8, pa3); }
; }
; __device__ __forceinline__ void stage_qk_fin(int kboff, f32x16& x0, f32x16& x1, LAS unsigned char* lds, int r32, int hi, const bf16x8* qr,
;                                              f32x16& y0, f32x16& y1, float alY, float& l_reg, bf16x8& pa0, bf16x8& pa1, bf16x8& pa2, bf16x8& pa3) {
;     x0 = (f32x16){}; x1 = (f32x16){};
;     unsigned kb[4];
; #pragma unroll
;     for (int dd = 0; dd < 4; ++dd) kb[dd] = lds_addr(lds) + K_OFF + kboff + r32 * 384 + (((2 * dd + hi) ^ ((r32 >> 1) & 7)) << 4);
;     ...
;     float ps = 0.f; bf16x8 bA[2], bB[2];
;     SBAR(); KGRP(bA, 0); KGRP(bB, 1); KWAIT(bA, 2); SBAR();
;     KMS(bA, 0); KGRP(bA, 2); KWAIT(bB, 2); SBAR();
;     KMS(bB, 1); KGRP(bB, 3); KWAIT(bA, 2); SBAR();
;     KMS(bA, 2); KGRP(bA, 4); KWAIT(bB, 2); SBAR();
;     KMS(bB, 3); KGRP(bB, 5); KWAIT(bA, 2); SBAR();
;     KMS(bA, 4); KGRP(bA, 6); KWAIT(bB, 2); SBAR();
;     KMS(bB, 5); KGRP(bB, 7); KWAIT(bA, 2); SBAR();
;     KMS(bA, 6); KGRP(bA, 8); KWAIT(bB, 2); SBAR();
;     KMS(bB, 7); KGRP(bB, 9); KWAIT(bA, 2); SBAR();
;     KMS(bA, 8); KGRP(bA, 10); KWAIT(bB, 2); SBAR();
;     KMS(bB, 9); KGRP(bB, 11); KWAIT(bA, 2); SBAR();
;     KMS(bA, 10); KWAIT(bB, 0); SBAR();
;     KMS(bB, 11);
.LBB0_328:
	s_cmp_gt_i32 s86, s84
	s_cselect_b64 vcc, -1, 0
	v_cndmask_b32_e32 v216, 0, v223, vcc
	ds_read_b128 v[2:5], v226 offset:0
	ds_read_b128 v[6:9], v226 offset:0x3000
	ds_read_b128 v[10:13], v227 offset:0
	ds_read_b128 v[176:179], v227 offset:0x3000
	s_nop 0
	s_waitcnt lgkmcnt(2)
	s_nop 0
	v_mfma_f32_32x32x16_bf16 v[96:111], v[2:5], v[128:131], 0
	v_exp_f32_e32 v214, v214
	v_exp_f32_e32 v215, v215
	v_mfma_f32_32x32x16_bf16 v[112:127], v[6:9], v[128:131], 0
	v_exp_f32_e32 v212, v212
	v_exp_f32_e32 v213, v213
	ds_read_b128 v[2:5], v228 offset:0
	ds_read_b128 v[6:9], v228 offset:0x3000
	s_waitcnt lgkmcnt(2)
	s_nop 0
	v_mfma_f32_32x32x16_bf16 v[96:111], v[10:13], v[132:135], v[96:111]
	v_exp_f32_e32 v210, v210
	v_exp_f32_e32 v211, v211
	v_mfma_f32_32x32x16_bf16 v[112:127], v[176:179], v[132:135], v[112:127]
	v_exp_f32_e32 v208, v208
	v_exp_f32_e32 v209, v209
	ds_read_b128 v[10:13], v229 offset:0
	ds_read_b128 v[176:179], v229 offset:0x3000
	s_waitcnt lgkmcnt(2)
	s_nop 0
	v_mfma_f32_32x32x16_bf16 v[96:111], v[2:5], v[136:139], v[96:111]
	v_exp_f32_e32 v206, v206
	v_exp_f32_e32 v207, v207
	v_mfma_f32_32x32x16_bf16 v[112:127], v[6:9], v[136:139], v[112:127]
	v_exp_f32_e32 v204, v204
	v_exp_f32_e32 v205, v205
	ds_read_b128 v[2:5], v226 offset:0x80
	ds_read_b128 v[6:9], v226 offset:0x3080
	s_waitcnt lgkmcnt(2)
	s_nop 0
	v_mfma_f32_32x32x16_bf16 v[96:111], v[10:13], v[140:143], v[96:111]
	v_exp_f32_e32 v202, v202
	v_exp_f32_e32 v203, v203
	v_mfma_f32_32x32x16_bf16 v[112:127], v[176:179], v[140:143], v[112:127]
	v_exp_f32_e32 v200, v200
	v_exp_f32_e32 v201, v201
	ds_read_b128 v[10:13], v227 offset:0x80
	ds_read_b128 v[176:179], v227 offset:0x3080
	s_waitcnt lgkmcnt(2)
	s_nop 0
	v_mfma_f32_32x32x16_bf16 v[96:111], v[2:5], v[144:147], v[96:111]
	v_add_f32_e32 v0, v80, v81
	v_add_f32_e32 v2, v214, v215
	v_add_f32_e32 v0, v0, v2
	v_mfma_f32_32x32x16_bf16 v[112:127], v[6:9], v[144:147], v[112:127]
	v_add_f32_e32 v2, v82, v83
	v_add_f32_e32 v3, v212, v213
	v_add_f32_e32 v2, v2, v3
	v_add_f32_e32 v0, v0, v2
	ds_read_b128 v[2:5], v228 offset:0x80
	ds_read_b128 v[6:9], v228 offset:0x3080
	s_waitcnt lgkmcnt(2)
	s_nop 0
	v_mfma_f32_32x32x16_bf16 v[96:111], v[10:13], v[148:151], v[96:111]
	v_add_f32_e32 v10, v84, v85
	v_add_f32_e32 v11, v210, v211
	v_add_f32_e32 v10, v10, v11
	v_add_f32_e32 v0, v10, v0
	v_mfma_f32_32x32x16_bf16 v[112:127], v[176:179], v[148:151], v[112:127]
	v_add_f32_e32 v10, v86, v87
	v_add_f32_e32 v11, v208, v209
	v_add_f32_e32 v10, v10, v11
	v_add_f32_e32 v0, v10, v0
	ds_read_b128 v[10:13], v229 offset:0x80
	ds_read_b128 v[176:179], v229 offset:0x3080
	s_waitcnt lgkmcnt(2)
	s_nop 0
	v_mfma_f32_32x32x16_bf16 v[96:111], v[2:5], v[152:155], v[96:111]
	v_add_f32_e32 v2, v88, v89
	v_add_f32_e32 v3, v206, v207
	v_add_f32_e32 v2, v2, v3
	v_add_f32_e32 v0, v2, v0
	v_mfma_f32_32x32x16_bf16 v[112:127], v[6:9], v[152:155], v[112:127]
	v_add_f32_e32 v2, v90, v91
	v_add_f32_e32 v3, v204, v205
	v_add_f32_e32 v2, v2, v3
	v_add_f32_e32 v0, v2, v0
	ds_read_b128 v[2:5], v226 offset:0x100
	ds_read_b128 v[6:9], v226 offset:0x3100
	s_waitcnt lgkmcnt(2)
	s_nop 0
	v_mfma_f32_32x32x16_bf16 v[96:111], v[10:13], v[156:159], v[96:111]
	v_add_f32_e32 v10, v92, v93
	v_add_f32_e32 v11, v202, v203
	v_add_f32_e32 v10, v10, v11
	v_add_f32_e32 v0, v10, v0
	v_mfma_f32_32x32x16_bf16 v[112:127], v[176:179], v[156:159], v[112:127]
	v_add_f32_e32 v10, v94, v95
	v_add_f32_e32 v11, v200, v201
	v_add_f32_e32 v10, v10, v11
	v_add_f32_e32 v14, v10, v0
	ds_read_b128 v[10:13], v227 offset:0x100
	ds_read_b128 v[176:179], v227 offset:0x3100
	s_waitcnt lgkmcnt(2)
	s_nop 0
	v_mfma_f32_32x32x16_bf16 v[96:111], v[2:5], v[160:163], v[96:111]
	v_mov_b32_e32 v15, v14
	s_nop 1
	v_permlane32_swap_b32_e32 v14, v15
	v_mfma_f32_32x32x16_bf16 v[112:127], v[6:9], v[160:163], v[112:127]
	v_cvt_pk_bf16_f32 v2, v80, v81
	v_cvt_pk_bf16_f32 v3, v82, v83
	v_cvt_pk_bf16_f32 v4, v84, v85
	v_cvt_pk_bf16_f32 v5, v86, v87
	s_nop 0
	v_permlane32_swap_b32_e32 v2, v4
	v_permlane32_swap_b32_e32 v3, v5
	ds_read_b128 v[194:197], v228 offset:0x100
	ds_read_b128 v[232:235], v228 offset:0x3100
	s_waitcnt lgkmcnt(2)
	s_nop 0
	v_mfma_f32_32x32x16_bf16 v[96:111], v[10:13], v[164:167], v[96:111]
	v_cvt_pk_bf16_f32 v6, v88, v89
	v_cvt_pk_bf16_f32 v7, v90, v91
	v_cvt_pk_bf16_f32 v8, v92, v93
	v_cvt_pk_bf16_f32 v9, v94, v95
	s_nop 0
	v_permlane32_swap_b32_e32 v6, v8
	v_permlane32_swap_b32_e32 v7, v9
	v_mfma_f32_32x32x16_bf16 v[112:127], v[176:179], v[164:167], v[112:127]
	v_cvt_pk_bf16_f32 v10, v214, v215
	v_cvt_pk_bf16_f32 v11, v212, v213
	v_cvt_pk_bf16_f32 v12, v210, v211
	v_cvt_pk_bf16_f32 v13, v208, v209
	s_nop 0
	v_permlane32_swap_b32_e32 v10, v12
	v_permlane32_swap_b32_e32 v11, v13
	ds_read_b128 v[236:239], v229 offset:0x100
	ds_read_b128 v[240:243], v229 offset:0x3100
	s_waitcnt lgkmcnt(2)
	s_nop 0
	v_mfma_f32_32x32x16_bf16 v[96:111], v[194:197], v[168:171], v[96:111]
	v_cvt_pk_bf16_f32 v176, v206, v207
	v_cvt_pk_bf16_f32 v177, v204, v205
	v_cvt_pk_bf16_f32 v178, v202, v203
	v_cvt_pk_bf16_f32 v179, v200, v201
	s_nop 0
	v_permlane32_swap_b32_e32 v176, v178
	v_permlane32_swap_b32_e32 v177, v179
	v_mfma_f32_32x32x16_bf16 v[112:127], v[232:235], v[168:171], v[112:127]
	v_add_f32_e32 v245, v14, v15
	v_fmac_f32_e32 v245, v192, v230
	s_waitcnt lgkmcnt(0)
	s_nop 0
	v_mfma_f32_32x32x16_bf16 v[96:111], v[236:239], v[172:175], v[96:111]
	v_mfma_f32_32x32x16_bf16 v[112:127], v[240:243], v[172:175], v[112:127]
	s_cmp_eq_u32 s100, 0
	s_cbranch_scc1 .Lmy_mid_a
	s_waitcnt vmcnt(0)
	s_barrier
; #define SBAR() __builtin_amdgcn_sched_barrier(0)
; #define PV_RD(F_, d0) do { constexpr int b_ = V_OFF + v_rd_off(d0, 0, 0); \
;         TRRD(F_[0], b_); TRRD(F_[1], b_ + 2048); TRRD(F_[2], b_ + 4096); TRRD(F_[3], b_ + 6144); TRRD(F_[4], b_ + 8192); TRRD(F_[5], b_ + 10240); TRRD(F_[6], b_ + 12288); TRRD(F_[7], b_ + 14336); } while (0)
; template <int k> __device__ __forceinline__ void par_snip(f32x16& p0, f32x16& p1, float& m_reg, float& pmax, float& alpha, float& mnL, float msk) {
;     constexpr float C2 = 1.4426950408889634f * SCALE;
;     if constexpr (k < 4) { constexpr int j = 4 * k; const float a = fmaxf(fmaxf(p0[j], p0[j + 1]), fmaxf(p0[j + 2], p0[j + 3])), b = fmaxf(fmaxf(p1[j], p1[j + 1]), fmaxf(p1[j + 2], p1[j + 3]));
;         pmax = (k == 0) ? fmaxf(a, b) : fmaxf(pmax, fmaxf(a, b)); }
;     else if constexpr (k == 4) { pmax += msk;
;         { auto rr = __builtin_amdgcn_permlane32_swap(__float_as_uint(pmax), __float_as_uint(pmax), false, false); pmax = fmaxf(__uint_as_float(rr[0]), __uint_as_float(rr[1])); }
;         const bool defer = __all((pmax - m_reg) * SCALE <= THR);
;         const float mn = defer ? m_reg : fmaxf(m_reg, pmax);
;         alpha = __builtin_amdgcn_exp2f((m_reg - mn) * C2); m_reg = mn; mnL = fmaf(-mn, C2, msk); }
;     else if constexpr (k < 9) { constexpr int j = 4 * (k - 5);
; #pragma unroll
;         for (int e = 0; e < 4; ++e) { p0[j + e] = fmaf(p0[j + e], C2, mnL); p1[j + e] = fmaf(p1[j + e], C2, mnL); } }
;     else if constexpr (k < 15) { constexpr int j = 2 * (k - 9); p0[j] = __builtin_amdgcn_exp2f(p0[j]); p0[j + 1] = __builtin_amdgcn_exp2f(p0[j + 1]); }
;     else if constexpr (k == 15) {
; #pragma unroll
;         for (int e = 12; e < 16; ++e) p0[e] = __builtin_amdgcn_exp2f(p0[e]); }
; }
; __device__ __forceinline__ void stage_pv_par(f32x16* o, int vb0, bf16x8 pa0, bf16x8 pa1, bf16x8 pa2, bf16x8 pa3,
;                                              f32x16& x0, f32x16& x1, float& m_reg, float& alpha, float msk) {
;     ...
;     float pmax = 0.f, mnL = 0.f; s16x4 fA[8];
;     SBAR(); PV_RD(fA, 0); PV_WAIT(fA, 0); SBAR();
;     PVS(fA, 0); PV_RD(fA, 1); PV_WAIT(fA, 0); SBAR();
;     PVS(fA, 1); PV_RD(fA, 2); PV_WAIT(fA, 0); SBAR();
;     PVS(fA, 2); PV_RD(fA, 3); PV_WAIT(fA, 0); SBAR();
;     PVS(fA, 3);
.Lmy_mid_a:
	s_and_b32 s34, s85, 0xc000
	v_add_u32_e32 v217, s34, v225
	ds_read_b64_tr_b16 v[194:195], v217 offset:0
	ds_read_b64_tr_b16 v[196:197], v217 offset:0x800
	ds_read_b64_tr_b16 v[200:201], v217 offset:0x1000
	ds_read_b64_tr_b16 v[202:203], v217 offset:0x1800
	ds_read_b64_tr_b16 v[204:205], v217 offset:0x2000
	ds_read_b64_tr_b16 v[206:207], v217 offset:0x2800
	ds_read_b64_tr_b16 v[208:209], v217 offset:0x3000
	ds_read_b64_tr_b16 v[210:211], v217 offset:0x3800
	s_nop 0
	s_waitcnt lgkmcnt(0)
	s_nop 0
	v_mfma_f32_32x32x16_bf16 v[64:79], v[194:197], v[2:5], v[64:79]
	s_nop 5
	v_max_f32_e32 v0, v99, v99
	v_max_f32_e32 v194, v98, v98
	v_max_f32_e32 v0, v194, v0
	v_max_f32_e32 v194, v115, v115
	v_max_f32_e32 v195, v114, v114
	v_max3_f32 v0, v96, v97, v0
	v_max_f32_e32 v194, v195, v194
	v_max3_f32 v194, v112, v113, v194
	v_mfma_f32_32x32x16_bf16 v[64:79], v[200:203], v[6:9], v[64:79]
	v_max_f32_e32 v195, v101, v101
	v_max_f32_e32 v196, v100, v100
	v_max_f32_e32 v195, v196, v195
	v_max_f32_e32 v196, v103, v103
	v_max_f32_e32 v197, v102, v102
	v_max_f32_e32 v196, v197, v196
	v_max_f32_e32 v197, v119, v119
	v_max_f32_e32 v231, v118, v118
	v_max_f32_e32 v197, v231, v197
	v_max3_f32 v197, v116, v117, v197
	v_max3_f32 v195, v195, v196, v197
	v_max3_f32 v0, v0, v194, v195
	v_mfma_f32_32x32x16_bf16 v[64:79], v[204:207], v[10:13], v[64:79]
	v_max_f32_e32 v194, v105, v105
	v_max_f32_e32 v195, v104, v104
	v_max_f32_e32 v194, v195, v194
	v_max_f32_e32 v195, v107, v107
	v_max_f32_e32 v196, v106, v106
	v_max_f32_e32 v195, v196, v195
	v_max_f32_e32 v196, v123, v123
	v_max_f32_e32 v197, v122, v122
	v_max_f32_e32 v196, v197, v196
	v_max3_f32 v196, v120, v121, v196
	v_max3_f32 v194, v194, v195, v196
	v_mfma_f32_32x32x16_bf16 v[64:79], v[208:211], v[176:179], v[64:79]
	v_max_f32_e32 v195, v109, v109
	v_max_f32_e32 v196, v108, v108
	v_max_f32_e32 v195, v196, v195
	v_max_f32_e32 v196, v111, v111
	v_max_f32_e32 v197, v110, v110
	v_max_f32_e32 v196, v197, v196
	v_max_f32_e32 v197, v127, v127
	v_max_f32_e32 v231, v126, v126
	v_max_f32_e32 v197, v231, v197
	v_max3_f32 v197, v124, v125, v197
	v_max3_f32 v195, v195, v196, v197
	v_max3_f32 v0, v0, v194, v195
	ds_read_b64_tr_b16 v[194:195], v217 offset:0x200
	ds_read_b64_tr_b16 v[196:197], v217 offset:0xa00
	ds_read_b64_tr_b16 v[200:201], v217 offset:0x1200
	ds_read_b64_tr_b16 v[202:203], v217 offset:0x1a00
	ds_read_b64_tr_b16 v[204:205], v217 offset:0x2200
	ds_read_b64_tr_b16 v[206:207], v217 offset:0x2a00
	ds_read_b64_tr_b16 v[208:209], v217 offset:0x3200
	ds_read_b64_tr_b16 v[210:211], v217 offset:0x3a00
	s_nop 0
	s_waitcnt lgkmcnt(0)
	v_add_f32_e32 v0, v216, v0
	v_mfma_f32_32x32x16_bf16 v[48:63], v[194:197], v[2:5], v[48:63]
	v_mov_b32_e32 v194, v0
	s_nop 1
	v_permlane32_swap_b32_e32 v0, v194
	v_max_f32_e32 v194, v194, v194
	v_max_f32_e32 v0, v0, v0
	v_max_f32_e32 v0, v0, v194
	v_sub_f32_e32 v194, v0, v244
	v_mul_f32_e32 v194, 0x3d93cd3a, v194
	v_cmp_ge_f32_e32 vcc, s63, v194
	s_cmp_eq_u64 vcc, exec
	v_max_f32_e32 v194, v244, v244
	s_cselect_b64 vcc, -1, 0
	v_max_f32_e32 v0, v194, v0
	v_cndmask_b32_e32 v246, v0, v244, vcc
	v_sub_f32_e32 v0, v244, v246
	v_mul_f32_e32 v0, 0x3dd53b94, v0
	v_exp_f32_e32 v0, v0
	v_fmac_f32_e32 v216, 0xbdd53b94, v246
	v_mfma_f32_32x32x16_bf16 v[48:63], v[200:203], v[6:9], v[48:63]
	v_fmamk_f32 v96, v96, 0x3dd53b94, v216
	v_fmamk_f32 v97, v97, 0x3dd53b94, v216
	v_fmamk_f32 v98, v98, 0x3dd53b94, v216
	v_fmamk_f32 v99, v99, 0x3dd53b94, v216
	v_exp_f32_e32 v243, v96
	v_mfma_f32_32x32x16_bf16 v[48:63], v[204:207], v[10:13], v[48:63]
	v_fmamk_f32 v100, v100, 0x3dd53b94, v216
	v_fmamk_f32 v101, v101, 0x3dd53b94, v216
	v_exp_f32_e32 v242, v97
	v_exp_f32_e32 v241, v98
	v_mfma_f32_32x32x16_bf16 v[48:63], v[208:211], v[176:179], v[48:63]
	v_fmamk_f32 v102, v102, 0x3dd53b94, v216
	v_fmamk_f32 v103, v103, 0x3dd53b94, v216
	v_exp_f32_e32 v240, v99
	v_exp_f32_e32 v239, v100
	ds_read_b64_tr_b16 v[194:195], v217 offset:0x400
	ds_read_b64_tr_b16 v[196:197], v217 offset:0xc00
	ds_read_b64_tr_b16 v[200:201], v217 offset:0x1400
	ds_read_b64_tr_b16 v[202:203], v217 offset:0x1c00
	ds_read_b64_tr_b16 v[204:205], v217 offset:0x2400
	ds_read_b64_tr_b16 v[206:207], v217 offset:0x2c00
	ds_read_b64_tr_b16 v[208:209], v217 offset:0x3400
	ds_read_b64_tr_b16 v[210:211], v217 offset:0x3c00
	s_nop 0
	s_waitcnt lgkmcnt(0)
	s_nop 0
	v_mfma_f32_32x32x16_bf16 v[32:47], v[194:197], v[2:5], v[32:47]
	v_fmamk_f32 v104, v104, 0x3dd53b94, v216
	v_fmamk_f32 v105, v105, 0x3dd53b94, v216
	v_exp_f32_e32 v238, v101
	v_exp_f32_e32 v237, v102
	v_mfma_f32_32x32x16_bf16 v[32:47], v[200:203], v[6:9], v[32:47]
	v_fmamk_f32 v106, v106, 0x3dd53b94, v216
	v_fmamk_f32 v107, v107, 0x3dd53b94, v216
	v_exp_f32_e32 v236, v103
	v_exp_f32_e32 v235, v104
	v_mfma_f32_32x32x16_bf16 v[32:47], v[204:207], v[10:13], v[32:47]
	v_fmamk_f32 v108, v108, 0x3dd53b94, v216
	v_fmamk_f32 v109, v109, 0x3dd53b94, v216
	v_exp_f32_e32 v234, v105
	v_exp_f32_e32 v233, v106
	v_mfma_f32_32x32x16_bf16 v[32:47], v[208:211], v[176:179], v[32:47]
	v_fmamk_f32 v110, v110, 0x3dd53b94, v216
	v_fmamk_f32 v111, v111, 0x3dd53b94, v216
	v_exp_f32_e32 v232, v107
	v_exp_f32_e32 v231, v108
	ds_read_b64_tr_b16 v[194:195], v217 offset:0x600
	ds_read_b64_tr_b16 v[196:197], v217 offset:0xe00
	ds_read_b64_tr_b16 v[200:201], v217 offset:0x1600
	ds_read_b64_tr_b16 v[202:203], v217 offset:0x1e00
	ds_read_b64_tr_b16 v[204:205], v217 offset:0x2600
	ds_read_b64_tr_b16 v[206:207], v217 offset:0x2e00
	ds_read_b64_tr_b16 v[208:209], v217 offset:0x3600
	ds_read_b64_tr_b16 v[210:211], v217 offset:0x3e00
	s_nop 0
	s_waitcnt lgkmcnt(0)
	s_nop 0
	v_mfma_f32_32x32x16_bf16 v[16:31], v[194:197], v[2:5], v[16:31]
	v_exp_f32_e32 v230, v109
	v_fmamk_f32 v14, v112, 0x3dd53b94, v216
	v_fmamk_f32 v15, v113, 0x3dd53b94, v216
	v_fmamk_f32 v116, v116, 0x3dd53b94, v216
	v_fmamk_f32 v117, v117, 0x3dd53b94, v216
	v_mfma_f32_32x32x16_bf16 v[16:31], v[200:203], v[6:9], v[16:31]
	v_fmamk_f32 v118, v118, 0x3dd53b94, v216
	v_fmamk_f32 v119, v119, 0x3dd53b94, v216
	v_fmamk_f32 v120, v120, 0x3dd53b94, v216
	v_fmamk_f32 v121, v121, 0x3dd53b94, v216
	v_fmamk_f32 v122, v122, 0x3dd53b94, v216
	v_fmamk_f32 v123, v123, 0x3dd53b94, v216
	v_mfma_f32_32x32x16_bf16 v[16:31], v[204:207], v[10:13], v[16:31]
	v_fmamk_f32 v124, v124, 0x3dd53b94, v216
	v_fmamk_f32 v125, v125, 0x3dd53b94, v216
	v_fmamk_f32 v126, v126, 0x3dd53b94, v216
	v_fmamk_f32 v127, v127, 0x3dd53b94, v216
	v_mfma_f32_32x32x16_bf16 v[16:31], v[208:211], v[176:179], v[16:31]
	v_cmp_gt_f32_e32 vcc, 1.0, v0
	s_cbranch_vccz .LBB0_330
; __device__ __forceinline__ void attn_block(const Params& p, LAS unsigned char* lds, int h, int qb) {
;     ...
;     float m_reg = -1e30f, l_reg = 0.f; f32x16 o[4];
; #pragma unroll
;     for (int j = 0; j < 4; ++j) o[j] = (f32x16){};
;     f32x16 pA0, pA1, pB0, pB1; float mnA, mnB, alA = 1.f, alB = 1.f; bf16x8 pa0, pa1, pa2, pa3;
;     ...
;     ADMA(0, 0, 0); __syncthreads();
;     ADMA(1, 1, 1);
;     qkt(0, pA0, pA1, lds, r32, hi, qr); partialSM(pA0, pA1, m_reg, mnA, alA);
;     __syncthreads();
;     ...
;     for (int t = 1; t < ntiles; t += 2) {
;         STEP(t, pB0, pB1, mnB, alB, pA0, pA1, alA);
;         if (t + 1 < ntiles) STEP(t + 1, pA0, pA1, mnA, alA, pB0, pB1, alB);
	v_pk_mul_f32 v[78:79], v[78:79], v[0:1] op_sel_hi:[1,0]
	v_pk_mul_f32 v[76:77], v[76:77], v[0:1] op_sel_hi:[1,0]
	v_pk_mul_f32 v[74:75], v[74:75], v[0:1] op_sel_hi:[1,0]
	v_pk_mul_f32 v[72:73], v[72:73], v[0:1] op_sel_hi:[1,0]
	v_pk_mul_f32 v[70:71], v[70:71], v[0:1] op_sel_hi:[1,0]
	v_pk_mul_f32 v[68:69], v[68:69], v[0:1] op_sel_hi:[1,0]
	v_pk_mul_f32 v[66:67], v[66:67], v[0:1] op_sel_hi:[1,0]
	v_pk_mul_f32 v[64:65], v[64:65], v[0:1] op_sel_hi:[1,0]
	v_pk_mul_f32 v[62:63], v[0:1], v[62:63] op_sel_hi:[0,1]
	v_pk_mul_f32 v[60:61], v[0:1], v[60:61] op_sel_hi:[0,1]
	v_pk_mul_f32 v[58:59], v[0:1], v[58:59] op_sel_hi:[0,1]
	v_pk_mul_f32 v[56:57], v[0:1], v[56:57] op_sel_hi:[0,1]
	v_pk_mul_f32 v[54:55], v[0:1], v[54:55] op_sel_hi:[0,1]
	v_pk_mul_f32 v[52:53], v[0:1], v[52:53] op_sel_hi:[0,1]
	v_pk_mul_f32 v[50:51], v[0:1], v[50:51] op_sel_hi:[0,1]
	v_pk_mul_f32 v[48:49], v[0:1], v[48:49] op_sel_hi:[0,1]
	v_pk_mul_f32 v[46:47], v[0:1], v[46:47] op_sel_hi:[0,1]
	v_pk_mul_f32 v[44:45], v[0:1], v[44:45] op_sel_hi:[0,1]
	v_pk_mul_f32 v[42:43], v[0:1], v[42:43] op_sel_hi:[0,1]
	v_pk_mul_f32 v[40:41], v[0:1], v[40:41] op_sel_hi:[0,1]
	v_pk_mul_f32 v[38:39], v[0:1], v[38:39] op_sel_hi:[0,1]
	v_pk_mul_f32 v[36:37], v[0:1], v[36:37] op_sel_hi:[0,1]
	v_pk_mul_f32 v[34:35], v[0:1], v[34:35] op_sel_hi:[0,1]
	v_pk_mul_f32 v[32:33], v[0:1], v[32:33] op_sel_hi:[0,1]
	v_pk_mul_f32 v[30:31], v[0:1], v[30:31] op_sel_hi:[0,1]
	v_pk_mul_f32 v[28:29], v[0:1], v[28:29] op_sel_hi:[0,1]
	v_pk_mul_f32 v[26:27], v[0:1], v[26:27] op_sel_hi:[0,1]
	v_pk_mul_f32 v[24:25], v[0:1], v[24:25] op_sel_hi:[0,1]
	v_pk_mul_f32 v[22:23], v[0:1], v[22:23] op_sel_hi:[0,1]
	v_pk_mul_f32 v[20:21], v[0:1], v[20:21] op_sel_hi:[0,1]
	v_pk_mul_f32 v[18:19], v[0:1], v[18:19] op_sel_hi:[0,1]
	v_pk_mul_f32 v[16:17], v[0:1], v[16:17] op_sel_hi:[0,1]
.LBB0_330:
	v_fmamk_f32 v176, v114, 0x3dd53b94, v216
	v_fmamk_f32 v177, v115, 0x3dd53b94, v216
	v_exp_f32_e32 v216, v110
	v_exp_f32_e32 v179, v111
	s_andn2_b64 vcc, exec, s[82:83]
	s_add_i32 s82, s86, 2
	s_waitcnt vmcnt(0) lgkmcnt(0)
	s_cmp_lg_u32 s100, 0
	s_cbranch_scc1 .Lmy_end_a
	s_barrier
.Lmy_end_a:
	s_cbranch_vccnz .LBB0_336
	s_cmp_ge_i32 s82, s80
	s_cbranch_scc1 .LBB0_333
	v_lshl_add_u64 v[2:3], s[14:15], 0, v[186:187]
	s_mov_b32 m0, s49
	v_lshl_add_u64 v[2:3], v[2:3], 0, s[58:59]
	global_load_lds_dwordx4 v[2:3], off
	v_lshl_add_u64 v[2:3], s[14:15], 0, v[188:189]
	v_lshl_add_u64 v[2:3], v[2:3], 0, s[58:59]
	s_mov_b32 m0, s0
	s_add_i32 s34, s85, 0xffffc000
	global_load_lds_dwordx4 v[2:3], off
	v_lshl_add_u64 v[2:3], s[14:15], 0, v[190:191]
	v_lshl_add_u64 v[2:3], v[2:3], 0, s[58:59]
	s_mov_b32 m0, s1
	s_and_b32 s34, s34, 0xc000
	global_load_lds_dwordx4 v[2:3], off
	s_add_i32 s34, s17, s34
	v_lshl_add_u64 v[2:3], s[14:15], 0, v[182:183]
	v_lshl_add_u64 v[2:3], v[2:3], 0, s[76:77]
	s_mov_b32 m0, s34
	s_nop 0
	global_load_lds_dwordx4 v[2:3], off
	v_lshl_add_u64 v[2:3], s[14:15], 0, v[184:185]
	v_lshl_add_u64 v[2:3], v[2:3], 0, s[76:77]
	s_add_i32 m0, s34, 0x2000
	s_nop 0
	global_load_lds_dwordx4 v[2:3], off
.LBB0_333:
	s_add_i32 s34, s85, 0xffff4000
	s_cmp_lt_i32 s86, s84
	s_cselect_b64 s[86:87], -1, 0
	v_cndmask_b32_e64 v178, v223, 0, s[86:87]
	ds_read_b128 v[2:5], v181 offset:0
	ds_read_b128 v[6:9], v181 offset:0x3000
	ds_read_b128 v[10:13], v219 offset:0
	ds_read_b128 v[112:115], v219 offset:0x3000
	s_nop 0
	s_waitcnt lgkmcnt(2)
	s_nop 0
	v_mfma_f32_32x32x16_bf16 v[96:111], v[2:5], v[128:131], 0
	v_exp_f32_e32 v14, v14
	v_exp_f32_e32 v15, v15
	v_mfma_f32_32x32x16_bf16 v[80:95], v[6:9], v[128:131], 0
	v_exp_f32_e32 v176, v176
	v_exp_f32_e32 v177, v177
	ds_read_b128 v[2:5], v220 offset:0
	ds_read_b128 v[6:9], v220 offset:0x3000
	s_waitcnt lgkmcnt(2)
	s_nop 0
	v_mfma_f32_32x32x16_bf16 v[96:111], v[10:13], v[132:135], v[96:111]
	v_exp_f32_e32 v116, v116
	v_exp_f32_e32 v117, v117
	v_mfma_f32_32x32x16_bf16 v[80:95], v[112:115], v[132:135], v[80:95]
	v_exp_f32_e32 v118, v118
	v_exp_f32_e32 v119, v119
	ds_read_b128 v[10:13], v221 offset:0
	ds_read_b128 v[112:115], v221 offset:0x3000
	s_waitcnt lgkmcnt(2)
	s_nop 0
	v_mfma_f32_32x32x16_bf16 v[96:111], v[2:5], v[136:139], v[96:111]
	v_exp_f32_e32 v120, v120
	v_exp_f32_e32 v121, v121
	v_mfma_f32_32x32x16_bf16 v[80:95], v[6:9], v[136:139], v[80:95]
	v_exp_f32_e32 v122, v122
	v_exp_f32_e32 v123, v123
	ds_read_b128 v[2:5], v181 offset:0x80
	ds_read_b128 v[6:9], v181 offset:0x3080
	s_waitcnt lgkmcnt(2)
	s_nop 0
	v_mfma_f32_32x32x16_bf16 v[96:111], v[10:13], v[140:143], v[96:111]
	v_exp_f32_e32 v124, v124
	v_exp_f32_e32 v125, v125
	v_mfma_f32_32x32x16_bf16 v[80:95], v[112:115], v[140:143], v[80:95]
	v_exp_f32_e32 v126, v126
	v_exp_f32_e32 v127, v127
	ds_read_b128 v[10:13], v219 offset:0x80
	ds_read_b128 v[112:115], v219 offset:0x3080
	s_waitcnt lgkmcnt(2)
	s_nop 0
	v_mfma_f32_32x32x16_bf16 v[96:111], v[2:5], v[144:147], v[96:111]
	v_add_f32_e32 v2, v243, v242
	v_add_f32_e32 v3, v14, v15
	v_add_f32_e32 v2, v2, v3
	v_mfma_f32_32x32x16_bf16 v[80:95], v[6:9], v[144:147], v[80:95]
	v_add_f32_e32 v3, v241, v240
	v_add_f32_e32 v4, v176, v177
	v_add_f32_e32 v3, v3, v4
	v_add_f32_e32 v192, v2, v3
	ds_read_b128 v[2:5], v220 offset:0x80
	ds_read_b128 v[6:9], v220 offset:0x3080
	s_waitcnt lgkmcnt(2)
	s_nop 0
	v_mfma_f32_32x32x16_bf16 v[96:111], v[10:13], v[148:151], v[96:111]
	v_add_f32_e32 v10, v239, v238
	v_add_f32_e32 v11, v116, v117
	v_add_f32_e32 v10, v10, v11
	v_add_f32_e32 v10, v10, v192
	v_mfma_f32_32x32x16_bf16 v[80:95], v[112:115], v[148:151], v[80:95]
	v_add_f32_e32 v11, v237, v236
	v_add_f32_e32 v12, v118, v119
	v_add_f32_e32 v11, v11, v12
	v_add_f32_e32 v192, v11, v10
	ds_read_b128 v[10:13], v221 offset:0x80
	ds_read_b128 v[112:115], v221 offset:0x3080
	s_waitcnt lgkmcnt(2)
; #define LAS __attribute__((address_space(3)))
; __device__ __forceinline__ unsigned lds_addr(LAS unsigned char* p) { return (unsigned)(size_t)p; }
; #define SBAR() __builtin_amdgcn_sched_barrier(0)
; #define KGRP(B_, g_) do { KRD(B_[0], kb[(2 * (g_)) & 3], ((2 * (g_)) >> 2) * 128); KRD(B_[1], kb[(2 * (g_)) & 3], ((2 * (g_)) >> 2) * 128 + 12288); \
;                           KRD(B_[2], kb[(2 * (g_) + 1) & 3], ((2 * (g_) + 1) >> 2) * 128); KRD(B_[3], kb[(2 * (g_) + 1) & 3], ((2 * (g_) + 1) >> 2) * 128 + 12288); } while (0)
; #define KWAIT(B_, n_) asm volatile("s_waitcnt lgkmcnt(" #n_ ")" : "+v"(B_[0]), "+v"(B_[1]), "+v"(B_[2]), "+v"(B_[3]) :: "memory")
; __device__ __forceinline__ void stage_qk_fin(int kboff, f32x16& x0, f32x16& x1, LAS unsigned char* lds, int r32, int hi, const bf16x8* qr,
;                                              f32x16& y0, f32x16& y1, float alY, float& l_reg, bf16x8& pa0, bf16x8& pa1, bf16x8& pa2, bf16x8& pa3) {
;     x0 = (f32x16){}; x1 = (f32x16){};
;     unsigned kb[4];
; #pragma unroll
;     for (int dd = 0; dd < 4; ++dd) kb[dd] = lds_addr(lds) + K_OFF + kboff + r32 * 384 + (((2 * dd + hi) ^ ((r32 >> 1) & 7)) << 4);
;     ...
;     float ps = 0.f; bf16x8 bA[2], bB[2];
;     SBAR(); KGRP(bA, 0); KGRP(bB, 1); KWAIT(bA, 2); SBAR();
;     KMS(bA, 0); KGRP(bA, 2); KWAIT(bB, 2); SBAR();
;     KMS(bB, 1); KGRP(bB, 3); KWAIT(bA, 2); SBAR();
;     KMS(bA, 2); KGRP(bA, 4); KWAIT(bB, 2); SBAR();
;     KMS(bB, 3); KGRP(bB, 5); KWAIT(bA, 2); SBAR();
;     KMS(bA, 4); KGRP(bA, 6); KWAIT(bB, 2); SBAR();
;     KMS(bB, 5); KGRP(bB, 7); KWAIT(bA, 2); SBAR();
;     KMS(bA, 6); KGRP(bA, 8); KWAIT(bB, 2); SBAR();
;     KMS(bB, 7); KGRP(bB, 9); KWAIT(bA, 2); SBAR();
;     KMS(bA, 8); KGRP(bA, 10); KWAIT(bB, 2); SBAR();
;     KMS(bB, 9); KGRP(bB, 11); KWAIT(bA, 2); SBAR();
;     KMS(bA, 10); KWAIT(bB, 0); SBAR();
;     KMS(bB, 11);
; __device__ __forceinline__ void stage_pv_par(f32x16* o, int vb0, bf16x8 pa0, bf16x8 pa1, bf16x8 pa2, bf16x8 pa3,
;                                              f32x16& x0, f32x16& x1, float& m_reg, float& alpha, float msk) {
;     ...
;     float pmax = 0.f, mnL = 0.f; s16x4 fA[8];
;     SBAR(); PV_RD(fA, 0); PV_WAIT(fA, 0); SBAR();
;     PVS(fA, 0); PV_RD(fA, 1); PV_WAIT(fA, 0); SBAR();
;     PVS(fA, 1); PV_RD(fA, 2); PV_WAIT(fA, 0); SBAR();
;     PVS(fA, 2); PV_RD(fA, 3); PV_WAIT(fA, 0); SBAR();
;     PVS(fA, 3);
	s_nop 0
	v_mfma_f32_32x32x16_bf16 v[96:111], v[2:5], v[152:155], v[96:111]
	v_add_f32_e32 v2, v235, v234
	v_add_f32_e32 v3, v120, v121
	v_add_f32_e32 v2, v2, v3
	v_add_f32_e32 v2, v2, v192
	v_mfma_f32_32x32x16_bf16 v[80:95], v[6:9], v[152:155], v[80:95]
	v_add_f32_e32 v3, v233, v232
	v_add_f32_e32 v4, v122, v123
	v_add_f32_e32 v3, v3, v4
	v_add_f32_e32 v192, v3, v2
	ds_read_b128 v[2:5], v181 offset:0x100
	ds_read_b128 v[6:9], v181 offset:0x3100
	s_waitcnt lgkmcnt(2)
	s_nop 0
	v_mfma_f32_32x32x16_bf16 v[96:111], v[10:13], v[156:159], v[96:111]
	v_add_f32_e32 v10, v231, v230
	v_add_f32_e32 v11, v124, v125
	v_add_f32_e32 v10, v10, v11
	v_add_f32_e32 v10, v10, v192
	v_mfma_f32_32x32x16_bf16 v[80:95], v[112:115], v[156:159], v[80:95]
	v_add_f32_e32 v11, v216, v179
	v_add_f32_e32 v12, v126, v127
	v_add_f32_e32 v11, v11, v12
	v_add_f32_e32 v200, v11, v10
	ds_read_b128 v[10:13], v219 offset:0x100
	ds_read_b128 v[112:115], v219 offset:0x3100
	s_waitcnt lgkmcnt(2)
	s_nop 0
	v_mfma_f32_32x32x16_bf16 v[96:111], v[2:5], v[160:163], v[96:111]
	v_mov_b32_e32 v201, v200
	s_nop 1
	v_permlane32_swap_b32_e32 v200, v201
	v_mfma_f32_32x32x16_bf16 v[80:95], v[6:9], v[160:163], v[80:95]
	v_cvt_pk_bf16_f32 v2, v243, v242
	v_cvt_pk_bf16_f32 v3, v241, v240
	v_cvt_pk_bf16_f32 v4, v239, v238
	v_cvt_pk_bf16_f32 v5, v237, v236
	s_nop 0
	v_permlane32_swap_b32_e32 v2, v4
	v_permlane32_swap_b32_e32 v3, v5
	ds_read_b128 v[194:197], v220 offset:0x100
	ds_read_b128 v[202:205], v220 offset:0x3100
	s_waitcnt lgkmcnt(2)
	s_nop 0
	v_mfma_f32_32x32x16_bf16 v[96:111], v[10:13], v[164:167], v[96:111]
	v_cvt_pk_bf16_f32 v6, v235, v234
	v_cvt_pk_bf16_f32 v7, v233, v232
	v_cvt_pk_bf16_f32 v8, v231, v230
	v_cvt_pk_bf16_f32 v9, v216, v179
	s_nop 0
	v_permlane32_swap_b32_e32 v6, v8
	v_permlane32_swap_b32_e32 v7, v9
	v_mfma_f32_32x32x16_bf16 v[80:95], v[112:115], v[164:167], v[80:95]
	v_cvt_pk_bf16_f32 v10, v14, v15
	v_cvt_pk_bf16_f32 v11, v176, v177
	v_cvt_pk_bf16_f32 v12, v116, v117
	v_cvt_pk_bf16_f32 v13, v118, v119
	s_nop 0
	v_permlane32_swap_b32_e32 v10, v12
	v_permlane32_swap_b32_e32 v11, v13
	ds_read_b128 v[206:209], v221 offset:0x100
	ds_read_b128 v[210:213], v221 offset:0x3100
	s_waitcnt lgkmcnt(2)
	s_nop 0
	v_mfma_f32_32x32x16_bf16 v[96:111], v[194:197], v[168:171], v[96:111]
	v_cvt_pk_bf16_f32 v112, v120, v121
	v_cvt_pk_bf16_f32 v113, v122, v123
	v_cvt_pk_bf16_f32 v114, v124, v125
	v_cvt_pk_bf16_f32 v115, v126, v127
	s_nop 0
	v_permlane32_swap_b32_e32 v112, v114
	v_permlane32_swap_b32_e32 v113, v115
	v_mfma_f32_32x32x16_bf16 v[80:95], v[202:205], v[168:171], v[80:95]
	v_add_f32_e32 v247, v200, v201
	v_fmac_f32_e32 v247, v245, v0
	v_mov_b32_e32 v245, v247
	s_waitcnt lgkmcnt(0)
	s_nop 0
	v_mfma_f32_32x32x16_bf16 v[96:111], v[206:209], v[172:175], v[96:111]
	v_mfma_f32_32x32x16_bf16 v[80:95], v[210:213], v[172:175], v[80:95]
	s_cmp_eq_u32 s100, 0
	s_cbranch_scc1 .Lmy_mid_b
	s_waitcnt vmcnt(0)
	s_barrier
.Lmy_mid_b:
	s_and_b32 s34, s34, 0xc000
	v_add_u32_e32 v217, s34, v225
	ds_read_b64_tr_b16 v[194:195], v217 offset:0
	ds_read_b64_tr_b16 v[196:197], v217 offset:0x800
	ds_read_b64_tr_b16 v[232:233], v217 offset:0x1000
	ds_read_b64_tr_b16 v[234:235], v217 offset:0x1800
	ds_read_b64_tr_b16 v[236:237], v217 offset:0x2000
	ds_read_b64_tr_b16 v[238:239], v217 offset:0x2800
	ds_read_b64_tr_b16 v[240:241], v217 offset:0x3000
	ds_read_b64_tr_b16 v[242:243], v217 offset:0x3800
	s_nop 0
	s_waitcnt lgkmcnt(0)
	s_nop 0
	v_mfma_f32_32x32x16_bf16 v[64:79], v[194:197], v[2:5], v[64:79]
	s_nop 5
	v_max_f32_e32 v192, v99, v99
	v_max_f32_e32 v194, v98, v98
	v_max_f32_e32 v192, v194, v192
	v_max_f32_e32 v194, v83, v83
	v_max_f32_e32 v195, v82, v82
	v_max3_f32 v192, v96, v97, v192
	v_max_f32_e32 v194, v195, v194
	v_max3_f32 v194, v80, v81, v194
	v_mfma_f32_32x32x16_bf16 v[64:79], v[232:235], v[6:9], v[64:79]
	v_max_f32_e32 v195, v101, v101
	v_max_f32_e32 v196, v100, v100
	v_max_f32_e32 v195, v196, v195
	v_max_f32_e32 v196, v103, v103
	v_max_f32_e32 v197, v102, v102
	v_max_f32_e32 v196, v197, v196
	v_max_f32_e32 v197, v87, v87
	v_max_f32_e32 v202, v86, v86
	v_max_f32_e32 v197, v202, v197
	v_max3_f32 v197, v84, v85, v197
	v_max3_f32 v195, v195, v196, v197
	v_max3_f32 v192, v192, v194, v195
	v_mfma_f32_32x32x16_bf16 v[64:79], v[236:239], v[10:13], v[64:79]
	v_max_f32_e32 v194, v105, v105
	v_max_f32_e32 v195, v104, v104
	v_max_f32_e32 v194, v195, v194
	v_max_f32_e32 v195, v107, v107
	v_max_f32_e32 v196, v106, v106
	v_max_f32_e32 v195, v196, v195
	v_max_f32_e32 v196, v91, v91
	v_max_f32_e32 v197, v90, v90
	v_max_f32_e32 v196, v197, v196
	v_max3_f32 v196, v88, v89, v196
	v_max3_f32 v194, v194, v195, v196
	v_mfma_f32_32x32x16_bf16 v[64:79], v[240:243], v[112:115], v[64:79]
	v_max_f32_e32 v195, v109, v109
	v_max_f32_e32 v196, v108, v108
	v_max_f32_e32 v195, v196, v195
	v_max_f32_e32 v196, v111, v111
	v_max_f32_e32 v197, v110, v110
	v_max_f32_e32 v196, v197, v196
	v_max_f32_e32 v197, v95, v95
	v_max_f32_e32 v202, v94, v94
	v_max_f32_e32 v197, v202, v197
	v_max3_f32 v197, v92, v93, v197
	v_max3_f32 v195, v195, v196, v197
	v_max3_f32 v192, v192, v194, v195
	ds_read_b64_tr_b16 v[194:195], v217 offset:0x200
	ds_read_b64_tr_b16 v[196:197], v217 offset:0xa00
	ds_read_b64_tr_b16 v[232:233], v217 offset:0x1200
	ds_read_b64_tr_b16 v[234:235], v217 offset:0x1a00
	ds_read_b64_tr_b16 v[236:237], v217 offset:0x2200
	ds_read_b64_tr_b16 v[238:239], v217 offset:0x2a00
	ds_read_b64_tr_b16 v[240:241], v217 offset:0x3200
	ds_read_b64_tr_b16 v[242:243], v217 offset:0x3a00
	s_nop 0
	s_waitcnt lgkmcnt(0)
; #define SBAR() __builtin_amdgcn_sched_barrier(0)
; #define PV_RD(F_, d0) do { constexpr int b_ = V_OFF + v_rd_off(d0, 0, 0); \
;         TRRD(F_[0], b_); TRRD(F_[1], b_ + 2048); TRRD(F_[2], b_ + 4096); TRRD(F_[3], b_ + 6144); TRRD(F_[4], b_ + 8192); TRRD(F_[5], b_ + 10240); TRRD(F_[6], b_ + 12288); TRRD(F_[7], b_ + 14336); } while (0)
; #define PV_WAIT(F_, n_) asm volatile("s_waitcnt lgkmcnt(" #n_ ")" : "+v"(F_[0]), "+v"(F_[1]), "+v"(F_[2]), "+v"(F_[3]), "+v"(F_[4]), "+v"(F_[5]), "+v"(F_[6]), "+v"(F_[7]) :: "memory")
; __device__ __forceinline__ void stage_pv_par(f32x16* o, int vb0, bf16x8 pa0, bf16x8 pa1, bf16x8 pa2, bf16x8 pa3,
;                                              f32x16& x0, f32x16& x1, float& m_reg, float& alpha, float msk) {
;     ...
;     float pmax = 0.f, mnL = 0.f; s16x4 fA[8];
;     SBAR(); PV_RD(fA, 0); PV_WAIT(fA, 0); SBAR();
;     PVS(fA, 0); PV_RD(fA, 1); PV_WAIT(fA, 0); SBAR();
;     PVS(fA, 1); PV_RD(fA, 2); PV_WAIT(fA, 0); SBAR();
;     PVS(fA, 2); PV_RD(fA, 3); PV_WAIT(fA, 0); SBAR();
;     PVS(fA, 3);
; __device__ __forceinline__ void attn_block(const Params& p, LAS unsigned char* lds, int h, int qb) {
;     ...
;     ADMA(0, 0, 0); __syncthreads();
;     ADMA(1, 1, 1);
;     qkt(0, pA0, pA1, lds, r32, hi, qr); partialSM(pA0, pA1, m_reg, mnA, alA);
;     __syncthreads();
	v_add_f32_e32 v192, v178, v192
	v_mfma_f32_32x32x16_bf16 v[48:63], v[194:197], v[2:5], v[48:63]
	v_mov_b32_e32 v194, v192
	s_nop 1
	v_permlane32_swap_b32_e32 v192, v194
	v_max_f32_e32 v194, v194, v194
	v_max_f32_e32 v192, v192, v192
	v_max_f32_e32 v192, v192, v194
	v_sub_f32_e32 v194, v192, v246
	v_mul_f32_e32 v194, 0x3d93cd3a, v194
	v_cmp_ge_f32_e32 vcc, s63, v194
	s_cmp_eq_u64 vcc, exec
	v_max_f32_e32 v194, v246, v246
	s_cselect_b64 vcc, -1, 0
	v_max_f32_e32 v192, v194, v192
	v_cndmask_b32_e32 v244, v192, v246, vcc
	v_sub_f32_e32 v192, v246, v244
	v_mul_f32_e32 v192, 0x3dd53b94, v192
	v_exp_f32_e32 v192, v192
	v_fmac_f32_e32 v178, 0xbdd53b94, v244
	v_mfma_f32_32x32x16_bf16 v[48:63], v[232:235], v[6:9], v[48:63]
	v_fmamk_f32 v214, v80, 0x3dd53b94, v178
	v_fmamk_f32 v215, v81, 0x3dd53b94, v178
	v_fmamk_f32 v212, v82, 0x3dd53b94, v178
	v_fmamk_f32 v213, v83, 0x3dd53b94, v178
	v_fmamk_f32 v210, v84, 0x3dd53b94, v178
	v_fmamk_f32 v211, v85, 0x3dd53b94, v178
	v_mfma_f32_32x32x16_bf16 v[48:63], v[236:239], v[10:13], v[48:63]
	v_fmamk_f32 v208, v86, 0x3dd53b94, v178
	v_fmamk_f32 v209, v87, 0x3dd53b94, v178
	v_fmamk_f32 v206, v88, 0x3dd53b94, v178
	v_fmamk_f32 v207, v89, 0x3dd53b94, v178
	v_fmamk_f32 v204, v90, 0x3dd53b94, v178
	v_fmamk_f32 v205, v91, 0x3dd53b94, v178
	v_mfma_f32_32x32x16_bf16 v[48:63], v[240:243], v[112:115], v[48:63]
	v_fmamk_f32 v202, v92, 0x3dd53b94, v178
	v_fmamk_f32 v203, v93, 0x3dd53b94, v178
	v_fmamk_f32 v200, v94, 0x3dd53b94, v178
	v_fmamk_f32 v201, v95, 0x3dd53b94, v178
	v_fmamk_f32 v96, v96, 0x3dd53b94, v178
	v_fmamk_f32 v97, v97, 0x3dd53b94, v178
	ds_read_b64_tr_b16 v[194:195], v217 offset:0x400
	ds_read_b64_tr_b16 v[196:197], v217 offset:0xc00
	ds_read_b64_tr_b16 v[232:233], v217 offset:0x1400
	ds_read_b64_tr_b16 v[234:235], v217 offset:0x1c00
	ds_read_b64_tr_b16 v[236:237], v217 offset:0x2400
	ds_read_b64_tr_b16 v[238:239], v217 offset:0x2c00
	ds_read_b64_tr_b16 v[240:241], v217 offset:0x3400
	ds_read_b64_tr_b16 v[242:243], v217 offset:0x3c00
	s_nop 0
	s_waitcnt lgkmcnt(0)
	s_nop 0
	v_mfma_f32_32x32x16_bf16 v[32:47], v[194:197], v[2:5], v[32:47]
	v_fmamk_f32 v98, v98, 0x3dd53b94, v178
	v_fmamk_f32 v99, v99, 0x3dd53b94, v178
	v_exp_f32_e32 v80, v96
	v_exp_f32_e32 v81, v97
	v_mfma_f32_32x32x16_bf16 v[32:47], v[232:235], v[6:9], v[32:47]
	v_fmamk_f32 v100, v100, 0x3dd53b94, v178
	v_fmamk_f32 v101, v101, 0x3dd53b94, v178
	v_exp_f32_e32 v82, v98
	v_exp_f32_e32 v83, v99
	v_mfma_f32_32x32x16_bf16 v[32:47], v[236:239], v[10:13], v[32:47]
	v_fmamk_f32 v102, v102, 0x3dd53b94, v178
	v_fmamk_f32 v103, v103, 0x3dd53b94, v178
	v_exp_f32_e32 v84, v100
	v_exp_f32_e32 v85, v101
	v_mfma_f32_32x32x16_bf16 v[32:47], v[240:243], v[112:115], v[32:47]
	v_fmamk_f32 v104, v104, 0x3dd53b94, v178
	v_fmamk_f32 v105, v105, 0x3dd53b94, v178
	v_exp_f32_e32 v86, v102
	v_exp_f32_e32 v87, v103
	ds_read_b64_tr_b16 v[194:195], v217 offset:0x600
	ds_read_b64_tr_b16 v[196:197], v217 offset:0xe00
	ds_read_b64_tr_b16 v[232:233], v217 offset:0x1600
	ds_read_b64_tr_b16 v[234:235], v217 offset:0x1e00
	ds_read_b64_tr_b16 v[236:237], v217 offset:0x2600
	ds_read_b64_tr_b16 v[238:239], v217 offset:0x2e00
	ds_read_b64_tr_b16 v[240:241], v217 offset:0x3600
	ds_read_b64_tr_b16 v[242:243], v217 offset:0x3e00
	s_nop 0
	s_waitcnt lgkmcnt(0)
	s_nop 0
	v_mfma_f32_32x32x16_bf16 v[16:31], v[194:197], v[2:5], v[16:31]
	v_fmamk_f32 v106, v106, 0x3dd53b94, v178
	v_fmamk_f32 v107, v107, 0x3dd53b94, v178
	v_exp_f32_e32 v88, v104
	v_exp_f32_e32 v89, v105
	v_mfma_f32_32x32x16_bf16 v[16:31], v[232:235], v[6:9], v[16:31]
	v_fmamk_f32 v108, v108, 0x3dd53b94, v178
	v_fmamk_f32 v109, v109, 0x3dd53b94, v178
	v_exp_f32_e32 v90, v106
	v_exp_f32_e32 v91, v107
	v_mfma_f32_32x32x16_bf16 v[16:31], v[236:239], v[10:13], v[16:31]
	v_fmamk_f32 v110, v110, 0x3dd53b94, v178
	v_fmamk_f32 v111, v111, 0x3dd53b94, v178
	v_exp_f32_e32 v92, v108
	v_exp_f32_e32 v93, v109
	v_mfma_f32_32x32x16_bf16 v[16:31], v[240:243], v[112:115], v[16:31]
	v_cmp_gt_f32_e32 vcc, 1.0, v192
	s_cbranch_vccz .LBB0_335
	v_pk_mul_f32 v[78:79], v[78:79], v[192:193] op_sel_hi:[1,0]
	v_pk_mul_f32 v[76:77], v[76:77], v[192:193] op_sel_hi:[1,0]
	v_pk_mul_f32 v[74:75], v[74:75], v[192:193] op_sel_hi:[1,0]
	v_pk_mul_f32 v[72:73], v[72:73], v[192:193] op_sel_hi:[1,0]
	v_pk_mul_f32 v[70:71], v[70:71], v[192:193] op_sel_hi:[1,0]
	v_pk_mul_f32 v[68:69], v[68:69], v[192:193] op_sel_hi:[1,0]
	v_pk_mul_f32 v[66:67], v[66:67], v[192:193] op_sel_hi:[1,0]
	v_pk_mul_f32 v[64:65], v[64:65], v[192:193] op_sel_hi:[1,0]
	v_pk_mul_f32 v[62:63], v[192:193], v[62:63] op_sel_hi:[0,1]
	v_pk_mul_f32 v[60:61], v[192:193], v[60:61] op_sel_hi:[0,1]
	v_pk_mul_f32 v[58:59], v[192:193], v[58:59] op_sel_hi:[0,1]
	v_pk_mul_f32 v[56:57], v[192:193], v[56:57] op_sel_hi:[0,1]
	v_pk_mul_f32 v[54:55], v[192:193], v[54:55] op_sel_hi:[0,1]
	v_pk_mul_f32 v[52:53], v[192:193], v[52:53] op_sel_hi:[0,1]
	v_pk_mul_f32 v[50:51], v[192:193], v[50:51] op_sel_hi:[0,1]
	v_pk_mul_f32 v[48:49], v[192:193], v[48:49] op_sel_hi:[0,1]
	v_pk_mul_f32 v[46:47], v[192:193], v[46:47] op_sel_hi:[0,1]
	v_pk_mul_f32 v[44:45], v[192:193], v[44:45] op_sel_hi:[0,1]
	v_pk_mul_f32 v[42:43], v[192:193], v[42:43] op_sel_hi:[0,1]
	v_pk_mul_f32 v[40:41], v[192:193], v[40:41] op_sel_hi:[0,1]
	v_pk_mul_f32 v[38:39], v[192:193], v[38:39] op_sel_hi:[0,1]
	v_pk_mul_f32 v[36:37], v[192:193], v[36:37] op_sel_hi:[0,1]
	v_pk_mul_f32 v[34:35], v[192:193], v[34:35] op_sel_hi:[0,1]
	v_pk_mul_f32 v[32:33], v[192:193], v[32:33] op_sel_hi:[0,1]
	v_pk_mul_f32 v[30:31], v[192:193], v[30:31] op_sel_hi:[0,1]
	v_pk_mul_f32 v[28:29], v[192:193], v[28:29] op_sel_hi:[0,1]
	v_pk_mul_f32 v[26:27], v[192:193], v[26:27] op_sel_hi:[0,1]
	v_pk_mul_f32 v[24:25], v[192:193], v[24:25] op_sel_hi:[0,1]
	v_pk_mul_f32 v[22:23], v[192:193], v[22:23] op_sel_hi:[0,1]
	v_pk_mul_f32 v[20:21], v[192:193], v[20:21] op_sel_hi:[0,1]
	v_pk_mul_f32 v[18:19], v[192:193], v[18:19] op_sel_hi:[0,1]
	v_pk_mul_f32 v[16:17], v[192:193], v[16:17] op_sel_hi:[0,1]
.LBB0_335:
	v_exp_f32_e32 v94, v110
	v_exp_f32_e32 v95, v111
	s_waitcnt vmcnt(0) lgkmcnt(0)
	s_cmp_lg_u32 s100, 0
	s_cbranch_scc1 .Lmy_end_b
	s_barrier
.Lmy_end_b:
	s_branch .LBB0_337
.LBB0_336:
	v_mov_b32_e32 v244, v246

; __device__ __forceinline__ int otid() { int t = threadIdx.x; asm volatile("" : "+v"(t)); return t; }
; __device__ __forceinline__ int obid() { int t = blockIdx.x; asm volatile("" : "+s"(t)); return t; }
; __device__ __forceinline__ int ogdim() { int t = gridDim.x; asm volatile("" : "+s"(t)); return t; }
; #define SLOAD(U_, D_, n0_) do { _Pragma("unroll") for (int j = 0; j < 16; ++j) { U_[j] = bf2f(sbuf[(size_t)((n0_) + j) * 131072 + e]); D_[j] = decg[(size_t)((n0_) + j) * 512 + dcol]; } } while (0)
; #define SPROC(U_, D_, n0_) do { _Pragma("unroll") for (int j = 0; j < 16; ++j) { sbuf[(size_t)((n0_) + j) * 131072 + e] = f2bf(st); st = D_[j] * st + U_[j]; } } while (0)
; __device__ __forceinline__ void gla_scan(const Params& p) {
;     bf16_t* sbuf = (bf16_t*)(p.ws + O_S); const float* decg = (const float*)(p.ws + O_DEC);
;     for (int e = obid() * NTHREADS + otid(); e < 4 * 256 * 128; e += ogdim() * NTHREADS) {
;         const int dcol = (e >> 15) * 128 + (e & 127); float st = 0.f;
;         float u0[16], d0[16], u1[16], d1[16];
;     ...
;         SLOAD(u0, d0, 0);
; #pragma unroll 1
;         for (int n0 = 0; n0 < 256; n0 += 32) {
;             SLOAD(u1, d1, n0 + 16);
;             SPROC(u0, d0, n0);
;             if (n0 + 32 < 256) SLOAD(u0, d0, n0 + 32);
;             SPROC(u1, d1, n0 + 16);
.LBB0_470:
	v_readlane_b32 s0, v253, 0
	v_mov_b32_e32 v0, v199
	s_nop 0
	v_lshl_add_u32 v2, s0, 9, v0
	s_mov_b32 s0, 0x20000
	v_cmp_gt_i32_e32 vcc, s0, v2
	s_and_saveexec_b64 s[12:13], vcc
	s_cbranch_execz .LBB0_477
	s_add_u32 s40, s14, 0x32a00000
	s_addc_u32 s41, s15, 0
	s_add_u32 s42, s14, 0x36a00000
	s_addc_u32 s43, s15, 0
	v_readlane_b32 s44, v253, 0
	v_lshrrev_b32_e32 v0, 5, v199
	v_and_b32_e32 v2, 31, v199
	v_lshlrev_b32_e32 v0, 11, v0
	v_lshl_add_u32 v0, v2, 4, v0
	v_lshlrev_b32_e32 v3, 4, v199
	v_add_u32_e32 v68, 0x10000, v3
	v_lshlrev_b32_e32 v2, 1, v199
	v_and_b32_e32 v69, 0x7f, v199
	v_lshlrev_b32_e32 v69, 2, v69
	v_add_u32_e32 v70, 0x10000, v69
.Lmy_sc_blk:
	s_cmpk_lt_u32 s44, 0x100
	s_cbranch_scc0 .Lmy_sc_done
	s_lshr_b32 s45, s44, 6
	s_lshl_b32 s45, s45, 9
	s_add_u32 s0, s42, s45
	s_addc_u32 s1, s43, 0
	global_load_dwordx4 v[4:7], v0, s[0:1]
	s_add_u32 s0, s0, 0x8000
	s_addc_u32 s1, s1, 0
	global_load_dwordx4 v[8:11], v0, s[0:1]
	s_add_u32 s0, s0, 0x8000
	s_addc_u32 s1, s1, 0
	global_load_dwordx4 v[12:15], v0, s[0:1]
	s_add_u32 s0, s0, 0x8000
	s_addc_u32 s1, s1, 0
	global_load_dwordx4 v[16:19], v0, s[0:1]
	s_add_u32 s0, s0, 0x8000
	s_addc_u32 s1, s1, 0
	global_load_dwordx4 v[20:23], v0, s[0:1]
	s_add_u32 s0, s0, 0x8000
	s_addc_u32 s1, s1, 0
	global_load_dwordx4 v[24:27], v0, s[0:1]
	s_add_u32 s0, s0, 0x8000
	s_addc_u32 s1, s1, 0
	global_load_dwordx4 v[28:31], v0, s[0:1]
	s_add_u32 s0, s0, 0x8000
	s_addc_u32 s1, s1, 0
	global_load_dwordx4 v[32:35], v0, s[0:1]
	s_add_u32 s0, s0, 0x8000
	s_addc_u32 s1, s1, 0
	global_load_dwordx4 v[36:39], v0, s[0:1]
	s_add_u32 s0, s0, 0x8000
	s_addc_u32 s1, s1, 0
	global_load_dwordx4 v[40:43], v0, s[0:1]
	s_add_u32 s0, s0, 0x8000
	s_addc_u32 s1, s1, 0
	global_load_dwordx4 v[44:47], v0, s[0:1]
	s_add_u32 s0, s0, 0x8000
	s_addc_u32 s1, s1, 0
	global_load_dwordx4 v[48:51], v0, s[0:1]
	s_add_u32 s0, s0, 0x8000
	s_addc_u32 s1, s1, 0
	global_load_dwordx4 v[52:55], v0, s[0:1]
	s_add_u32 s0, s0, 0x8000
	s_addc_u32 s1, s1, 0
	global_load_dwordx4 v[56:59], v0, s[0:1]
	s_add_u32 s0, s0, 0x8000
	s_addc_u32 s1, s1, 0
	global_load_dwordx4 v[60:63], v0, s[0:1]
	s_add_u32 s0, s0, 0x8000
	s_addc_u32 s1, s1, 0
	global_load_dwordx4 v[64:67], v0, s[0:1]
	s_lshl_b32 s45, s44, 10
	s_add_u32 s16, s40, s45
	s_addc_u32 s17, s41, 0
	s_mov_b32 s98, s16
	s_mov_b32 s99, s17
	s_waitcnt vmcnt(0)
	ds_write_b128 v3, v[4:7] offset:0
	ds_write_b128 v3, v[8:11] offset:8192
	ds_write_b128 v3, v[12:15] offset:16384
	ds_write_b128 v3, v[16:19] offset:24576
	ds_write_b128 v3, v[20:23] offset:32768
	ds_write_b128 v3, v[24:27] offset:40960
	ds_write_b128 v3, v[28:31] offset:49152
	ds_write_b128 v3, v[32:35] offset:57344
	ds_write_b128 v68, v[36:39] offset:0
	ds_write_b128 v68, v[40:43] offset:8192
	ds_write_b128 v68, v[44:47] offset:16384
	ds_write_b128 v68, v[48:51] offset:24576
	ds_write_b128 v68, v[52:55] offset:32768
	ds_write_b128 v68, v[56:59] offset:40960
	ds_write_b128 v68, v[60:63] offset:49152
	ds_write_b128 v68, v[64:67] offset:57344
	global_load_ushort v4, v2, s[16:17]
	s_add_u32 s16, s16, 0x40000
	s_addc_u32 s17, s17, 0
	global_load_ushort v5, v2, s[16:17]
	s_add_u32 s16, s16, 0x40000
	s_addc_u32 s17, s17, 0
	global_load_ushort v6, v2, s[16:17]
	s_add_u32 s16, s16, 0x40000
	s_addc_u32 s17, s17, 0
	global_load_ushort v7, v2, s[16:17]
	s_add_u32 s16, s16, 0x40000
	s_addc_u32 s17, s17, 0
	global_load_ushort v8, v2, s[16:17]
	s_add_u32 s16, s16, 0x40000
	s_addc_u32 s17, s17, 0
	global_load_ushort v9, v2, s[16:17]
	s_add_u32 s16, s16, 0x40000
	s_addc_u32 s17, s17, 0
	global_load_ushort v10, v2, s[16:17]
	s_add_u32 s16, s16, 0x40000
	s_addc_u32 s17, s17, 0
	global_load_ushort v11, v2, s[16:17]
	s_add_u32 s16, s16, 0x40000
	s_addc_u32 s17, s17, 0
	global_load_ushort v12, v2, s[16:17]
	s_add_u32 s16, s16, 0x40000
	s_addc_u32 s17, s17, 0
	global_load_ushort v13, v2, s[16:17]
	s_add_u32 s16, s16, 0x40000
	s_addc_u32 s17, s17, 0
	global_load_ushort v14, v2, s[16:17]
	s_add_u32 s16, s16, 0x40000
	s_addc_u32 s17, s17, 0
	global_load_ushort v15, v2, s[16:17]
	s_add_u32 s16, s16, 0x40000
	s_addc_u32 s17, s17, 0
	global_load_ushort v16, v2, s[16:17]
	s_add_u32 s16, s16, 0x40000
	s_addc_u32 s17, s17, 0
	global_load_ushort v17, v2, s[16:17]
	s_add_u32 s16, s16, 0x40000
	s_addc_u32 s17, s17, 0
	global_load_ushort v18, v2, s[16:17]
	s_add_u32 s16, s16, 0x40000
	s_addc_u32 s17, s17, 0
	global_load_ushort v19, v2, s[16:17]
	s_add_u32 s16, s16, 0x40000
	s_addc_u32 s17, s17, 0
	global_load_ushort v20, v2, s[16:17]
	s_add_u32 s16, s16, 0x40000
	s_addc_u32 s17, s17, 0
	global_load_ushort v21, v2, s[16:17]
	s_add_u32 s16, s16, 0x40000
	s_addc_u32 s17, s17, 0
	global_load_ushort v22, v2, s[16:17]
	s_add_u32 s16, s16, 0x40000
	s_addc_u32 s17, s17, 0
	global_load_ushort v23, v2, s[16:17]
	s_add_u32 s16, s16, 0x40000
	s_addc_u32 s17, s17, 0
	global_load_ushort v24, v2, s[16:17]
	s_add_u32 s16, s16, 0x40000
	s_addc_u32 s17, s17, 0
	global_load_ushort v25, v2, s[16:17]
	s_add_u32 s16, s16, 0x40000
	s_addc_u32 s17, s17, 0
	global_load_ushort v26, v2, s[16:17]
	s_add_u32 s16, s16, 0x40000
	s_addc_u32 s17, s17, 0
	global_load_ushort v27, v2, s[16:17]
	s_add_u32 s16, s16, 0x40000
	s_addc_u32 s17, s17, 0
	global_load_ushort v28, v2, s[16:17]
	s_add_u32 s16, s16, 0x40000
	s_addc_u32 s17, s17, 0
	global_load_ushort v29, v2, s[16:17]
	s_add_u32 s16, s16, 0x40000
	s_addc_u32 s17, s17, 0
	global_load_ushort v30, v2, s[16:17]
	s_add_u32 s16, s16, 0x40000
	s_addc_u32 s17, s17, 0
	global_load_ushort v31, v2, s[16:17]
	s_add_u32 s16, s16, 0x40000
	s_addc_u32 s17, s17, 0
	global_load_ushort v32, v2, s[16:17]
	s_add_u32 s16, s16, 0x40000
	s_addc_u32 s17, s17, 0
	global_load_ushort v33, v2, s[16:17]
	s_add_u32 s16, s16, 0x40000
	s_addc_u32 s17, s17, 0
	global_load_ushort v34, v2, s[16:17]
	s_add_u32 s16, s16, 0x40000
	s_addc_u32 s17, s17, 0
	global_load_ushort v35, v2, s[16:17]
	s_add_u32 s16, s16, 0x40000
	s_addc_u32 s17, s17, 0
	s_waitcnt lgkmcnt(0)
	s_barrier
; __device__ __forceinline__ int otid() { int t = threadIdx.x; asm volatile("" : "+v"(t)); return t; }
; __device__ __forceinline__ int obid() { int t = blockIdx.x; asm volatile("" : "+s"(t)); return t; }
; __device__ __forceinline__ int ogdim() { int t = gridDim.x; asm volatile("" : "+s"(t)); return t; }
; #define SLOAD(U_, D_, n0_) do { _Pragma("unroll") for (int j = 0; j < 16; ++j) { U_[j] = bf2f(sbuf[(size_t)((n0_) + j) * 131072 + e]); D_[j] = decg[(size_t)((n0_) + j) * 512 + dcol]; } } while (0)
; #define SPROC(U_, D_, n0_) do { _Pragma("unroll") for (int j = 0; j < 16; ++j) { sbuf[(size_t)((n0_) + j) * 131072 + e] = f2bf(st); st = D_[j] * st + U_[j]; } } while (0)
; __device__ __forceinline__ void gla_scan(const Params& p) {
;     ...
;     for (int e = obid() * NTHREADS + otid(); e < 4 * 256 * 128; e += ogdim() * NTHREADS) {
;         const int dcol = (e >> 15) * 128 + (e & 127); float st = 0.f;
;         float u0[16], d0[16], u1[16], d1[16];
;     ...
;         SLOAD(u0, d0, 0);
; #pragma unroll 1
;         for (int n0 = 0; n0 < 256; n0 += 32) {
;             SLOAD(u1, d1, n0 + 16);
;             SPROC(u0, d0, n0);
;             if (n0 + 32 < 256) SLOAD(u0, d0, n0 + 32);
;             SPROC(u1, d1, n0 + 16);
;         }
	v_mov_b32_e32 v71, 0
	global_load_ushort v36, v2, s[16:17]
	s_add_u32 s16, s16, 0x40000
	s_addc_u32 s17, s17, 0
	global_load_ushort v37, v2, s[16:17]
	s_add_u32 s16, s16, 0x40000
	s_addc_u32 s17, s17, 0
	global_load_ushort v38, v2, s[16:17]
	s_add_u32 s16, s16, 0x40000
	s_addc_u32 s17, s17, 0
	global_load_ushort v39, v2, s[16:17]
	s_add_u32 s16, s16, 0x40000
	s_addc_u32 s17, s17, 0
	global_load_ushort v40, v2, s[16:17]
	s_add_u32 s16, s16, 0x40000
	s_addc_u32 s17, s17, 0
	global_load_ushort v41, v2, s[16:17]
	s_add_u32 s16, s16, 0x40000
	s_addc_u32 s17, s17, 0
	global_load_ushort v42, v2, s[16:17]
	s_add_u32 s16, s16, 0x40000
	s_addc_u32 s17, s17, 0
	global_load_ushort v43, v2, s[16:17]
	s_add_u32 s16, s16, 0x40000
	s_addc_u32 s17, s17, 0
	ds_read_b32 v76, v69 offset:0
	ds_read_b32 v77, v69 offset:512
	ds_read_b32 v78, v69 offset:1024
	ds_read_b32 v79, v69 offset:1536
	ds_read_b32 v80, v69 offset:2048
	ds_read_b32 v81, v69 offset:2560
	ds_read_b32 v82, v69 offset:3072
	ds_read_b32 v83, v69 offset:3584
	s_waitcnt vmcnt(32)
	s_waitcnt lgkmcnt(0)
	v_cvt_pk_bf16_f32 v72, v71, v71
	v_lshlrev_b32_e32 v74, 16, v4
	global_store_short v2, v72, s[98:99]
	s_add_u32 s98, s98, 0x40000
	s_addc_u32 s99, s99, 0
	v_fma_f32 v71, v76, v71, v74
	v_cvt_pk_bf16_f32 v73, v71, v71
	v_lshlrev_b32_e32 v74, 16, v5
	global_store_short v2, v73, s[98:99]
	s_add_u32 s98, s98, 0x40000
	s_addc_u32 s99, s99, 0
	v_fma_f32 v71, v77, v71, v74
	v_cvt_pk_bf16_f32 v72, v71, v71
	v_lshlrev_b32_e32 v74, 16, v6
	global_store_short v2, v72, s[98:99]
	s_add_u32 s98, s98, 0x40000
	s_addc_u32 s99, s99, 0
	v_fma_f32 v71, v78, v71, v74
	v_cvt_pk_bf16_f32 v73, v71, v71
	v_lshlrev_b32_e32 v74, 16, v7
	global_store_short v2, v73, s[98:99]
	s_add_u32 s98, s98, 0x40000
	s_addc_u32 s99, s99, 0
	v_fma_f32 v71, v79, v71, v74
	v_cvt_pk_bf16_f32 v72, v71, v71
	v_lshlrev_b32_e32 v74, 16, v8
	global_store_short v2, v72, s[98:99]
	s_add_u32 s98, s98, 0x40000
	s_addc_u32 s99, s99, 0
	v_fma_f32 v71, v80, v71, v74
	v_cvt_pk_bf16_f32 v73, v71, v71
	v_lshlrev_b32_e32 v74, 16, v9
	global_store_short v2, v73, s[98:99]
	s_add_u32 s98, s98, 0x40000
	s_addc_u32 s99, s99, 0
	v_fma_f32 v71, v81, v71, v74
	v_cvt_pk_bf16_f32 v72, v71, v71
	v_lshlrev_b32_e32 v74, 16, v10
	global_store_short v2, v72, s[98:99]
	s_add_u32 s98, s98, 0x40000
	s_addc_u32 s99, s99, 0
	v_fma_f32 v71, v82, v71, v74
	v_cvt_pk_bf16_f32 v73, v71, v71
	v_lshlrev_b32_e32 v74, 16, v11
	global_store_short v2, v73, s[98:99]
	s_add_u32 s98, s98, 0x40000
	s_addc_u32 s99, s99, 0
	v_fma_f32 v71, v83, v71, v74
	global_load_ushort v4, v2, s[16:17]
	s_add_u32 s16, s16, 0x40000
	s_addc_u32 s17, s17, 0
	global_load_ushort v5, v2, s[16:17]
	s_add_u32 s16, s16, 0x40000
	s_addc_u32 s17, s17, 0
	global_load_ushort v6, v2, s[16:17]
	s_add_u32 s16, s16, 0x40000
	s_addc_u32 s17, s17, 0
	global_load_ushort v7, v2, s[16:17]
	s_add_u32 s16, s16, 0x40000
	s_addc_u32 s17, s17, 0
	global_load_ushort v8, v2, s[16:17]
	s_add_u32 s16, s16, 0x40000
	s_addc_u32 s17, s17, 0
	global_load_ushort v9, v2, s[16:17]
	s_add_u32 s16, s16, 0x40000
	s_addc_u32 s17, s17, 0
	global_load_ushort v10, v2, s[16:17]
	s_add_u32 s16, s16, 0x40000
	s_addc_u32 s17, s17, 0
	global_load_ushort v11, v2, s[16:17]
	s_add_u32 s16, s16, 0x40000
	s_addc_u32 s17, s17, 0
	ds_read_b32 v76, v69 offset:4096
	ds_read_b32 v77, v69 offset:4608
	ds_read_b32 v78, v69 offset:5120
	ds_read_b32 v79, v69 offset:5632
	ds_read_b32 v80, v69 offset:6144
	ds_read_b32 v81, v69 offset:6656
	ds_read_b32 v82, v69 offset:7168
	ds_read_b32 v83, v69 offset:7680
	s_waitcnt vmcnt(40)
	s_waitcnt lgkmcnt(0)
	v_cvt_pk_bf16_f32 v72, v71, v71
	v_lshlrev_b32_e32 v74, 16, v12
	global_store_short v2, v72, s[98:99]
	s_add_u32 s98, s98, 0x40000
	s_addc_u32 s99, s99, 0
	v_fma_f32 v71, v76, v71, v74
	v_cvt_pk_bf16_f32 v73, v71, v71
	v_lshlrev_b32_e32 v74, 16, v13
	global_store_short v2, v73, s[98:99]
	s_add_u32 s98, s98, 0x40000
	s_addc_u32 s99, s99, 0
	v_fma_f32 v71, v77, v71, v74
	v_cvt_pk_bf16_f32 v72, v71, v71
	v_lshlrev_b32_e32 v74, 16, v14
	global_store_short v2, v72, s[98:99]
	s_add_u32 s98, s98, 0x40000
	s_addc_u32 s99, s99, 0
	v_fma_f32 v71, v78, v71, v74
	v_cvt_pk_bf16_f32 v73, v71, v71
	v_lshlrev_b32_e32 v74, 16, v15
	global_store_short v2, v73, s[98:99]
	s_add_u32 s98, s98, 0x40000
	s_addc_u32 s99, s99, 0
	v_fma_f32 v71, v79, v71, v74
	v_cvt_pk_bf16_f32 v72, v71, v71
	v_lshlrev_b32_e32 v74, 16, v16
	global_store_short v2, v72, s[98:99]
	s_add_u32 s98, s98, 0x40000
	s_addc_u32 s99, s99, 0
	v_fma_f32 v71, v80, v71, v74
	v_cvt_pk_bf16_f32 v73, v71, v71
	v_lshlrev_b32_e32 v74, 16, v17
	global_store_short v2, v73, s[98:99]
	s_add_u32 s98, s98, 0x40000
	s_addc_u32 s99, s99, 0
	v_fma_f32 v71, v81, v71, v74
	v_cvt_pk_bf16_f32 v72, v71, v71
	v_lshlrev_b32_e32 v74, 16, v18
	global_store_short v2, v72, s[98:99]
	s_add_u32 s98, s98, 0x40000
	s_addc_u32 s99, s99, 0
	v_fma_f32 v71, v82, v71, v74
	v_cvt_pk_bf16_f32 v73, v71, v71
	v_lshlrev_b32_e32 v74, 16, v19
	global_store_short v2, v73, s[98:99]
	s_add_u32 s98, s98, 0x40000
	s_addc_u32 s99, s99, 0
	v_fma_f32 v71, v83, v71, v74
	global_load_ushort v12, v2, s[16:17]
	s_add_u32 s16, s16, 0x40000
	s_addc_u32 s17, s17, 0
	global_load_ushort v13, v2, s[16:17]
	s_add_u32 s16, s16, 0x40000
	s_addc_u32 s17, s17, 0
	global_load_ushort v14, v2, s[16:17]
	s_add_u32 s16, s16, 0x40000
	s_addc_u32 s17, s17, 0
	global_load_ushort v15, v2, s[16:17]
	s_add_u32 s16, s16, 0x40000
	s_addc_u32 s17, s17, 0
	global_load_ushort v16, v2, s[16:17]
	s_add_u32 s16, s16, 0x40000
	s_addc_u32 s17, s17, 0
	global_load_ushort v17, v2, s[16:17]
	s_add_u32 s16, s16, 0x40000
	s_addc_u32 s17, s17, 0
	global_load_ushort v18, v2, s[16:17]
	s_add_u32 s16, s16, 0x40000
	s_addc_u32 s17, s17, 0
	global_load_ushort v19, v2, s[16:17]
	s_add_u32 s16, s16, 0x40000
	s_addc_u32 s17, s17, 0
	ds_read_b32 v76, v69 offset:8192
	ds_read_b32 v77, v69 offset:8704
	ds_read_b32 v78, v69 offset:9216
	ds_read_b32 v79, v69 offset:9728
	ds_read_b32 v80, v69 offset:10240
	ds_read_b32 v81, v69 offset:10752
	ds_read_b32 v82, v69 offset:11264
	ds_read_b32 v83, v69 offset:11776
	s_waitcnt vmcnt(48)
; __device__ __forceinline__ int otid() { int t = threadIdx.x; asm volatile("" : "+v"(t)); return t; }
; __device__ __forceinline__ int obid() { int t = blockIdx.x; asm volatile("" : "+s"(t)); return t; }
; __device__ __forceinline__ int ogdim() { int t = gridDim.x; asm volatile("" : "+s"(t)); return t; }
; #define SLOAD(U_, D_, n0_) do { _Pragma("unroll") for (int j = 0; j < 16; ++j) { U_[j] = bf2f(sbuf[(size_t)((n0_) + j) * 131072 + e]); D_[j] = decg[(size_t)((n0_) + j) * 512 + dcol]; } } while (0)
; #define SPROC(U_, D_, n0_) do { _Pragma("unroll") for (int j = 0; j < 16; ++j) { sbuf[(size_t)((n0_) + j) * 131072 + e] = f2bf(st); st = D_[j] * st + U_[j]; } } while (0)
; __device__ __forceinline__ void gla_scan(const Params& p) {
;     ...
;     for (int e = obid() * NTHREADS + otid(); e < 4 * 256 * 128; e += ogdim() * NTHREADS) {
;         const int dcol = (e >> 15) * 128 + (e & 127); float st = 0.f;
;         float u0[16], d0[16], u1[16], d1[16];
;     ...
;         SLOAD(u0, d0, 0);
; #pragma unroll 1
;         for (int n0 = 0; n0 < 256; n0 += 32) {
;             SLOAD(u1, d1, n0 + 16);
;             SPROC(u0, d0, n0);
;             if (n0 + 32 < 256) SLOAD(u0, d0, n0 + 32);
;             SPROC(u1, d1, n0 + 16);
;         }
	s_waitcnt lgkmcnt(0)
	v_cvt_pk_bf16_f32 v72, v71, v71
	v_lshlrev_b32_e32 v74, 16, v20
	global_store_short v2, v72, s[98:99]
	s_add_u32 s98, s98, 0x40000
	s_addc_u32 s99, s99, 0
	v_fma_f32 v71, v76, v71, v74
	v_cvt_pk_bf16_f32 v73, v71, v71
	v_lshlrev_b32_e32 v74, 16, v21
	global_store_short v2, v73, s[98:99]
	s_add_u32 s98, s98, 0x40000
	s_addc_u32 s99, s99, 0
	v_fma_f32 v71, v77, v71, v74
	v_cvt_pk_bf16_f32 v72, v71, v71
	v_lshlrev_b32_e32 v74, 16, v22
	global_store_short v2, v72, s[98:99]
	s_add_u32 s98, s98, 0x40000
	s_addc_u32 s99, s99, 0
	v_fma_f32 v71, v78, v71, v74
	v_cvt_pk_bf16_f32 v73, v71, v71
	v_lshlrev_b32_e32 v74, 16, v23
	global_store_short v2, v73, s[98:99]
	s_add_u32 s98, s98, 0x40000
	s_addc_u32 s99, s99, 0
	v_fma_f32 v71, v79, v71, v74
	v_cvt_pk_bf16_f32 v72, v71, v71
	v_lshlrev_b32_e32 v74, 16, v24
	global_store_short v2, v72, s[98:99]
	s_add_u32 s98, s98, 0x40000
	s_addc_u32 s99, s99, 0
	v_fma_f32 v71, v80, v71, v74
	v_cvt_pk_bf16_f32 v73, v71, v71
	v_lshlrev_b32_e32 v74, 16, v25
	global_store_short v2, v73, s[98:99]
	s_add_u32 s98, s98, 0x40000
	s_addc_u32 s99, s99, 0
	v_fma_f32 v71, v81, v71, v74
	v_cvt_pk_bf16_f32 v72, v71, v71
	v_lshlrev_b32_e32 v74, 16, v26
	global_store_short v2, v72, s[98:99]
	s_add_u32 s98, s98, 0x40000
	s_addc_u32 s99, s99, 0
	v_fma_f32 v71, v82, v71, v74
	v_cvt_pk_bf16_f32 v73, v71, v71
	v_lshlrev_b32_e32 v74, 16, v27
	global_store_short v2, v73, s[98:99]
	s_add_u32 s98, s98, 0x40000
	s_addc_u32 s99, s99, 0
	v_fma_f32 v71, v83, v71, v74
	global_load_ushort v20, v2, s[16:17]
	s_add_u32 s16, s16, 0x40000
	s_addc_u32 s17, s17, 0
	global_load_ushort v21, v2, s[16:17]
	s_add_u32 s16, s16, 0x40000
	s_addc_u32 s17, s17, 0
	global_load_ushort v22, v2, s[16:17]
	s_add_u32 s16, s16, 0x40000
	s_addc_u32 s17, s17, 0
	global_load_ushort v23, v2, s[16:17]
	s_add_u32 s16, s16, 0x40000
	s_addc_u32 s17, s17, 0
	global_load_ushort v24, v2, s[16:17]
	s_add_u32 s16, s16, 0x40000
	s_addc_u32 s17, s17, 0
	global_load_ushort v25, v2, s[16:17]
	s_add_u32 s16, s16, 0x40000
	s_addc_u32 s17, s17, 0
	global_load_ushort v26, v2, s[16:17]
	s_add_u32 s16, s16, 0x40000
	s_addc_u32 s17, s17, 0
	global_load_ushort v27, v2, s[16:17]
	s_add_u32 s16, s16, 0x40000
	s_addc_u32 s17, s17, 0
	ds_read_b32 v76, v69 offset:12288
	ds_read_b32 v77, v69 offset:12800
	ds_read_b32 v78, v69 offset:13312
	ds_read_b32 v79, v69 offset:13824
	ds_read_b32 v80, v69 offset:14336
	ds_read_b32 v81, v69 offset:14848
	ds_read_b32 v82, v69 offset:15360
	ds_read_b32 v83, v69 offset:15872
	s_waitcnt vmcnt(56)
	s_waitcnt lgkmcnt(0)
	v_cvt_pk_bf16_f32 v72, v71, v71
	v_lshlrev_b32_e32 v74, 16, v28
	global_store_short v2, v72, s[98:99]
	s_add_u32 s98, s98, 0x40000
	s_addc_u32 s99, s99, 0
	v_fma_f32 v71, v76, v71, v74
	v_cvt_pk_bf16_f32 v73, v71, v71
	v_lshlrev_b32_e32 v74, 16, v29
	global_store_short v2, v73, s[98:99]
	s_add_u32 s98, s98, 0x40000
	s_addc_u32 s99, s99, 0
	v_fma_f32 v71, v77, v71, v74
	v_cvt_pk_bf16_f32 v72, v71, v71
	v_lshlrev_b32_e32 v74, 16, v30
	global_store_short v2, v72, s[98:99]
	s_add_u32 s98, s98, 0x40000
	s_addc_u32 s99, s99, 0
	v_fma_f32 v71, v78, v71, v74
	v_cvt_pk_bf16_f32 v73, v71, v71
	v_lshlrev_b32_e32 v74, 16, v31
	global_store_short v2, v73, s[98:99]
	s_add_u32 s98, s98, 0x40000
	s_addc_u32 s99, s99, 0
	v_fma_f32 v71, v79, v71, v74
	v_cvt_pk_bf16_f32 v72, v71, v71
	v_lshlrev_b32_e32 v74, 16, v32
	global_store_short v2, v72, s[98:99]
	s_add_u32 s98, s98, 0x40000
	s_addc_u32 s99, s99, 0
	v_fma_f32 v71, v80, v71, v74
	v_cvt_pk_bf16_f32 v73, v71, v71
	v_lshlrev_b32_e32 v74, 16, v33
	global_store_short v2, v73, s[98:99]
	s_add_u32 s98, s98, 0x40000
	s_addc_u32 s99, s99, 0
	v_fma_f32 v71, v81, v71, v74
	v_cvt_pk_bf16_f32 v72, v71, v71
	v_lshlrev_b32_e32 v74, 16, v34
	global_store_short v2, v72, s[98:99]
	s_add_u32 s98, s98, 0x40000
	s_addc_u32 s99, s99, 0
	v_fma_f32 v71, v82, v71, v74
	v_cvt_pk_bf16_f32 v73, v71, v71
	v_lshlrev_b32_e32 v74, 16, v35
	global_store_short v2, v73, s[98:99]
	s_add_u32 s98, s98, 0x40000
	s_addc_u32 s99, s99, 0
	v_fma_f32 v71, v83, v71, v74
	global_load_ushort v28, v2, s[16:17]
	s_add_u32 s16, s16, 0x40000
	s_addc_u32 s17, s17, 0
	global_load_ushort v29, v2, s[16:17]
	s_add_u32 s16, s16, 0x40000
	s_addc_u32 s17, s17, 0
	global_load_ushort v30, v2, s[16:17]
	s_add_u32 s16, s16, 0x40000
	s_addc_u32 s17, s17, 0
	global_load_ushort v31, v2, s[16:17]
	s_add_u32 s16, s16, 0x40000
	s_addc_u32 s17, s17, 0
	global_load_ushort v32, v2, s[16:17]
	s_add_u32 s16, s16, 0x40000
	s_addc_u32 s17, s17, 0
	global_load_ushort v33, v2, s[16:17]
	s_add_u32 s16, s16, 0x40000
	s_addc_u32 s17, s17, 0
	global_load_ushort v34, v2, s[16:17]
	s_add_u32 s16, s16, 0x40000
	s_addc_u32 s17, s17, 0
	global_load_ushort v35, v2, s[16:17]
	s_add_u32 s16, s16, 0x40000
	s_addc_u32 s17, s17, 0
	ds_read_b32 v76, v69 offset:16384
	ds_read_b32 v77, v69 offset:16896
	ds_read_b32 v78, v69 offset:17408
	ds_read_b32 v79, v69 offset:17920
	ds_read_b32 v80, v69 offset:18432
	ds_read_b32 v81, v69 offset:18944
	ds_read_b32 v82, v69 offset:19456
	ds_read_b32 v83, v69 offset:19968
	s_waitcnt vmcnt(63)
	s_waitcnt lgkmcnt(0)
; __device__ __forceinline__ int otid() { int t = threadIdx.x; asm volatile("" : "+v"(t)); return t; }
; __device__ __forceinline__ int obid() { int t = blockIdx.x; asm volatile("" : "+s"(t)); return t; }
; __device__ __forceinline__ int ogdim() { int t = gridDim.x; asm volatile("" : "+s"(t)); return t; }
; #define SLOAD(U_, D_, n0_) do { _Pragma("unroll") for (int j = 0; j < 16; ++j) { U_[j] = bf2f(sbuf[(size_t)((n0_) + j) * 131072 + e]); D_[j] = decg[(size_t)((n0_) + j) * 512 + dcol]; } } while (0)
; #define SPROC(U_, D_, n0_) do { _Pragma("unroll") for (int j = 0; j < 16; ++j) { sbuf[(size_t)((n0_) + j) * 131072 + e] = f2bf(st); st = D_[j] * st + U_[j]; } } while (0)
; __device__ __forceinline__ void gla_scan(const Params& p) {
;     ...
;     for (int e = obid() * NTHREADS + otid(); e < 4 * 256 * 128; e += ogdim() * NTHREADS) {
;         const int dcol = (e >> 15) * 128 + (e & 127); float st = 0.f;
;         float u0[16], d0[16], u1[16], d1[16];
;     ...
;         SLOAD(u0, d0, 0);
; #pragma unroll 1
;         for (int n0 = 0; n0 < 256; n0 += 32) {
;             SLOAD(u1, d1, n0 + 16);
;             SPROC(u0, d0, n0);
;             if (n0 + 32 < 256) SLOAD(u0, d0, n0 + 32);
;             SPROC(u1, d1, n0 + 16);
;         }
	v_cvt_pk_bf16_f32 v72, v71, v71
	v_lshlrev_b32_e32 v74, 16, v36
	global_store_short v2, v72, s[98:99]
	s_add_u32 s98, s98, 0x40000
	s_addc_u32 s99, s99, 0
	v_fma_f32 v71, v76, v71, v74
	v_cvt_pk_bf16_f32 v73, v71, v71
	v_lshlrev_b32_e32 v74, 16, v37
	global_store_short v2, v73, s[98:99]
	s_add_u32 s98, s98, 0x40000
	s_addc_u32 s99, s99, 0
	v_fma_f32 v71, v77, v71, v74
	v_cvt_pk_bf16_f32 v72, v71, v71
	v_lshlrev_b32_e32 v74, 16, v38
	global_store_short v2, v72, s[98:99]
	s_add_u32 s98, s98, 0x40000
	s_addc_u32 s99, s99, 0
	v_fma_f32 v71, v78, v71, v74
	v_cvt_pk_bf16_f32 v73, v71, v71
	v_lshlrev_b32_e32 v74, 16, v39
	global_store_short v2, v73, s[98:99]
	s_add_u32 s98, s98, 0x40000
	s_addc_u32 s99, s99, 0
	v_fma_f32 v71, v79, v71, v74
	v_cvt_pk_bf16_f32 v72, v71, v71
	v_lshlrev_b32_e32 v74, 16, v40
	global_store_short v2, v72, s[98:99]
	s_add_u32 s98, s98, 0x40000
	s_addc_u32 s99, s99, 0
	v_fma_f32 v71, v80, v71, v74
	v_cvt_pk_bf16_f32 v73, v71, v71
	v_lshlrev_b32_e32 v74, 16, v41
	global_store_short v2, v73, s[98:99]
	s_add_u32 s98, s98, 0x40000
	s_addc_u32 s99, s99, 0
	v_fma_f32 v71, v81, v71, v74
	v_cvt_pk_bf16_f32 v72, v71, v71
	v_lshlrev_b32_e32 v74, 16, v42
	global_store_short v2, v72, s[98:99]
	s_add_u32 s98, s98, 0x40000
	s_addc_u32 s99, s99, 0
	v_fma_f32 v71, v82, v71, v74
	v_cvt_pk_bf16_f32 v73, v71, v71
	v_lshlrev_b32_e32 v74, 16, v43
	global_store_short v2, v73, s[98:99]
	s_add_u32 s98, s98, 0x40000
	s_addc_u32 s99, s99, 0
	v_fma_f32 v71, v83, v71, v74
	global_load_ushort v36, v2, s[16:17]
	s_add_u32 s16, s16, 0x40000
	s_addc_u32 s17, s17, 0
	global_load_ushort v37, v2, s[16:17]
	s_add_u32 s16, s16, 0x40000
	s_addc_u32 s17, s17, 0
	global_load_ushort v38, v2, s[16:17]
	s_add_u32 s16, s16, 0x40000
	s_addc_u32 s17, s17, 0
	global_load_ushort v39, v2, s[16:17]
	s_add_u32 s16, s16, 0x40000
	s_addc_u32 s17, s17, 0
	global_load_ushort v40, v2, s[16:17]
	s_add_u32 s16, s16, 0x40000
	s_addc_u32 s17, s17, 0
	global_load_ushort v41, v2, s[16:17]
	s_add_u32 s16, s16, 0x40000
	s_addc_u32 s17, s17, 0
	global_load_ushort v42, v2, s[16:17]
	s_add_u32 s16, s16, 0x40000
	s_addc_u32 s17, s17, 0
	global_load_ushort v43, v2, s[16:17]
	s_add_u32 s16, s16, 0x40000
	s_addc_u32 s17, s17, 0
	ds_read_b32 v76, v69 offset:20480
	ds_read_b32 v77, v69 offset:20992
	ds_read_b32 v78, v69 offset:21504
	ds_read_b32 v79, v69 offset:22016
	ds_read_b32 v80, v69 offset:22528
	ds_read_b32 v81, v69 offset:23040
	ds_read_b32 v82, v69 offset:23552
	ds_read_b32 v83, v69 offset:24064
	s_waitcnt vmcnt(63)
	s_waitcnt lgkmcnt(0)
	v_cvt_pk_bf16_f32 v72, v71, v71
	v_lshlrev_b32_e32 v74, 16, v4
	global_store_short v2, v72, s[98:99]
	s_add_u32 s98, s98, 0x40000
	s_addc_u32 s99, s99, 0
	v_fma_f32 v71, v76, v71, v74
	v_cvt_pk_bf16_f32 v73, v71, v71
	v_lshlrev_b32_e32 v74, 16, v5
	global_store_short v2, v73, s[98:99]
	s_add_u32 s98, s98, 0x40000
	s_addc_u32 s99, s99, 0
	v_fma_f32 v71, v77, v71, v74
	v_cvt_pk_bf16_f32 v72, v71, v71
	v_lshlrev_b32_e32 v74, 16, v6
	global_store_short v2, v72, s[98:99]
	s_add_u32 s98, s98, 0x40000
	s_addc_u32 s99, s99, 0
	v_fma_f32 v71, v78, v71, v74
	v_cvt_pk_bf16_f32 v73, v71, v71
	v_lshlrev_b32_e32 v74, 16, v7
	global_store_short v2, v73, s[98:99]
	s_add_u32 s98, s98, 0x40000
	s_addc_u32 s99, s99, 0
	v_fma_f32 v71, v79, v71, v74
	v_cvt_pk_bf16_f32 v72, v71, v71
	v_lshlrev_b32_e32 v74, 16, v8
	global_store_short v2, v72, s[98:99]
	s_add_u32 s98, s98, 0x40000
	s_addc_u32 s99, s99, 0
	v_fma_f32 v71, v80, v71, v74
	v_cvt_pk_bf16_f32 v73, v71, v71
	v_lshlrev_b32_e32 v74, 16, v9
	global_store_short v2, v73, s[98:99]
	s_add_u32 s98, s98, 0x40000
	s_addc_u32 s99, s99, 0
	v_fma_f32 v71, v81, v71, v74
	v_cvt_pk_bf16_f32 v72, v71, v71
	v_lshlrev_b32_e32 v74, 16, v10
	global_store_short v2, v72, s[98:99]
	s_add_u32 s98, s98, 0x40000
	s_addc_u32 s99, s99, 0
	v_fma_f32 v71, v82, v71, v74
	v_cvt_pk_bf16_f32 v73, v71, v71
	v_lshlrev_b32_e32 v74, 16, v11
	global_store_short v2, v73, s[98:99]
	s_add_u32 s98, s98, 0x40000
	s_addc_u32 s99, s99, 0
	v_fma_f32 v71, v83, v71, v74
	global_load_ushort v4, v2, s[16:17]
	s_add_u32 s16, s16, 0x40000
	s_addc_u32 s17, s17, 0
	global_load_ushort v5, v2, s[16:17]
	s_add_u32 s16, s16, 0x40000
	s_addc_u32 s17, s17, 0
	global_load_ushort v6, v2, s[16:17]
	s_add_u32 s16, s16, 0x40000
	s_addc_u32 s17, s17, 0
	global_load_ushort v7, v2, s[16:17]
	s_add_u32 s16, s16, 0x40000
	s_addc_u32 s17, s17, 0
	global_load_ushort v8, v2, s[16:17]
	s_add_u32 s16, s16, 0x40000
	s_addc_u32 s17, s17, 0
	global_load_ushort v9, v2, s[16:17]
	s_add_u32 s16, s16, 0x40000
	s_addc_u32 s17, s17, 0
	global_load_ushort v10, v2, s[16:17]
	s_add_u32 s16, s16, 0x40000
	s_addc_u32 s17, s17, 0
	global_load_ushort v11, v2, s[16:17]
	s_add_u32 s16, s16, 0x40000
	s_addc_u32 s17, s17, 0
	ds_read_b32 v76, v69 offset:24576
	ds_read_b32 v77, v69 offset:25088
	ds_read_b32 v78, v69 offset:25600
	ds_read_b32 v79, v69 offset:26112
	ds_read_b32 v80, v69 offset:26624
	ds_read_b32 v81, v69 offset:27136
	ds_read_b32 v82, v69 offset:27648
	ds_read_b32 v83, v69 offset:28160
	s_waitcnt vmcnt(63)
	s_waitcnt lgkmcnt(0)
; __device__ __forceinline__ int otid() { int t = threadIdx.x; asm volatile("" : "+v"(t)); return t; }
; __device__ __forceinline__ int obid() { int t = blockIdx.x; asm volatile("" : "+s"(t)); return t; }
; __device__ __forceinline__ int ogdim() { int t = gridDim.x; asm volatile("" : "+s"(t)); return t; }
; #define SLOAD(U_, D_, n0_) do { _Pragma("unroll") for (int j = 0; j < 16; ++j) { U_[j] = bf2f(sbuf[(size_t)((n0_) + j) * 131072 + e]); D_[j] = decg[(size_t)((n0_) + j) * 512 + dcol]; } } while (0)
; #define SPROC(U_, D_, n0_) do { _Pragma("unroll") for (int j = 0; j < 16; ++j) { sbuf[(size_t)((n0_) + j) * 131072 + e] = f2bf(st); st = D_[j] * st + U_[j]; } } while (0)
; __device__ __forceinline__ void gla_scan(const Params& p) {
;     ...
;     for (int e = obid() * NTHREADS + otid(); e < 4 * 256 * 128; e += ogdim() * NTHREADS) {
;         const int dcol = (e >> 15) * 128 + (e & 127); float st = 0.f;
;         float u0[16], d0[16], u1[16], d1[16];
;     ...
;         SLOAD(u0, d0, 0);
; #pragma unroll 1
;         for (int n0 = 0; n0 < 256; n0 += 32) {
;             SLOAD(u1, d1, n0 + 16);
;             SPROC(u0, d0, n0);
;             if (n0 + 32 < 256) SLOAD(u0, d0, n0 + 32);
;             SPROC(u1, d1, n0 + 16);
;         }
	v_cvt_pk_bf16_f32 v72, v71, v71
	v_lshlrev_b32_e32 v74, 16, v12
	global_store_short v2, v72, s[98:99]
	s_add_u32 s98, s98, 0x40000
	s_addc_u32 s99, s99, 0
	v_fma_f32 v71, v76, v71, v74
	v_cvt_pk_bf16_f32 v73, v71, v71
	v_lshlrev_b32_e32 v74, 16, v13
	global_store_short v2, v73, s[98:99]
	s_add_u32 s98, s98, 0x40000
	s_addc_u32 s99, s99, 0
	v_fma_f32 v71, v77, v71, v74
	v_cvt_pk_bf16_f32 v72, v71, v71
	v_lshlrev_b32_e32 v74, 16, v14
	global_store_short v2, v72, s[98:99]
	s_add_u32 s98, s98, 0x40000
	s_addc_u32 s99, s99, 0
	v_fma_f32 v71, v78, v71, v74
	v_cvt_pk_bf16_f32 v73, v71, v71
	v_lshlrev_b32_e32 v74, 16, v15
	global_store_short v2, v73, s[98:99]
	s_add_u32 s98, s98, 0x40000
	s_addc_u32 s99, s99, 0
	v_fma_f32 v71, v79, v71, v74
	v_cvt_pk_bf16_f32 v72, v71, v71
	v_lshlrev_b32_e32 v74, 16, v16
	global_store_short v2, v72, s[98:99]
	s_add_u32 s98, s98, 0x40000
	s_addc_u32 s99, s99, 0
	v_fma_f32 v71, v80, v71, v74
	v_cvt_pk_bf16_f32 v73, v71, v71
	v_lshlrev_b32_e32 v74, 16, v17
	global_store_short v2, v73, s[98:99]
	s_add_u32 s98, s98, 0x40000
	s_addc_u32 s99, s99, 0
	v_fma_f32 v71, v81, v71, v74
	v_cvt_pk_bf16_f32 v72, v71, v71
	v_lshlrev_b32_e32 v74, 16, v18
	global_store_short v2, v72, s[98:99]
	s_add_u32 s98, s98, 0x40000
	s_addc_u32 s99, s99, 0
	v_fma_f32 v71, v82, v71, v74
	v_cvt_pk_bf16_f32 v73, v71, v71
	v_lshlrev_b32_e32 v74, 16, v19
	global_store_short v2, v73, s[98:99]
	s_add_u32 s98, s98, 0x40000
	s_addc_u32 s99, s99, 0
	v_fma_f32 v71, v83, v71, v74
	global_load_ushort v12, v2, s[16:17]
	s_add_u32 s16, s16, 0x40000
	s_addc_u32 s17, s17, 0
	global_load_ushort v13, v2, s[16:17]
	s_add_u32 s16, s16, 0x40000
	s_addc_u32 s17, s17, 0
	global_load_ushort v14, v2, s[16:17]
	s_add_u32 s16, s16, 0x40000
	s_addc_u32 s17, s17, 0
	global_load_ushort v15, v2, s[16:17]
	s_add_u32 s16, s16, 0x40000
	s_addc_u32 s17, s17, 0
	global_load_ushort v16, v2, s[16:17]
	s_add_u32 s16, s16, 0x40000
	s_addc_u32 s17, s17, 0
	global_load_ushort v17, v2, s[16:17]
	s_add_u32 s16, s16, 0x40000
	s_addc_u32 s17, s17, 0
	global_load_ushort v18, v2, s[16:17]
	s_add_u32 s16, s16, 0x40000
	s_addc_u32 s17, s17, 0
	global_load_ushort v19, v2, s[16:17]
	s_add_u32 s16, s16, 0x40000
	s_addc_u32 s17, s17, 0
	ds_read_b32 v76, v69 offset:28672
	ds_read_b32 v77, v69 offset:29184
	ds_read_b32 v78, v69 offset:29696
	ds_read_b32 v79, v69 offset:30208
	ds_read_b32 v80, v69 offset:30720
	ds_read_b32 v81, v69 offset:31232
	ds_read_b32 v82, v69 offset:31744
	ds_read_b32 v83, v69 offset:32256
	s_waitcnt vmcnt(63)
	s_waitcnt lgkmcnt(0)
	v_cvt_pk_bf16_f32 v72, v71, v71
	v_lshlrev_b32_e32 v74, 16, v20
	global_store_short v2, v72, s[98:99]
	s_add_u32 s98, s98, 0x40000
	s_addc_u32 s99, s99, 0
	v_fma_f32 v71, v76, v71, v74
	v_cvt_pk_bf16_f32 v73, v71, v71
	v_lshlrev_b32_e32 v74, 16, v21
	global_store_short v2, v73, s[98:99]
	s_add_u32 s98, s98, 0x40000
	s_addc_u32 s99, s99, 0
	v_fma_f32 v71, v77, v71, v74
	v_cvt_pk_bf16_f32 v72, v71, v71
	v_lshlrev_b32_e32 v74, 16, v22
	global_store_short v2, v72, s[98:99]
	s_add_u32 s98, s98, 0x40000
	s_addc_u32 s99, s99, 0
	v_fma_f32 v71, v78, v71, v74
	v_cvt_pk_bf16_f32 v73, v71, v71
	v_lshlrev_b32_e32 v74, 16, v23
	global_store_short v2, v73, s[98:99]
	s_add_u32 s98, s98, 0x40000
	s_addc_u32 s99, s99, 0
	v_fma_f32 v71, v79, v71, v74
	v_cvt_pk_bf16_f32 v72, v71, v71
	v_lshlrev_b32_e32 v74, 16, v24
	global_store_short v2, v72, s[98:99]
	s_add_u32 s98, s98, 0x40000
	s_addc_u32 s99, s99, 0
	v_fma_f32 v71, v80, v71, v74
	v_cvt_pk_bf16_f32 v73, v71, v71
	v_lshlrev_b32_e32 v74, 16, v25
	global_store_short v2, v73, s[98:99]
	s_add_u32 s98, s98, 0x40000
	s_addc_u32 s99, s99, 0
	v_fma_f32 v71, v81, v71, v74
	v_cvt_pk_bf16_f32 v72, v71, v71
	v_lshlrev_b32_e32 v74, 16, v26
	global_store_short v2, v72, s[98:99]
	s_add_u32 s98, s98, 0x40000
	s_addc_u32 s99, s99, 0
	v_fma_f32 v71, v82, v71, v74
	v_cvt_pk_bf16_f32 v73, v71, v71
	v_lshlrev_b32_e32 v74, 16, v27
	global_store_short v2, v73, s[98:99]
	s_add_u32 s98, s98, 0x40000
	s_addc_u32 s99, s99, 0
	v_fma_f32 v71, v83, v71, v74
	global_load_ushort v20, v2, s[16:17]
	s_add_u32 s16, s16, 0x40000
	s_addc_u32 s17, s17, 0
	global_load_ushort v21, v2, s[16:17]
	s_add_u32 s16, s16, 0x40000
	s_addc_u32 s17, s17, 0
	global_load_ushort v22, v2, s[16:17]
	s_add_u32 s16, s16, 0x40000
	s_addc_u32 s17, s17, 0
	global_load_ushort v23, v2, s[16:17]
	s_add_u32 s16, s16, 0x40000
	s_addc_u32 s17, s17, 0
	global_load_ushort v24, v2, s[16:17]
	s_add_u32 s16, s16, 0x40000
	s_addc_u32 s17, s17, 0
	global_load_ushort v25, v2, s[16:17]
	s_add_u32 s16, s16, 0x40000
	s_addc_u32 s17, s17, 0
	global_load_ushort v26, v2, s[16:17]
	s_add_u32 s16, s16, 0x40000
	s_addc_u32 s17, s17, 0
	global_load_ushort v27, v2, s[16:17]
	s_add_u32 s16, s16, 0x40000
	s_addc_u32 s17, s17, 0
	ds_read_b32 v76, v69 offset:32768
	ds_read_b32 v77, v69 offset:33280
	ds_read_b32 v78, v69 offset:33792
	ds_read_b32 v79, v69 offset:34304
	ds_read_b32 v80, v69 offset:34816
	ds_read_b32 v81, v69 offset:35328
	ds_read_b32 v82, v69 offset:35840
	ds_read_b32 v83, v69 offset:36352
	s_waitcnt vmcnt(63)
	s_waitcnt lgkmcnt(0)
; __device__ __forceinline__ int otid() { int t = threadIdx.x; asm volatile("" : "+v"(t)); return t; }
; __device__ __forceinline__ int obid() { int t = blockIdx.x; asm volatile("" : "+s"(t)); return t; }
; __device__ __forceinline__ int ogdim() { int t = gridDim.x; asm volatile("" : "+s"(t)); return t; }
; #define SLOAD(U_, D_, n0_) do { _Pragma("unroll") for (int j = 0; j < 16; ++j) { U_[j] = bf2f(sbuf[(size_t)((n0_) + j) * 131072 + e]); D_[j] = decg[(size_t)((n0_) + j) * 512 + dcol]; } } while (0)
; #define SPROC(U_, D_, n0_) do { _Pragma("unroll") for (int j = 0; j < 16; ++j) { sbuf[(size_t)((n0_) + j) * 131072 + e] = f2bf(st); st = D_[j] * st + U_[j]; } } while (0)
; __device__ __forceinline__ void gla_scan(const Params& p) {
;     ...
;     for (int e = obid() * NTHREADS + otid(); e < 4 * 256 * 128; e += ogdim() * NTHREADS) {
;         const int dcol = (e >> 15) * 128 + (e & 127); float st = 0.f;
;         float u0[16], d0[16], u1[16], d1[16];
;     ...
;         SLOAD(u0, d0, 0);
; #pragma unroll 1
;         for (int n0 = 0; n0 < 256; n0 += 32) {
;             SLOAD(u1, d1, n0 + 16);
;             SPROC(u0, d0, n0);
;             if (n0 + 32 < 256) SLOAD(u0, d0, n0 + 32);
;             SPROC(u1, d1, n0 + 16);
;         }
	v_cvt_pk_bf16_f32 v72, v71, v71
	v_lshlrev_b32_e32 v74, 16, v28
	global_store_short v2, v72, s[98:99]
	s_add_u32 s98, s98, 0x40000
	s_addc_u32 s99, s99, 0
	v_fma_f32 v71, v76, v71, v74
	v_cvt_pk_bf16_f32 v73, v71, v71
	v_lshlrev_b32_e32 v74, 16, v29
	global_store_short v2, v73, s[98:99]
	s_add_u32 s98, s98, 0x40000
	s_addc_u32 s99, s99, 0
	v_fma_f32 v71, v77, v71, v74
	v_cvt_pk_bf16_f32 v72, v71, v71
	v_lshlrev_b32_e32 v74, 16, v30
	global_store_short v2, v72, s[98:99]
	s_add_u32 s98, s98, 0x40000
	s_addc_u32 s99, s99, 0
	v_fma_f32 v71, v78, v71, v74
	v_cvt_pk_bf16_f32 v73, v71, v71
	v_lshlrev_b32_e32 v74, 16, v31
	global_store_short v2, v73, s[98:99]
	s_add_u32 s98, s98, 0x40000
	s_addc_u32 s99, s99, 0
	v_fma_f32 v71, v79, v71, v74
	v_cvt_pk_bf16_f32 v72, v71, v71
	v_lshlrev_b32_e32 v74, 16, v32
	global_store_short v2, v72, s[98:99]
	s_add_u32 s98, s98, 0x40000
	s_addc_u32 s99, s99, 0
	v_fma_f32 v71, v80, v71, v74
	v_cvt_pk_bf16_f32 v73, v71, v71
	v_lshlrev_b32_e32 v74, 16, v33
	global_store_short v2, v73, s[98:99]
	s_add_u32 s98, s98, 0x40000
	s_addc_u32 s99, s99, 0
	v_fma_f32 v71, v81, v71, v74
	v_cvt_pk_bf16_f32 v72, v71, v71
	v_lshlrev_b32_e32 v74, 16, v34
	global_store_short v2, v72, s[98:99]
	s_add_u32 s98, s98, 0x40000
	s_addc_u32 s99, s99, 0
	v_fma_f32 v71, v82, v71, v74
	v_cvt_pk_bf16_f32 v73, v71, v71
	v_lshlrev_b32_e32 v74, 16, v35
	global_store_short v2, v73, s[98:99]
	s_add_u32 s98, s98, 0x40000
	s_addc_u32 s99, s99, 0
	v_fma_f32 v71, v83, v71, v74
	global_load_ushort v28, v2, s[16:17]
	s_add_u32 s16, s16, 0x40000
	s_addc_u32 s17, s17, 0
	global_load_ushort v29, v2, s[16:17]
	s_add_u32 s16, s16, 0x40000
	s_addc_u32 s17, s17, 0
	global_load_ushort v30, v2, s[16:17]
	s_add_u32 s16, s16, 0x40000
	s_addc_u32 s17, s17, 0
	global_load_ushort v31, v2, s[16:17]
	s_add_u32 s16, s16, 0x40000
	s_addc_u32 s17, s17, 0
	global_load_ushort v32, v2, s[16:17]
	s_add_u32 s16, s16, 0x40000
	s_addc_u32 s17, s17, 0
	global_load_ushort v33, v2, s[16:17]
	s_add_u32 s16, s16, 0x40000
	s_addc_u32 s17, s17, 0
	global_load_ushort v34, v2, s[16:17]
	s_add_u32 s16, s16, 0x40000
	s_addc_u32 s17, s17, 0
	global_load_ushort v35, v2, s[16:17]
	s_add_u32 s16, s16, 0x40000
	s_addc_u32 s17, s17, 0
	ds_read_b32 v76, v69 offset:36864
	ds_read_b32 v77, v69 offset:37376
	ds_read_b32 v78, v69 offset:37888
	ds_read_b32 v79, v69 offset:38400
	ds_read_b32 v80, v69 offset:38912
	ds_read_b32 v81, v69 offset:39424
	ds_read_b32 v82, v69 offset:39936
	ds_read_b32 v83, v69 offset:40448
	s_waitcnt vmcnt(63)
	s_waitcnt lgkmcnt(0)
	v_cvt_pk_bf16_f32 v72, v71, v71
	v_lshlrev_b32_e32 v74, 16, v36
	global_store_short v2, v72, s[98:99]
	s_add_u32 s98, s98, 0x40000
	s_addc_u32 s99, s99, 0
	v_fma_f32 v71, v76, v71, v74
	v_cvt_pk_bf16_f32 v73, v71, v71
	v_lshlrev_b32_e32 v74, 16, v37
	global_store_short v2, v73, s[98:99]
	s_add_u32 s98, s98, 0x40000
	s_addc_u32 s99, s99, 0
	v_fma_f32 v71, v77, v71, v74
	v_cvt_pk_bf16_f32 v72, v71, v71
	v_lshlrev_b32_e32 v74, 16, v38
	global_store_short v2, v72, s[98:99]
	s_add_u32 s98, s98, 0x40000
	s_addc_u32 s99, s99, 0
	v_fma_f32 v71, v78, v71, v74
	v_cvt_pk_bf16_f32 v73, v71, v71
	v_lshlrev_b32_e32 v74, 16, v39
	global_store_short v2, v73, s[98:99]
	s_add_u32 s98, s98, 0x40000
	s_addc_u32 s99, s99, 0
	v_fma_f32 v71, v79, v71, v74
	v_cvt_pk_bf16_f32 v72, v71, v71
	v_lshlrev_b32_e32 v74, 16, v40
	global_store_short v2, v72, s[98:99]
	s_add_u32 s98, s98, 0x40000
	s_addc_u32 s99, s99, 0
	v_fma_f32 v71, v80, v71, v74
	v_cvt_pk_bf16_f32 v73, v71, v71
	v_lshlrev_b32_e32 v74, 16, v41
	global_store_short v2, v73, s[98:99]
	s_add_u32 s98, s98, 0x40000
	s_addc_u32 s99, s99, 0
	v_fma_f32 v71, v81, v71, v74
	v_cvt_pk_bf16_f32 v72, v71, v71
	v_lshlrev_b32_e32 v74, 16, v42
	global_store_short v2, v72, s[98:99]
	s_add_u32 s98, s98, 0x40000
	s_addc_u32 s99, s99, 0
	v_fma_f32 v71, v82, v71, v74
	v_cvt_pk_bf16_f32 v73, v71, v71
	v_lshlrev_b32_e32 v74, 16, v43
	global_store_short v2, v73, s[98:99]
	s_add_u32 s98, s98, 0x40000
	s_addc_u32 s99, s99, 0
	v_fma_f32 v71, v83, v71, v74
	global_load_ushort v36, v2, s[16:17]
	s_add_u32 s16, s16, 0x40000
	s_addc_u32 s17, s17, 0
	global_load_ushort v37, v2, s[16:17]
	s_add_u32 s16, s16, 0x40000
	s_addc_u32 s17, s17, 0
	global_load_ushort v38, v2, s[16:17]
	s_add_u32 s16, s16, 0x40000
	s_addc_u32 s17, s17, 0
	global_load_ushort v39, v2, s[16:17]
	s_add_u32 s16, s16, 0x40000
	s_addc_u32 s17, s17, 0
	global_load_ushort v40, v2, s[16:17]
	s_add_u32 s16, s16, 0x40000
	s_addc_u32 s17, s17, 0
	global_load_ushort v41, v2, s[16:17]
	s_add_u32 s16, s16, 0x40000
	s_addc_u32 s17, s17, 0
	global_load_ushort v42, v2, s[16:17]
	s_add_u32 s16, s16, 0x40000
	s_addc_u32 s17, s17, 0
	global_load_ushort v43, v2, s[16:17]
	s_add_u32 s16, s16, 0x40000
	s_addc_u32 s17, s17, 0
	ds_read_b32 v76, v69 offset:40960
	ds_read_b32 v77, v69 offset:41472
	ds_read_b32 v78, v69 offset:41984
	ds_read_b32 v79, v69 offset:42496
	ds_read_b32 v80, v69 offset:43008
	ds_read_b32 v81, v69 offset:43520
	ds_read_b32 v82, v69 offset:44032
	ds_read_b32 v83, v69 offset:44544
	s_waitcnt vmcnt(63)
	s_waitcnt lgkmcnt(0)
; __device__ __forceinline__ int otid() { int t = threadIdx.x; asm volatile("" : "+v"(t)); return t; }
; __device__ __forceinline__ int obid() { int t = blockIdx.x; asm volatile("" : "+s"(t)); return t; }
; __device__ __forceinline__ int ogdim() { int t = gridDim.x; asm volatile("" : "+s"(t)); return t; }
; #define SLOAD(U_, D_, n0_) do { _Pragma("unroll") for (int j = 0; j < 16; ++j) { U_[j] = bf2f(sbuf[(size_t)((n0_) + j) * 131072 + e]); D_[j] = decg[(size_t)((n0_) + j) * 512 + dcol]; } } while (0)
; #define SPROC(U_, D_, n0_) do { _Pragma("unroll") for (int j = 0; j < 16; ++j) { sbuf[(size_t)((n0_) + j) * 131072 + e] = f2bf(st); st = D_[j] * st + U_[j]; } } while (0)
; __device__ __forceinline__ void gla_scan(const Params& p) {
;     ...
;     for (int e = obid() * NTHREADS + otid(); e < 4 * 256 * 128; e += ogdim() * NTHREADS) {
;         const int dcol = (e >> 15) * 128 + (e & 127); float st = 0.f;
;         float u0[16], d0[16], u1[16], d1[16];
;     ...
;         SLOAD(u0, d0, 0);
; #pragma unroll 1
;         for (int n0 = 0; n0 < 256; n0 += 32) {
;             SLOAD(u1, d1, n0 + 16);
;             SPROC(u0, d0, n0);
;             if (n0 + 32 < 256) SLOAD(u0, d0, n0 + 32);
;             SPROC(u1, d1, n0 + 16);
;         }
	v_cvt_pk_bf16_f32 v72, v71, v71
	v_lshlrev_b32_e32 v74, 16, v4
	global_store_short v2, v72, s[98:99]
	s_add_u32 s98, s98, 0x40000
	s_addc_u32 s99, s99, 0
	v_fma_f32 v71, v76, v71, v74
	v_cvt_pk_bf16_f32 v73, v71, v71
	v_lshlrev_b32_e32 v74, 16, v5
	global_store_short v2, v73, s[98:99]
	s_add_u32 s98, s98, 0x40000
	s_addc_u32 s99, s99, 0
	v_fma_f32 v71, v77, v71, v74
	v_cvt_pk_bf16_f32 v72, v71, v71
	v_lshlrev_b32_e32 v74, 16, v6
	global_store_short v2, v72, s[98:99]
	s_add_u32 s98, s98, 0x40000
	s_addc_u32 s99, s99, 0
	v_fma_f32 v71, v78, v71, v74
	v_cvt_pk_bf16_f32 v73, v71, v71
	v_lshlrev_b32_e32 v74, 16, v7
	global_store_short v2, v73, s[98:99]
	s_add_u32 s98, s98, 0x40000
	s_addc_u32 s99, s99, 0
	v_fma_f32 v71, v79, v71, v74
	v_cvt_pk_bf16_f32 v72, v71, v71
	v_lshlrev_b32_e32 v74, 16, v8
	global_store_short v2, v72, s[98:99]
	s_add_u32 s98, s98, 0x40000
	s_addc_u32 s99, s99, 0
	v_fma_f32 v71, v80, v71, v74
	v_cvt_pk_bf16_f32 v73, v71, v71
	v_lshlrev_b32_e32 v74, 16, v9
	global_store_short v2, v73, s[98:99]
	s_add_u32 s98, s98, 0x40000
	s_addc_u32 s99, s99, 0
	v_fma_f32 v71, v81, v71, v74
	v_cvt_pk_bf16_f32 v72, v71, v71
	v_lshlrev_b32_e32 v74, 16, v10
	global_store_short v2, v72, s[98:99]
	s_add_u32 s98, s98, 0x40000
	s_addc_u32 s99, s99, 0
	v_fma_f32 v71, v82, v71, v74
	v_cvt_pk_bf16_f32 v73, v71, v71
	v_lshlrev_b32_e32 v74, 16, v11
	global_store_short v2, v73, s[98:99]
	s_add_u32 s98, s98, 0x40000
	s_addc_u32 s99, s99, 0
	v_fma_f32 v71, v83, v71, v74
	global_load_ushort v4, v2, s[16:17]
	s_add_u32 s16, s16, 0x40000
	s_addc_u32 s17, s17, 0
	global_load_ushort v5, v2, s[16:17]
	s_add_u32 s16, s16, 0x40000
	s_addc_u32 s17, s17, 0
	global_load_ushort v6, v2, s[16:17]
	s_add_u32 s16, s16, 0x40000
	s_addc_u32 s17, s17, 0
	global_load_ushort v7, v2, s[16:17]
	s_add_u32 s16, s16, 0x40000
	s_addc_u32 s17, s17, 0
	global_load_ushort v8, v2, s[16:17]
	s_add_u32 s16, s16, 0x40000
	s_addc_u32 s17, s17, 0
	global_load_ushort v9, v2, s[16:17]
	s_add_u32 s16, s16, 0x40000
	s_addc_u32 s17, s17, 0
	global_load_ushort v10, v2, s[16:17]
	s_add_u32 s16, s16, 0x40000
	s_addc_u32 s17, s17, 0
	global_load_ushort v11, v2, s[16:17]
	s_add_u32 s16, s16, 0x40000
	s_addc_u32 s17, s17, 0
	ds_read_b32 v76, v69 offset:45056
	ds_read_b32 v77, v69 offset:45568
	ds_read_b32 v78, v69 offset:46080
	ds_read_b32 v79, v69 offset:46592
	ds_read_b32 v80, v69 offset:47104
	ds_read_b32 v81, v69 offset:47616
	ds_read_b32 v82, v69 offset:48128
	ds_read_b32 v83, v69 offset:48640
	s_waitcnt vmcnt(63)
	s_waitcnt lgkmcnt(0)
	v_cvt_pk_bf16_f32 v72, v71, v71
	v_lshlrev_b32_e32 v74, 16, v12
	global_store_short v2, v72, s[98:99]
	s_add_u32 s98, s98, 0x40000
	s_addc_u32 s99, s99, 0
	v_fma_f32 v71, v76, v71, v74
	v_cvt_pk_bf16_f32 v73, v71, v71
	v_lshlrev_b32_e32 v74, 16, v13
	global_store_short v2, v73, s[98:99]
	s_add_u32 s98, s98, 0x40000
	s_addc_u32 s99, s99, 0
	v_fma_f32 v71, v77, v71, v74
	v_cvt_pk_bf16_f32 v72, v71, v71
	v_lshlrev_b32_e32 v74, 16, v14
	global_store_short v2, v72, s[98:99]
	s_add_u32 s98, s98, 0x40000
	s_addc_u32 s99, s99, 0
	v_fma_f32 v71, v78, v71, v74
	v_cvt_pk_bf16_f32 v73, v71, v71
	v_lshlrev_b32_e32 v74, 16, v15
	global_store_short v2, v73, s[98:99]
	s_add_u32 s98, s98, 0x40000
	s_addc_u32 s99, s99, 0
	v_fma_f32 v71, v79, v71, v74
	v_cvt_pk_bf16_f32 v72, v71, v71
	v_lshlrev_b32_e32 v74, 16, v16
	global_store_short v2, v72, s[98:99]
	s_add_u32 s98, s98, 0x40000
	s_addc_u32 s99, s99, 0
	v_fma_f32 v71, v80, v71, v74
	v_cvt_pk_bf16_f32 v73, v71, v71
	v_lshlrev_b32_e32 v74, 16, v17
	global_store_short v2, v73, s[98:99]
	s_add_u32 s98, s98, 0x40000
	s_addc_u32 s99, s99, 0
	v_fma_f32 v71, v81, v71, v74
	v_cvt_pk_bf16_f32 v72, v71, v71
	v_lshlrev_b32_e32 v74, 16, v18
	global_store_short v2, v72, s[98:99]
	s_add_u32 s98, s98, 0x40000
	s_addc_u32 s99, s99, 0
	v_fma_f32 v71, v82, v71, v74
	v_cvt_pk_bf16_f32 v73, v71, v71
	v_lshlrev_b32_e32 v74, 16, v19
	global_store_short v2, v73, s[98:99]
	s_add_u32 s98, s98, 0x40000
	s_addc_u32 s99, s99, 0
	v_fma_f32 v71, v83, v71, v74
	global_load_ushort v12, v2, s[16:17]
	s_add_u32 s16, s16, 0x40000
	s_addc_u32 s17, s17, 0
	global_load_ushort v13, v2, s[16:17]
	s_add_u32 s16, s16, 0x40000
	s_addc_u32 s17, s17, 0
	global_load_ushort v14, v2, s[16:17]
	s_add_u32 s16, s16, 0x40000
	s_addc_u32 s17, s17, 0
	global_load_ushort v15, v2, s[16:17]
	s_add_u32 s16, s16, 0x40000
	s_addc_u32 s17, s17, 0
	global_load_ushort v16, v2, s[16:17]
	s_add_u32 s16, s16, 0x40000
	s_addc_u32 s17, s17, 0
	global_load_ushort v17, v2, s[16:17]
	s_add_u32 s16, s16, 0x40000
	s_addc_u32 s17, s17, 0
	global_load_ushort v18, v2, s[16:17]
	s_add_u32 s16, s16, 0x40000
	s_addc_u32 s17, s17, 0
	global_load_ushort v19, v2, s[16:17]
	s_add_u32 s16, s16, 0x40000
	s_addc_u32 s17, s17, 0
	ds_read_b32 v76, v69 offset:49152
	ds_read_b32 v77, v69 offset:49664
	ds_read_b32 v78, v69 offset:50176
	ds_read_b32 v79, v69 offset:50688
	ds_read_b32 v80, v69 offset:51200
	ds_read_b32 v81, v69 offset:51712
	ds_read_b32 v82, v69 offset:52224
	ds_read_b32 v83, v69 offset:52736
	s_waitcnt vmcnt(63)
	s_waitcnt lgkmcnt(0)
; __device__ __forceinline__ int otid() { int t = threadIdx.x; asm volatile("" : "+v"(t)); return t; }
; __device__ __forceinline__ int obid() { int t = blockIdx.x; asm volatile("" : "+s"(t)); return t; }
; __device__ __forceinline__ int ogdim() { int t = gridDim.x; asm volatile("" : "+s"(t)); return t; }
; #define SLOAD(U_, D_, n0_) do { _Pragma("unroll") for (int j = 0; j < 16; ++j) { U_[j] = bf2f(sbuf[(size_t)((n0_) + j) * 131072 + e]); D_[j] = decg[(size_t)((n0_) + j) * 512 + dcol]; } } while (0)
; #define SPROC(U_, D_, n0_) do { _Pragma("unroll") for (int j = 0; j < 16; ++j) { sbuf[(size_t)((n0_) + j) * 131072 + e] = f2bf(st); st = D_[j] * st + U_[j]; } } while (0)
; __device__ __forceinline__ void gla_scan(const Params& p) {
;     ...
;     for (int e = obid() * NTHREADS + otid(); e < 4 * 256 * 128; e += ogdim() * NTHREADS) {
;         const int dcol = (e >> 15) * 128 + (e & 127); float st = 0.f;
;         float u0[16], d0[16], u1[16], d1[16];
;     ...
;         SLOAD(u0, d0, 0);
; #pragma unroll 1
;         for (int n0 = 0; n0 < 256; n0 += 32) {
;             SLOAD(u1, d1, n0 + 16);
;             SPROC(u0, d0, n0);
;             if (n0 + 32 < 256) SLOAD(u0, d0, n0 + 32);
;             SPROC(u1, d1, n0 + 16);
;         }
	v_cvt_pk_bf16_f32 v72, v71, v71
	v_lshlrev_b32_e32 v74, 16, v20
	global_store_short v2, v72, s[98:99]
	s_add_u32 s98, s98, 0x40000
	s_addc_u32 s99, s99, 0
	v_fma_f32 v71, v76, v71, v74
	v_cvt_pk_bf16_f32 v73, v71, v71
	v_lshlrev_b32_e32 v74, 16, v21
	global_store_short v2, v73, s[98:99]
	s_add_u32 s98, s98, 0x40000
	s_addc_u32 s99, s99, 0
	v_fma_f32 v71, v77, v71, v74
	v_cvt_pk_bf16_f32 v72, v71, v71
	v_lshlrev_b32_e32 v74, 16, v22
	global_store_short v2, v72, s[98:99]
	s_add_u32 s98, s98, 0x40000
	s_addc_u32 s99, s99, 0
	v_fma_f32 v71, v78, v71, v74
	v_cvt_pk_bf16_f32 v73, v71, v71
	v_lshlrev_b32_e32 v74, 16, v23
	global_store_short v2, v73, s[98:99]
	s_add_u32 s98, s98, 0x40000
	s_addc_u32 s99, s99, 0
	v_fma_f32 v71, v79, v71, v74
	v_cvt_pk_bf16_f32 v72, v71, v71
	v_lshlrev_b32_e32 v74, 16, v24
	global_store_short v2, v72, s[98:99]
	s_add_u32 s98, s98, 0x40000
	s_addc_u32 s99, s99, 0
	v_fma_f32 v71, v80, v71, v74
	v_cvt_pk_bf16_f32 v73, v71, v71
	v_lshlrev_b32_e32 v74, 16, v25
	global_store_short v2, v73, s[98:99]
	s_add_u32 s98, s98, 0x40000
	s_addc_u32 s99, s99, 0
	v_fma_f32 v71, v81, v71, v74
	v_cvt_pk_bf16_f32 v72, v71, v71
	v_lshlrev_b32_e32 v74, 16, v26
	global_store_short v2, v72, s[98:99]
	s_add_u32 s98, s98, 0x40000
	s_addc_u32 s99, s99, 0
	v_fma_f32 v71, v82, v71, v74
	v_cvt_pk_bf16_f32 v73, v71, v71
	v_lshlrev_b32_e32 v74, 16, v27
	global_store_short v2, v73, s[98:99]
	s_add_u32 s98, s98, 0x40000
	s_addc_u32 s99, s99, 0
	v_fma_f32 v71, v83, v71, v74
	global_load_ushort v20, v2, s[16:17]
	s_add_u32 s16, s16, 0x40000
	s_addc_u32 s17, s17, 0
	global_load_ushort v21, v2, s[16:17]
	s_add_u32 s16, s16, 0x40000
	s_addc_u32 s17, s17, 0
	global_load_ushort v22, v2, s[16:17]
	s_add_u32 s16, s16, 0x40000
	s_addc_u32 s17, s17, 0
	global_load_ushort v23, v2, s[16:17]
	s_add_u32 s16, s16, 0x40000
	s_addc_u32 s17, s17, 0
	global_load_ushort v24, v2, s[16:17]
	s_add_u32 s16, s16, 0x40000
	s_addc_u32 s17, s17, 0
	global_load_ushort v25, v2, s[16:17]
	s_add_u32 s16, s16, 0x40000
	s_addc_u32 s17, s17, 0
	global_load_ushort v26, v2, s[16:17]
	s_add_u32 s16, s16, 0x40000
	s_addc_u32 s17, s17, 0
	global_load_ushort v27, v2, s[16:17]
	s_add_u32 s16, s16, 0x40000
	s_addc_u32 s17, s17, 0
	ds_read_b32 v76, v69 offset:53248
	ds_read_b32 v77, v69 offset:53760
	ds_read_b32 v78, v69 offset:54272
	ds_read_b32 v79, v69 offset:54784
	ds_read_b32 v80, v69 offset:55296
	ds_read_b32 v81, v69 offset:55808
	ds_read_b32 v82, v69 offset:56320
	ds_read_b32 v83, v69 offset:56832
	s_waitcnt vmcnt(63)
	s_waitcnt lgkmcnt(0)
	v_cvt_pk_bf16_f32 v72, v71, v71
	v_lshlrev_b32_e32 v74, 16, v28
	global_store_short v2, v72, s[98:99]
	s_add_u32 s98, s98, 0x40000
	s_addc_u32 s99, s99, 0
	v_fma_f32 v71, v76, v71, v74
	v_cvt_pk_bf16_f32 v73, v71, v71
	v_lshlrev_b32_e32 v74, 16, v29
	global_store_short v2, v73, s[98:99]
	s_add_u32 s98, s98, 0x40000
	s_addc_u32 s99, s99, 0
	v_fma_f32 v71, v77, v71, v74
	v_cvt_pk_bf16_f32 v72, v71, v71
	v_lshlrev_b32_e32 v74, 16, v30
	global_store_short v2, v72, s[98:99]
	s_add_u32 s98, s98, 0x40000
	s_addc_u32 s99, s99, 0
	v_fma_f32 v71, v78, v71, v74
	v_cvt_pk_bf16_f32 v73, v71, v71
	v_lshlrev_b32_e32 v74, 16, v31
	global_store_short v2, v73, s[98:99]
	s_add_u32 s98, s98, 0x40000
	s_addc_u32 s99, s99, 0
	v_fma_f32 v71, v79, v71, v74
	v_cvt_pk_bf16_f32 v72, v71, v71
	v_lshlrev_b32_e32 v74, 16, v32
	global_store_short v2, v72, s[98:99]
	s_add_u32 s98, s98, 0x40000
	s_addc_u32 s99, s99, 0
	v_fma_f32 v71, v80, v71, v74
	v_cvt_pk_bf16_f32 v73, v71, v71
	v_lshlrev_b32_e32 v74, 16, v33
	global_store_short v2, v73, s[98:99]
	s_add_u32 s98, s98, 0x40000
	s_addc_u32 s99, s99, 0
	v_fma_f32 v71, v81, v71, v74
	v_cvt_pk_bf16_f32 v72, v71, v71
	v_lshlrev_b32_e32 v74, 16, v34
	global_store_short v2, v72, s[98:99]
	s_add_u32 s98, s98, 0x40000
	s_addc_u32 s99, s99, 0
	v_fma_f32 v71, v82, v71, v74
	v_cvt_pk_bf16_f32 v73, v71, v71
	v_lshlrev_b32_e32 v74, 16, v35
	global_store_short v2, v73, s[98:99]
	s_add_u32 s98, s98, 0x40000
	s_addc_u32 s99, s99, 0
	v_fma_f32 v71, v83, v71, v74
	global_load_ushort v28, v2, s[16:17]
	s_add_u32 s16, s16, 0x40000
	s_addc_u32 s17, s17, 0
	global_load_ushort v29, v2, s[16:17]
	s_add_u32 s16, s16, 0x40000
	s_addc_u32 s17, s17, 0
	global_load_ushort v30, v2, s[16:17]
	s_add_u32 s16, s16, 0x40000
	s_addc_u32 s17, s17, 0
	global_load_ushort v31, v2, s[16:17]
	s_add_u32 s16, s16, 0x40000
	s_addc_u32 s17, s17, 0
	global_load_ushort v32, v2, s[16:17]
	s_add_u32 s16, s16, 0x40000
	s_addc_u32 s17, s17, 0
	global_load_ushort v33, v2, s[16:17]
	s_add_u32 s16, s16, 0x40000
	s_addc_u32 s17, s17, 0
	global_load_ushort v34, v2, s[16:17]
	s_add_u32 s16, s16, 0x40000
	s_addc_u32 s17, s17, 0
	global_load_ushort v35, v2, s[16:17]
	s_add_u32 s16, s16, 0x40000
	s_addc_u32 s17, s17, 0
	ds_read_b32 v76, v69 offset:57344
	ds_read_b32 v77, v69 offset:57856
	ds_read_b32 v78, v69 offset:58368
	ds_read_b32 v79, v69 offset:58880
	ds_read_b32 v80, v69 offset:59392
	ds_read_b32 v81, v69 offset:59904
	ds_read_b32 v82, v69 offset:60416
	ds_read_b32 v83, v69 offset:60928
	s_waitcnt vmcnt(63)
	s_waitcnt lgkmcnt(0)
; __device__ __forceinline__ int otid() { int t = threadIdx.x; asm volatile("" : "+v"(t)); return t; }
; __device__ __forceinline__ int obid() { int t = blockIdx.x; asm volatile("" : "+s"(t)); return t; }
; __device__ __forceinline__ int ogdim() { int t = gridDim.x; asm volatile("" : "+s"(t)); return t; }
; #define SLOAD(U_, D_, n0_) do { _Pragma("unroll") for (int j = 0; j < 16; ++j) { U_[j] = bf2f(sbuf[(size_t)((n0_) + j) * 131072 + e]); D_[j] = decg[(size_t)((n0_) + j) * 512 + dcol]; } } while (0)
; #define SPROC(U_, D_, n0_) do { _Pragma("unroll") for (int j = 0; j < 16; ++j) { sbuf[(size_t)((n0_) + j) * 131072 + e] = f2bf(st); st = D_[j] * st + U_[j]; } } while (0)
; __device__ __forceinline__ void gla_scan(const Params& p) {
;     ...
;     for (int e = obid() * NTHREADS + otid(); e < 4 * 256 * 128; e += ogdim() * NTHREADS) {
;         const int dcol = (e >> 15) * 128 + (e & 127); float st = 0.f;
;         float u0[16], d0[16], u1[16], d1[16];
;     ...
;         SLOAD(u0, d0, 0);
; #pragma unroll 1
;         for (int n0 = 0; n0 < 256; n0 += 32) {
;             SLOAD(u1, d1, n0 + 16);
;             SPROC(u0, d0, n0);
;             if (n0 + 32 < 256) SLOAD(u0, d0, n0 + 32);
;             SPROC(u1, d1, n0 + 16);
;         }
	v_cvt_pk_bf16_f32 v72, v71, v71
	v_lshlrev_b32_e32 v74, 16, v36
	global_store_short v2, v72, s[98:99]
	s_add_u32 s98, s98, 0x40000
	s_addc_u32 s99, s99, 0
	v_fma_f32 v71, v76, v71, v74
	v_cvt_pk_bf16_f32 v73, v71, v71
	v_lshlrev_b32_e32 v74, 16, v37
	global_store_short v2, v73, s[98:99]
	s_add_u32 s98, s98, 0x40000
	s_addc_u32 s99, s99, 0
	v_fma_f32 v71, v77, v71, v74
	v_cvt_pk_bf16_f32 v72, v71, v71
	v_lshlrev_b32_e32 v74, 16, v38
	global_store_short v2, v72, s[98:99]
	s_add_u32 s98, s98, 0x40000
	s_addc_u32 s99, s99, 0
	v_fma_f32 v71, v78, v71, v74
	v_cvt_pk_bf16_f32 v73, v71, v71
	v_lshlrev_b32_e32 v74, 16, v39
	global_store_short v2, v73, s[98:99]
	s_add_u32 s98, s98, 0x40000
	s_addc_u32 s99, s99, 0
	v_fma_f32 v71, v79, v71, v74
	v_cvt_pk_bf16_f32 v72, v71, v71
	v_lshlrev_b32_e32 v74, 16, v40
	global_store_short v2, v72, s[98:99]
	s_add_u32 s98, s98, 0x40000
	s_addc_u32 s99, s99, 0
	v_fma_f32 v71, v80, v71, v74
	v_cvt_pk_bf16_f32 v73, v71, v71
	v_lshlrev_b32_e32 v74, 16, v41
	global_store_short v2, v73, s[98:99]
	s_add_u32 s98, s98, 0x40000
	s_addc_u32 s99, s99, 0
	v_fma_f32 v71, v81, v71, v74
	v_cvt_pk_bf16_f32 v72, v71, v71
	v_lshlrev_b32_e32 v74, 16, v42
	global_store_short v2, v72, s[98:99]
	s_add_u32 s98, s98, 0x40000
	s_addc_u32 s99, s99, 0
	v_fma_f32 v71, v82, v71, v74
	v_cvt_pk_bf16_f32 v73, v71, v71
	v_lshlrev_b32_e32 v74, 16, v43
	global_store_short v2, v73, s[98:99]
	s_add_u32 s98, s98, 0x40000
	s_addc_u32 s99, s99, 0
	v_fma_f32 v71, v83, v71, v74
	global_load_ushort v36, v2, s[16:17]
	s_add_u32 s16, s16, 0x40000
	s_addc_u32 s17, s17, 0
	global_load_ushort v37, v2, s[16:17]
	s_add_u32 s16, s16, 0x40000
	s_addc_u32 s17, s17, 0
	global_load_ushort v38, v2, s[16:17]
	s_add_u32 s16, s16, 0x40000
	s_addc_u32 s17, s17, 0
	global_load_ushort v39, v2, s[16:17]
	s_add_u32 s16, s16, 0x40000
	s_addc_u32 s17, s17, 0
	global_load_ushort v40, v2, s[16:17]
	s_add_u32 s16, s16, 0x40000
	s_addc_u32 s17, s17, 0
	global_load_ushort v41, v2, s[16:17]
	s_add_u32 s16, s16, 0x40000
	s_addc_u32 s17, s17, 0
	global_load_ushort v42, v2, s[16:17]
	s_add_u32 s16, s16, 0x40000
	s_addc_u32 s17, s17, 0
	global_load_ushort v43, v2, s[16:17]
	s_add_u32 s16, s16, 0x40000
	s_addc_u32 s17, s17, 0
	ds_read_b32 v76, v69 offset:61440
	ds_read_b32 v77, v69 offset:61952
	ds_read_b32 v78, v69 offset:62464
	ds_read_b32 v79, v69 offset:62976
	ds_read_b32 v80, v69 offset:63488
	ds_read_b32 v81, v69 offset:64000
	ds_read_b32 v82, v69 offset:64512
	ds_read_b32 v83, v69 offset:65024
	s_waitcnt vmcnt(63)
	s_waitcnt lgkmcnt(0)
	v_cvt_pk_bf16_f32 v72, v71, v71
	v_lshlrev_b32_e32 v74, 16, v4
	global_store_short v2, v72, s[98:99]
	s_add_u32 s98, s98, 0x40000
	s_addc_u32 s99, s99, 0
	v_fma_f32 v71, v76, v71, v74
	v_cvt_pk_bf16_f32 v73, v71, v71
	v_lshlrev_b32_e32 v74, 16, v5
	global_store_short v2, v73, s[98:99]
	s_add_u32 s98, s98, 0x40000
	s_addc_u32 s99, s99, 0
	v_fma_f32 v71, v77, v71, v74
	v_cvt_pk_bf16_f32 v72, v71, v71
	v_lshlrev_b32_e32 v74, 16, v6
	global_store_short v2, v72, s[98:99]
	s_add_u32 s98, s98, 0x40000
	s_addc_u32 s99, s99, 0
	v_fma_f32 v71, v78, v71, v74
	v_cvt_pk_bf16_f32 v73, v71, v71
	v_lshlrev_b32_e32 v74, 16, v7
	global_store_short v2, v73, s[98:99]
	s_add_u32 s98, s98, 0x40000
	s_addc_u32 s99, s99, 0
	v_fma_f32 v71, v79, v71, v74
	v_cvt_pk_bf16_f32 v72, v71, v71
	v_lshlrev_b32_e32 v74, 16, v8
	global_store_short v2, v72, s[98:99]
	s_add_u32 s98, s98, 0x40000
	s_addc_u32 s99, s99, 0
	v_fma_f32 v71, v80, v71, v74
	v_cvt_pk_bf16_f32 v73, v71, v71
	v_lshlrev_b32_e32 v74, 16, v9
	global_store_short v2, v73, s[98:99]
	s_add_u32 s98, s98, 0x40000
	s_addc_u32 s99, s99, 0
	v_fma_f32 v71, v81, v71, v74
	v_cvt_pk_bf16_f32 v72, v71, v71
	v_lshlrev_b32_e32 v74, 16, v10
	global_store_short v2, v72, s[98:99]
	s_add_u32 s98, s98, 0x40000
	s_addc_u32 s99, s99, 0
	v_fma_f32 v71, v82, v71, v74
	v_cvt_pk_bf16_f32 v73, v71, v71
	v_lshlrev_b32_e32 v74, 16, v11
	global_store_short v2, v73, s[98:99]
	s_add_u32 s98, s98, 0x40000
	s_addc_u32 s99, s99, 0
	v_fma_f32 v71, v83, v71, v74
	global_load_ushort v4, v2, s[16:17]
	s_add_u32 s16, s16, 0x40000
	s_addc_u32 s17, s17, 0
	global_load_ushort v5, v2, s[16:17]
	s_add_u32 s16, s16, 0x40000
	s_addc_u32 s17, s17, 0
	global_load_ushort v6, v2, s[16:17]
	s_add_u32 s16, s16, 0x40000
	s_addc_u32 s17, s17, 0
	global_load_ushort v7, v2, s[16:17]
	s_add_u32 s16, s16, 0x40000
	s_addc_u32 s17, s17, 0
	global_load_ushort v8, v2, s[16:17]
	s_add_u32 s16, s16, 0x40000
	s_addc_u32 s17, s17, 0
	global_load_ushort v9, v2, s[16:17]
	s_add_u32 s16, s16, 0x40000
	s_addc_u32 s17, s17, 0
	global_load_ushort v10, v2, s[16:17]
	s_add_u32 s16, s16, 0x40000
	s_addc_u32 s17, s17, 0
	global_load_ushort v11, v2, s[16:17]
	s_add_u32 s16, s16, 0x40000
	s_addc_u32 s17, s17, 0
	ds_read_b32 v76, v70 offset:0
	ds_read_b32 v77, v70 offset:512
	ds_read_b32 v78, v70 offset:1024
	ds_read_b32 v79, v70 offset:1536
	ds_read_b32 v80, v70 offset:2048
	ds_read_b32 v81, v70 offset:2560
	ds_read_b32 v82, v70 offset:3072
	ds_read_b32 v83, v70 offset:3584
	s_waitcnt vmcnt(63)
	s_waitcnt lgkmcnt(0)
; __device__ __forceinline__ int otid() { int t = threadIdx.x; asm volatile("" : "+v"(t)); return t; }
; __device__ __forceinline__ int obid() { int t = blockIdx.x; asm volatile("" : "+s"(t)); return t; }
; __device__ __forceinline__ int ogdim() { int t = gridDim.x; asm volatile("" : "+s"(t)); return t; }
; #define SLOAD(U_, D_, n0_) do { _Pragma("unroll") for (int j = 0; j < 16; ++j) { U_[j] = bf2f(sbuf[(size_t)((n0_) + j) * 131072 + e]); D_[j] = decg[(size_t)((n0_) + j) * 512 + dcol]; } } while (0)
; #define SPROC(U_, D_, n0_) do { _Pragma("unroll") for (int j = 0; j < 16; ++j) { sbuf[(size_t)((n0_) + j) * 131072 + e] = f2bf(st); st = D_[j] * st + U_[j]; } } while (0)
; __device__ __forceinline__ void gla_scan(const Params& p) {
;     ...
;     for (int e = obid() * NTHREADS + otid(); e < 4 * 256 * 128; e += ogdim() * NTHREADS) {
;         const int dcol = (e >> 15) * 128 + (e & 127); float st = 0.f;
;         float u0[16], d0[16], u1[16], d1[16];
;     ...
;         SLOAD(u0, d0, 0);
; #pragma unroll 1
;         for (int n0 = 0; n0 < 256; n0 += 32) {
;             SLOAD(u1, d1, n0 + 16);
;             SPROC(u0, d0, n0);
;             if (n0 + 32 < 256) SLOAD(u0, d0, n0 + 32);
;             SPROC(u1, d1, n0 + 16);
;         }
	v_cvt_pk_bf16_f32 v72, v71, v71
	v_lshlrev_b32_e32 v74, 16, v12
	global_store_short v2, v72, s[98:99]
	s_add_u32 s98, s98, 0x40000
	s_addc_u32 s99, s99, 0
	v_fma_f32 v71, v76, v71, v74
	v_cvt_pk_bf16_f32 v73, v71, v71
	v_lshlrev_b32_e32 v74, 16, v13
	global_store_short v2, v73, s[98:99]
	s_add_u32 s98, s98, 0x40000
	s_addc_u32 s99, s99, 0
	v_fma_f32 v71, v77, v71, v74
	v_cvt_pk_bf16_f32 v72, v71, v71
	v_lshlrev_b32_e32 v74, 16, v14
	global_store_short v2, v72, s[98:99]
	s_add_u32 s98, s98, 0x40000
	s_addc_u32 s99, s99, 0
	v_fma_f32 v71, v78, v71, v74
	v_cvt_pk_bf16_f32 v73, v71, v71
	v_lshlrev_b32_e32 v74, 16, v15
	global_store_short v2, v73, s[98:99]
	s_add_u32 s98, s98, 0x40000
	s_addc_u32 s99, s99, 0
	v_fma_f32 v71, v79, v71, v74
	v_cvt_pk_bf16_f32 v72, v71, v71
	v_lshlrev_b32_e32 v74, 16, v16
	global_store_short v2, v72, s[98:99]
	s_add_u32 s98, s98, 0x40000
	s_addc_u32 s99, s99, 0
	v_fma_f32 v71, v80, v71, v74
	v_cvt_pk_bf16_f32 v73, v71, v71
	v_lshlrev_b32_e32 v74, 16, v17
	global_store_short v2, v73, s[98:99]
	s_add_u32 s98, s98, 0x40000
	s_addc_u32 s99, s99, 0
	v_fma_f32 v71, v81, v71, v74
	v_cvt_pk_bf16_f32 v72, v71, v71
	v_lshlrev_b32_e32 v74, 16, v18
	global_store_short v2, v72, s[98:99]
	s_add_u32 s98, s98, 0x40000
	s_addc_u32 s99, s99, 0
	v_fma_f32 v71, v82, v71, v74
	v_cvt_pk_bf16_f32 v73, v71, v71
	v_lshlrev_b32_e32 v74, 16, v19
	global_store_short v2, v73, s[98:99]
	s_add_u32 s98, s98, 0x40000
	s_addc_u32 s99, s99, 0
	v_fma_f32 v71, v83, v71, v74
	global_load_ushort v12, v2, s[16:17]
	s_add_u32 s16, s16, 0x40000
	s_addc_u32 s17, s17, 0
	global_load_ushort v13, v2, s[16:17]
	s_add_u32 s16, s16, 0x40000
	s_addc_u32 s17, s17, 0
	global_load_ushort v14, v2, s[16:17]
	s_add_u32 s16, s16, 0x40000
	s_addc_u32 s17, s17, 0
	global_load_ushort v15, v2, s[16:17]
	s_add_u32 s16, s16, 0x40000
	s_addc_u32 s17, s17, 0
	global_load_ushort v16, v2, s[16:17]
	s_add_u32 s16, s16, 0x40000
	s_addc_u32 s17, s17, 0
	global_load_ushort v17, v2, s[16:17]
	s_add_u32 s16, s16, 0x40000
	s_addc_u32 s17, s17, 0
	global_load_ushort v18, v2, s[16:17]
	s_add_u32 s16, s16, 0x40000
	s_addc_u32 s17, s17, 0
	global_load_ushort v19, v2, s[16:17]
	s_add_u32 s16, s16, 0x40000
	s_addc_u32 s17, s17, 0
	ds_read_b32 v76, v70 offset:4096
	ds_read_b32 v77, v70 offset:4608
	ds_read_b32 v78, v70 offset:5120
	ds_read_b32 v79, v70 offset:5632
	ds_read_b32 v80, v70 offset:6144
	ds_read_b32 v81, v70 offset:6656
	ds_read_b32 v82, v70 offset:7168
	ds_read_b32 v83, v70 offset:7680
	s_waitcnt vmcnt(63)
	s_waitcnt lgkmcnt(0)
	v_cvt_pk_bf16_f32 v72, v71, v71
	v_lshlrev_b32_e32 v74, 16, v20
	global_store_short v2, v72, s[98:99]
	s_add_u32 s98, s98, 0x40000
	s_addc_u32 s99, s99, 0
	v_fma_f32 v71, v76, v71, v74
	v_cvt_pk_bf16_f32 v73, v71, v71
	v_lshlrev_b32_e32 v74, 16, v21
	global_store_short v2, v73, s[98:99]
	s_add_u32 s98, s98, 0x40000
	s_addc_u32 s99, s99, 0
	v_fma_f32 v71, v77, v71, v74
	v_cvt_pk_bf16_f32 v72, v71, v71
	v_lshlrev_b32_e32 v74, 16, v22
	global_store_short v2, v72, s[98:99]
	s_add_u32 s98, s98, 0x40000
	s_addc_u32 s99, s99, 0
	v_fma_f32 v71, v78, v71, v74
	v_cvt_pk_bf16_f32 v73, v71, v71
	v_lshlrev_b32_e32 v74, 16, v23
	global_store_short v2, v73, s[98:99]
	s_add_u32 s98, s98, 0x40000
	s_addc_u32 s99, s99, 0
	v_fma_f32 v71, v79, v71, v74
	v_cvt_pk_bf16_f32 v72, v71, v71
	v_lshlrev_b32_e32 v74, 16, v24
	global_store_short v2, v72, s[98:99]
	s_add_u32 s98, s98, 0x40000
	s_addc_u32 s99, s99, 0
	v_fma_f32 v71, v80, v71, v74
	v_cvt_pk_bf16_f32 v73, v71, v71
	v_lshlrev_b32_e32 v74, 16, v25
	global_store_short v2, v73, s[98:99]
	s_add_u32 s98, s98, 0x40000
	s_addc_u32 s99, s99, 0
	v_fma_f32 v71, v81, v71, v74
	v_cvt_pk_bf16_f32 v72, v71, v71
	v_lshlrev_b32_e32 v74, 16, v26
	global_store_short v2, v72, s[98:99]
	s_add_u32 s98, s98, 0x40000
	s_addc_u32 s99, s99, 0
	v_fma_f32 v71, v82, v71, v74
	v_cvt_pk_bf16_f32 v73, v71, v71
	v_lshlrev_b32_e32 v74, 16, v27
	global_store_short v2, v73, s[98:99]
	s_add_u32 s98, s98, 0x40000
	s_addc_u32 s99, s99, 0
	v_fma_f32 v71, v83, v71, v74
	global_load_ushort v20, v2, s[16:17]
	s_add_u32 s16, s16, 0x40000
	s_addc_u32 s17, s17, 0
	global_load_ushort v21, v2, s[16:17]
	s_add_u32 s16, s16, 0x40000
	s_addc_u32 s17, s17, 0
	global_load_ushort v22, v2, s[16:17]
	s_add_u32 s16, s16, 0x40000
	s_addc_u32 s17, s17, 0
	global_load_ushort v23, v2, s[16:17]
	s_add_u32 s16, s16, 0x40000
	s_addc_u32 s17, s17, 0
	global_load_ushort v24, v2, s[16:17]
	s_add_u32 s16, s16, 0x40000
	s_addc_u32 s17, s17, 0
	global_load_ushort v25, v2, s[16:17]
	s_add_u32 s16, s16, 0x40000
	s_addc_u32 s17, s17, 0
	global_load_ushort v26, v2, s[16:17]
	s_add_u32 s16, s16, 0x40000
	s_addc_u32 s17, s17, 0
	global_load_ushort v27, v2, s[16:17]
	s_add_u32 s16, s16, 0x40000
	s_addc_u32 s17, s17, 0
	ds_read_b32 v76, v70 offset:8192
	ds_read_b32 v77, v70 offset:8704
	ds_read_b32 v78, v70 offset:9216
	ds_read_b32 v79, v70 offset:9728
	ds_read_b32 v80, v70 offset:10240
	ds_read_b32 v81, v70 offset:10752
	ds_read_b32 v82, v70 offset:11264
	ds_read_b32 v83, v70 offset:11776
	s_waitcnt vmcnt(63)
	s_waitcnt lgkmcnt(0)
; __device__ __forceinline__ int otid() { int t = threadIdx.x; asm volatile("" : "+v"(t)); return t; }
; __device__ __forceinline__ int obid() { int t = blockIdx.x; asm volatile("" : "+s"(t)); return t; }
; __device__ __forceinline__ int ogdim() { int t = gridDim.x; asm volatile("" : "+s"(t)); return t; }
; #define SLOAD(U_, D_, n0_) do { _Pragma("unroll") for (int j = 0; j < 16; ++j) { U_[j] = bf2f(sbuf[(size_t)((n0_) + j) * 131072 + e]); D_[j] = decg[(size_t)((n0_) + j) * 512 + dcol]; } } while (0)
; #define SPROC(U_, D_, n0_) do { _Pragma("unroll") for (int j = 0; j < 16; ++j) { sbuf[(size_t)((n0_) + j) * 131072 + e] = f2bf(st); st = D_[j] * st + U_[j]; } } while (0)
; __device__ __forceinline__ void gla_scan(const Params& p) {
;     ...
;     for (int e = obid() * NTHREADS + otid(); e < 4 * 256 * 128; e += ogdim() * NTHREADS) {
;         const int dcol = (e >> 15) * 128 + (e & 127); float st = 0.f;
;         float u0[16], d0[16], u1[16], d1[16];
;     ...
;         SLOAD(u0, d0, 0);
; #pragma unroll 1
;         for (int n0 = 0; n0 < 256; n0 += 32) {
;             SLOAD(u1, d1, n0 + 16);
;             SPROC(u0, d0, n0);
;             if (n0 + 32 < 256) SLOAD(u0, d0, n0 + 32);
;             SPROC(u1, d1, n0 + 16);
;         }
	v_cvt_pk_bf16_f32 v72, v71, v71
	v_lshlrev_b32_e32 v74, 16, v28
	global_store_short v2, v72, s[98:99]
	s_add_u32 s98, s98, 0x40000
	s_addc_u32 s99, s99, 0
	v_fma_f32 v71, v76, v71, v74
	v_cvt_pk_bf16_f32 v73, v71, v71
	v_lshlrev_b32_e32 v74, 16, v29
	global_store_short v2, v73, s[98:99]
	s_add_u32 s98, s98, 0x40000
	s_addc_u32 s99, s99, 0
	v_fma_f32 v71, v77, v71, v74
	v_cvt_pk_bf16_f32 v72, v71, v71
	v_lshlrev_b32_e32 v74, 16, v30
	global_store_short v2, v72, s[98:99]
	s_add_u32 s98, s98, 0x40000
	s_addc_u32 s99, s99, 0
	v_fma_f32 v71, v78, v71, v74
	v_cvt_pk_bf16_f32 v73, v71, v71
	v_lshlrev_b32_e32 v74, 16, v31
	global_store_short v2, v73, s[98:99]
	s_add_u32 s98, s98, 0x40000
	s_addc_u32 s99, s99, 0
	v_fma_f32 v71, v79, v71, v74
	v_cvt_pk_bf16_f32 v72, v71, v71
	v_lshlrev_b32_e32 v74, 16, v32
	global_store_short v2, v72, s[98:99]
	s_add_u32 s98, s98, 0x40000
	s_addc_u32 s99, s99, 0
	v_fma_f32 v71, v80, v71, v74
	v_cvt_pk_bf16_f32 v73, v71, v71
	v_lshlrev_b32_e32 v74, 16, v33
	global_store_short v2, v73, s[98:99]
	s_add_u32 s98, s98, 0x40000
	s_addc_u32 s99, s99, 0
	v_fma_f32 v71, v81, v71, v74
	v_cvt_pk_bf16_f32 v72, v71, v71
	v_lshlrev_b32_e32 v74, 16, v34
	global_store_short v2, v72, s[98:99]
	s_add_u32 s98, s98, 0x40000
	s_addc_u32 s99, s99, 0
	v_fma_f32 v71, v82, v71, v74
	v_cvt_pk_bf16_f32 v73, v71, v71
	v_lshlrev_b32_e32 v74, 16, v35
	global_store_short v2, v73, s[98:99]
	s_add_u32 s98, s98, 0x40000
	s_addc_u32 s99, s99, 0
	v_fma_f32 v71, v83, v71, v74
	global_load_ushort v28, v2, s[16:17]
	s_add_u32 s16, s16, 0x40000
	s_addc_u32 s17, s17, 0
	global_load_ushort v29, v2, s[16:17]
	s_add_u32 s16, s16, 0x40000
	s_addc_u32 s17, s17, 0
	global_load_ushort v30, v2, s[16:17]
	s_add_u32 s16, s16, 0x40000
	s_addc_u32 s17, s17, 0
	global_load_ushort v31, v2, s[16:17]
	s_add_u32 s16, s16, 0x40000
	s_addc_u32 s17, s17, 0
	global_load_ushort v32, v2, s[16:17]
	s_add_u32 s16, s16, 0x40000
	s_addc_u32 s17, s17, 0
	global_load_ushort v33, v2, s[16:17]
	s_add_u32 s16, s16, 0x40000
	s_addc_u32 s17, s17, 0
	global_load_ushort v34, v2, s[16:17]
	s_add_u32 s16, s16, 0x40000
	s_addc_u32 s17, s17, 0
	global_load_ushort v35, v2, s[16:17]
	s_add_u32 s16, s16, 0x40000
	s_addc_u32 s17, s17, 0
	ds_read_b32 v76, v70 offset:12288
	ds_read_b32 v77, v70 offset:12800
	ds_read_b32 v78, v70 offset:13312
	ds_read_b32 v79, v70 offset:13824
	ds_read_b32 v80, v70 offset:14336
	ds_read_b32 v81, v70 offset:14848
	ds_read_b32 v82, v70 offset:15360
	ds_read_b32 v83, v70 offset:15872
	s_waitcnt vmcnt(63)
	s_waitcnt lgkmcnt(0)
	v_cvt_pk_bf16_f32 v72, v71, v71
	v_lshlrev_b32_e32 v74, 16, v36
	global_store_short v2, v72, s[98:99]
	s_add_u32 s98, s98, 0x40000
	s_addc_u32 s99, s99, 0
	v_fma_f32 v71, v76, v71, v74
	v_cvt_pk_bf16_f32 v73, v71, v71
	v_lshlrev_b32_e32 v74, 16, v37
	global_store_short v2, v73, s[98:99]
	s_add_u32 s98, s98, 0x40000
	s_addc_u32 s99, s99, 0
	v_fma_f32 v71, v77, v71, v74
	v_cvt_pk_bf16_f32 v72, v71, v71
	v_lshlrev_b32_e32 v74, 16, v38
	global_store_short v2, v72, s[98:99]
	s_add_u32 s98, s98, 0x40000
	s_addc_u32 s99, s99, 0
	v_fma_f32 v71, v78, v71, v74
	v_cvt_pk_bf16_f32 v73, v71, v71
	v_lshlrev_b32_e32 v74, 16, v39
	global_store_short v2, v73, s[98:99]
	s_add_u32 s98, s98, 0x40000
	s_addc_u32 s99, s99, 0
	v_fma_f32 v71, v79, v71, v74
	v_cvt_pk_bf16_f32 v72, v71, v71
	v_lshlrev_b32_e32 v74, 16, v40
	global_store_short v2, v72, s[98:99]
	s_add_u32 s98, s98, 0x40000
	s_addc_u32 s99, s99, 0
	v_fma_f32 v71, v80, v71, v74
	v_cvt_pk_bf16_f32 v73, v71, v71
	v_lshlrev_b32_e32 v74, 16, v41
	global_store_short v2, v73, s[98:99]
	s_add_u32 s98, s98, 0x40000
	s_addc_u32 s99, s99, 0
	v_fma_f32 v71, v81, v71, v74
	v_cvt_pk_bf16_f32 v72, v71, v71
	v_lshlrev_b32_e32 v74, 16, v42
	global_store_short v2, v72, s[98:99]
	s_add_u32 s98, s98, 0x40000
	s_addc_u32 s99, s99, 0
	v_fma_f32 v71, v82, v71, v74
	v_cvt_pk_bf16_f32 v73, v71, v71
	v_lshlrev_b32_e32 v74, 16, v43
	global_store_short v2, v73, s[98:99]
	s_add_u32 s98, s98, 0x40000
	s_addc_u32 s99, s99, 0
	v_fma_f32 v71, v83, v71, v74
	global_load_ushort v36, v2, s[16:17]
	s_add_u32 s16, s16, 0x40000
	s_addc_u32 s17, s17, 0
	global_load_ushort v37, v2, s[16:17]
	s_add_u32 s16, s16, 0x40000
	s_addc_u32 s17, s17, 0
	global_load_ushort v38, v2, s[16:17]
	s_add_u32 s16, s16, 0x40000
	s_addc_u32 s17, s17, 0
	global_load_ushort v39, v2, s[16:17]
	s_add_u32 s16, s16, 0x40000
	s_addc_u32 s17, s17, 0
	global_load_ushort v40, v2, s[16:17]
	s_add_u32 s16, s16, 0x40000
	s_addc_u32 s17, s17, 0
	global_load_ushort v41, v2, s[16:17]
	s_add_u32 s16, s16, 0x40000
	s_addc_u32 s17, s17, 0
	global_load_ushort v42, v2, s[16:17]
	s_add_u32 s16, s16, 0x40000
	s_addc_u32 s17, s17, 0
	global_load_ushort v43, v2, s[16:17]
	s_add_u32 s16, s16, 0x40000
	s_addc_u32 s17, s17, 0
	ds_read_b32 v76, v70 offset:16384
	ds_read_b32 v77, v70 offset:16896
	ds_read_b32 v78, v70 offset:17408
	ds_read_b32 v79, v70 offset:17920
	ds_read_b32 v80, v70 offset:18432
	ds_read_b32 v81, v70 offset:18944
	ds_read_b32 v82, v70 offset:19456
	ds_read_b32 v83, v70 offset:19968
	s_waitcnt vmcnt(63)
	s_waitcnt lgkmcnt(0)
; __device__ __forceinline__ int otid() { int t = threadIdx.x; asm volatile("" : "+v"(t)); return t; }
; __device__ __forceinline__ int obid() { int t = blockIdx.x; asm volatile("" : "+s"(t)); return t; }
; __device__ __forceinline__ int ogdim() { int t = gridDim.x; asm volatile("" : "+s"(t)); return t; }
; #define SLOAD(U_, D_, n0_) do { _Pragma("unroll") for (int j = 0; j < 16; ++j) { U_[j] = bf2f(sbuf[(size_t)((n0_) + j) * 131072 + e]); D_[j] = decg[(size_t)((n0_) + j) * 512 + dcol]; } } while (0)
; #define SPROC(U_, D_, n0_) do { _Pragma("unroll") for (int j = 0; j < 16; ++j) { sbuf[(size_t)((n0_) + j) * 131072 + e] = f2bf(st); st = D_[j] * st + U_[j]; } } while (0)
; __device__ __forceinline__ void gla_scan(const Params& p) {
;     ...
;     for (int e = obid() * NTHREADS + otid(); e < 4 * 256 * 128; e += ogdim() * NTHREADS) {
;         const int dcol = (e >> 15) * 128 + (e & 127); float st = 0.f;
;         float u0[16], d0[16], u1[16], d1[16];
;     ...
;         SLOAD(u0, d0, 0);
; #pragma unroll 1
;         for (int n0 = 0; n0 < 256; n0 += 32) {
;             SLOAD(u1, d1, n0 + 16);
;             SPROC(u0, d0, n0);
;             if (n0 + 32 < 256) SLOAD(u0, d0, n0 + 32);
;             SPROC(u1, d1, n0 + 16);
;         }
	v_cvt_pk_bf16_f32 v72, v71, v71
	v_lshlrev_b32_e32 v74, 16, v4
	global_store_short v2, v72, s[98:99]
	s_add_u32 s98, s98, 0x40000
	s_addc_u32 s99, s99, 0
	v_fma_f32 v71, v76, v71, v74
	v_cvt_pk_bf16_f32 v73, v71, v71
	v_lshlrev_b32_e32 v74, 16, v5
	global_store_short v2, v73, s[98:99]
	s_add_u32 s98, s98, 0x40000
	s_addc_u32 s99, s99, 0
	v_fma_f32 v71, v77, v71, v74
	v_cvt_pk_bf16_f32 v72, v71, v71
	v_lshlrev_b32_e32 v74, 16, v6
	global_store_short v2, v72, s[98:99]
	s_add_u32 s98, s98, 0x40000
	s_addc_u32 s99, s99, 0
	v_fma_f32 v71, v78, v71, v74
	v_cvt_pk_bf16_f32 v73, v71, v71
	v_lshlrev_b32_e32 v74, 16, v7
	global_store_short v2, v73, s[98:99]
	s_add_u32 s98, s98, 0x40000
	s_addc_u32 s99, s99, 0
	v_fma_f32 v71, v79, v71, v74
	v_cvt_pk_bf16_f32 v72, v71, v71
	v_lshlrev_b32_e32 v74, 16, v8
	global_store_short v2, v72, s[98:99]
	s_add_u32 s98, s98, 0x40000
	s_addc_u32 s99, s99, 0
	v_fma_f32 v71, v80, v71, v74
	v_cvt_pk_bf16_f32 v73, v71, v71
	v_lshlrev_b32_e32 v74, 16, v9
	global_store_short v2, v73, s[98:99]
	s_add_u32 s98, s98, 0x40000
	s_addc_u32 s99, s99, 0
	v_fma_f32 v71, v81, v71, v74
	v_cvt_pk_bf16_f32 v72, v71, v71
	v_lshlrev_b32_e32 v74, 16, v10
	global_store_short v2, v72, s[98:99]
	s_add_u32 s98, s98, 0x40000
	s_addc_u32 s99, s99, 0
	v_fma_f32 v71, v82, v71, v74
	v_cvt_pk_bf16_f32 v73, v71, v71
	v_lshlrev_b32_e32 v74, 16, v11
	global_store_short v2, v73, s[98:99]
	s_add_u32 s98, s98, 0x40000
	s_addc_u32 s99, s99, 0
	v_fma_f32 v71, v83, v71, v74
	global_load_ushort v4, v2, s[16:17]
	s_add_u32 s16, s16, 0x40000
	s_addc_u32 s17, s17, 0
	global_load_ushort v5, v2, s[16:17]
	s_add_u32 s16, s16, 0x40000
	s_addc_u32 s17, s17, 0
	global_load_ushort v6, v2, s[16:17]
	s_add_u32 s16, s16, 0x40000
	s_addc_u32 s17, s17, 0
	global_load_ushort v7, v2, s[16:17]
	s_add_u32 s16, s16, 0x40000
	s_addc_u32 s17, s17, 0
	global_load_ushort v8, v2, s[16:17]
	s_add_u32 s16, s16, 0x40000
	s_addc_u32 s17, s17, 0
	global_load_ushort v9, v2, s[16:17]
	s_add_u32 s16, s16, 0x40000
	s_addc_u32 s17, s17, 0
	global_load_ushort v10, v2, s[16:17]
	s_add_u32 s16, s16, 0x40000
	s_addc_u32 s17, s17, 0
	global_load_ushort v11, v2, s[16:17]
	s_add_u32 s16, s16, 0x40000
	s_addc_u32 s17, s17, 0
	ds_read_b32 v76, v70 offset:20480
	ds_read_b32 v77, v70 offset:20992
	ds_read_b32 v78, v70 offset:21504
	ds_read_b32 v79, v70 offset:22016
	ds_read_b32 v80, v70 offset:22528
	ds_read_b32 v81, v70 offset:23040
	ds_read_b32 v82, v70 offset:23552
	ds_read_b32 v83, v70 offset:24064
	s_waitcnt vmcnt(63)
	s_waitcnt lgkmcnt(0)
	v_cvt_pk_bf16_f32 v72, v71, v71
	v_lshlrev_b32_e32 v74, 16, v12
	global_store_short v2, v72, s[98:99]
	s_add_u32 s98, s98, 0x40000
	s_addc_u32 s99, s99, 0
	v_fma_f32 v71, v76, v71, v74
	v_cvt_pk_bf16_f32 v73, v71, v71
	v_lshlrev_b32_e32 v74, 16, v13
	global_store_short v2, v73, s[98:99]
	s_add_u32 s98, s98, 0x40000
	s_addc_u32 s99, s99, 0
	v_fma_f32 v71, v77, v71, v74
	v_cvt_pk_bf16_f32 v72, v71, v71
	v_lshlrev_b32_e32 v74, 16, v14
	global_store_short v2, v72, s[98:99]
	s_add_u32 s98, s98, 0x40000
	s_addc_u32 s99, s99, 0
	v_fma_f32 v71, v78, v71, v74
	v_cvt_pk_bf16_f32 v73, v71, v71
	v_lshlrev_b32_e32 v74, 16, v15
	global_store_short v2, v73, s[98:99]
	s_add_u32 s98, s98, 0x40000
	s_addc_u32 s99, s99, 0
	v_fma_f32 v71, v79, v71, v74
	v_cvt_pk_bf16_f32 v72, v71, v71
	v_lshlrev_b32_e32 v74, 16, v16
	global_store_short v2, v72, s[98:99]
	s_add_u32 s98, s98, 0x40000
	s_addc_u32 s99, s99, 0
	v_fma_f32 v71, v80, v71, v74
	v_cvt_pk_bf16_f32 v73, v71, v71
	v_lshlrev_b32_e32 v74, 16, v17
	global_store_short v2, v73, s[98:99]
	s_add_u32 s98, s98, 0x40000
	s_addc_u32 s99, s99, 0
	v_fma_f32 v71, v81, v71, v74
	v_cvt_pk_bf16_f32 v72, v71, v71
	v_lshlrev_b32_e32 v74, 16, v18
	global_store_short v2, v72, s[98:99]
	s_add_u32 s98, s98, 0x40000
	s_addc_u32 s99, s99, 0
	v_fma_f32 v71, v82, v71, v74
	v_cvt_pk_bf16_f32 v73, v71, v71
	v_lshlrev_b32_e32 v74, 16, v19
	global_store_short v2, v73, s[98:99]
	s_add_u32 s98, s98, 0x40000
	s_addc_u32 s99, s99, 0
	v_fma_f32 v71, v83, v71, v74
	global_load_ushort v12, v2, s[16:17]
	s_add_u32 s16, s16, 0x40000
	s_addc_u32 s17, s17, 0
	global_load_ushort v13, v2, s[16:17]
	s_add_u32 s16, s16, 0x40000
	s_addc_u32 s17, s17, 0
	global_load_ushort v14, v2, s[16:17]
	s_add_u32 s16, s16, 0x40000
	s_addc_u32 s17, s17, 0
	global_load_ushort v15, v2, s[16:17]
	s_add_u32 s16, s16, 0x40000
	s_addc_u32 s17, s17, 0
	global_load_ushort v16, v2, s[16:17]
	s_add_u32 s16, s16, 0x40000
	s_addc_u32 s17, s17, 0
	global_load_ushort v17, v2, s[16:17]
	s_add_u32 s16, s16, 0x40000
	s_addc_u32 s17, s17, 0
	global_load_ushort v18, v2, s[16:17]
	s_add_u32 s16, s16, 0x40000
	s_addc_u32 s17, s17, 0
	global_load_ushort v19, v2, s[16:17]
	s_add_u32 s16, s16, 0x40000
	s_addc_u32 s17, s17, 0
	ds_read_b32 v76, v70 offset:24576
	ds_read_b32 v77, v70 offset:25088
	ds_read_b32 v78, v70 offset:25600
	ds_read_b32 v79, v70 offset:26112
	ds_read_b32 v80, v70 offset:26624
	ds_read_b32 v81, v70 offset:27136
	ds_read_b32 v82, v70 offset:27648
	ds_read_b32 v83, v70 offset:28160
	s_waitcnt vmcnt(63)
	s_waitcnt lgkmcnt(0)
; __device__ __forceinline__ int otid() { int t = threadIdx.x; asm volatile("" : "+v"(t)); return t; }
; __device__ __forceinline__ int obid() { int t = blockIdx.x; asm volatile("" : "+s"(t)); return t; }
; __device__ __forceinline__ int ogdim() { int t = gridDim.x; asm volatile("" : "+s"(t)); return t; }
; #define SLOAD(U_, D_, n0_) do { _Pragma("unroll") for (int j = 0; j < 16; ++j) { U_[j] = bf2f(sbuf[(size_t)((n0_) + j) * 131072 + e]); D_[j] = decg[(size_t)((n0_) + j) * 512 + dcol]; } } while (0)
; #define SPROC(U_, D_, n0_) do { _Pragma("unroll") for (int j = 0; j < 16; ++j) { sbuf[(size_t)((n0_) + j) * 131072 + e] = f2bf(st); st = D_[j] * st + U_[j]; } } while (0)
; __device__ __forceinline__ void gla_scan(const Params& p) {
;     ...
;     for (int e = obid() * NTHREADS + otid(); e < 4 * 256 * 128; e += ogdim() * NTHREADS) {
;         const int dcol = (e >> 15) * 128 + (e & 127); float st = 0.f;
;         float u0[16], d0[16], u1[16], d1[16];
;     ...
;         SLOAD(u0, d0, 0);
; #pragma unroll 1
;         for (int n0 = 0; n0 < 256; n0 += 32) {
;             SLOAD(u1, d1, n0 + 16);
;             SPROC(u0, d0, n0);
;             if (n0 + 32 < 256) SLOAD(u0, d0, n0 + 32);
;             SPROC(u1, d1, n0 + 16);
;         }
	v_cvt_pk_bf16_f32 v72, v71, v71
	v_lshlrev_b32_e32 v74, 16, v20
	global_store_short v2, v72, s[98:99]
	s_add_u32 s98, s98, 0x40000
	s_addc_u32 s99, s99, 0
	v_fma_f32 v71, v76, v71, v74
	v_cvt_pk_bf16_f32 v73, v71, v71
	v_lshlrev_b32_e32 v74, 16, v21
	global_store_short v2, v73, s[98:99]
	s_add_u32 s98, s98, 0x40000
	s_addc_u32 s99, s99, 0
	v_fma_f32 v71, v77, v71, v74
	v_cvt_pk_bf16_f32 v72, v71, v71
	v_lshlrev_b32_e32 v74, 16, v22
	global_store_short v2, v72, s[98:99]
	s_add_u32 s98, s98, 0x40000
	s_addc_u32 s99, s99, 0
	v_fma_f32 v71, v78, v71, v74
	v_cvt_pk_bf16_f32 v73, v71, v71
	v_lshlrev_b32_e32 v74, 16, v23
	global_store_short v2, v73, s[98:99]
	s_add_u32 s98, s98, 0x40000
	s_addc_u32 s99, s99, 0
	v_fma_f32 v71, v79, v71, v74
	v_cvt_pk_bf16_f32 v72, v71, v71
	v_lshlrev_b32_e32 v74, 16, v24
	global_store_short v2, v72, s[98:99]
	s_add_u32 s98, s98, 0x40000
	s_addc_u32 s99, s99, 0
	v_fma_f32 v71, v80, v71, v74
	v_cvt_pk_bf16_f32 v73, v71, v71
	v_lshlrev_b32_e32 v74, 16, v25
	global_store_short v2, v73, s[98:99]
	s_add_u32 s98, s98, 0x40000
	s_addc_u32 s99, s99, 0
	v_fma_f32 v71, v81, v71, v74
	v_cvt_pk_bf16_f32 v72, v71, v71
	v_lshlrev_b32_e32 v74, 16, v26
	global_store_short v2, v72, s[98:99]
	s_add_u32 s98, s98, 0x40000
	s_addc_u32 s99, s99, 0
	v_fma_f32 v71, v82, v71, v74
	v_cvt_pk_bf16_f32 v73, v71, v71
	v_lshlrev_b32_e32 v74, 16, v27
	global_store_short v2, v73, s[98:99]
	s_add_u32 s98, s98, 0x40000
	s_addc_u32 s99, s99, 0
	v_fma_f32 v71, v83, v71, v74
	global_load_ushort v20, v2, s[16:17]
	s_add_u32 s16, s16, 0x40000
	s_addc_u32 s17, s17, 0
	global_load_ushort v21, v2, s[16:17]
	s_add_u32 s16, s16, 0x40000
	s_addc_u32 s17, s17, 0
	global_load_ushort v22, v2, s[16:17]
	s_add_u32 s16, s16, 0x40000
	s_addc_u32 s17, s17, 0
	global_load_ushort v23, v2, s[16:17]
	s_add_u32 s16, s16, 0x40000
	s_addc_u32 s17, s17, 0
	global_load_ushort v24, v2, s[16:17]
	s_add_u32 s16, s16, 0x40000
	s_addc_u32 s17, s17, 0
	global_load_ushort v25, v2, s[16:17]
	s_add_u32 s16, s16, 0x40000
	s_addc_u32 s17, s17, 0
	global_load_ushort v26, v2, s[16:17]
	s_add_u32 s16, s16, 0x40000
	s_addc_u32 s17, s17, 0
	global_load_ushort v27, v2, s[16:17]
	s_add_u32 s16, s16, 0x40000
	s_addc_u32 s17, s17, 0
	ds_read_b32 v76, v70 offset:28672
	ds_read_b32 v77, v70 offset:29184
	ds_read_b32 v78, v70 offset:29696
	ds_read_b32 v79, v70 offset:30208
	ds_read_b32 v80, v70 offset:30720
	ds_read_b32 v81, v70 offset:31232
	ds_read_b32 v82, v70 offset:31744
	ds_read_b32 v83, v70 offset:32256
	s_waitcnt vmcnt(63)
	s_waitcnt lgkmcnt(0)
	v_cvt_pk_bf16_f32 v72, v71, v71
	v_lshlrev_b32_e32 v74, 16, v28
	global_store_short v2, v72, s[98:99]
	s_add_u32 s98, s98, 0x40000
	s_addc_u32 s99, s99, 0
	v_fma_f32 v71, v76, v71, v74
	v_cvt_pk_bf16_f32 v73, v71, v71
	v_lshlrev_b32_e32 v74, 16, v29
	global_store_short v2, v73, s[98:99]
	s_add_u32 s98, s98, 0x40000
	s_addc_u32 s99, s99, 0
	v_fma_f32 v71, v77, v71, v74
	v_cvt_pk_bf16_f32 v72, v71, v71
	v_lshlrev_b32_e32 v74, 16, v30
	global_store_short v2, v72, s[98:99]
	s_add_u32 s98, s98, 0x40000
	s_addc_u32 s99, s99, 0
	v_fma_f32 v71, v78, v71, v74
	v_cvt_pk_bf16_f32 v73, v71, v71
	v_lshlrev_b32_e32 v74, 16, v31
	global_store_short v2, v73, s[98:99]
	s_add_u32 s98, s98, 0x40000
	s_addc_u32 s99, s99, 0
	v_fma_f32 v71, v79, v71, v74
	v_cvt_pk_bf16_f32 v72, v71, v71
	v_lshlrev_b32_e32 v74, 16, v32
	global_store_short v2, v72, s[98:99]
	s_add_u32 s98, s98, 0x40000
	s_addc_u32 s99, s99, 0
	v_fma_f32 v71, v80, v71, v74
	v_cvt_pk_bf16_f32 v73, v71, v71
	v_lshlrev_b32_e32 v74, 16, v33
	global_store_short v2, v73, s[98:99]
	s_add_u32 s98, s98, 0x40000
	s_addc_u32 s99, s99, 0
	v_fma_f32 v71, v81, v71, v74
	v_cvt_pk_bf16_f32 v72, v71, v71
	v_lshlrev_b32_e32 v74, 16, v34
	global_store_short v2, v72, s[98:99]
	s_add_u32 s98, s98, 0x40000
	s_addc_u32 s99, s99, 0
	v_fma_f32 v71, v82, v71, v74
	v_cvt_pk_bf16_f32 v73, v71, v71
	v_lshlrev_b32_e32 v74, 16, v35
	global_store_short v2, v73, s[98:99]
	s_add_u32 s98, s98, 0x40000
	s_addc_u32 s99, s99, 0
	v_fma_f32 v71, v83, v71, v74
	global_load_ushort v28, v2, s[16:17]
	s_add_u32 s16, s16, 0x40000
	s_addc_u32 s17, s17, 0
	global_load_ushort v29, v2, s[16:17]
	s_add_u32 s16, s16, 0x40000
	s_addc_u32 s17, s17, 0
	global_load_ushort v30, v2, s[16:17]
	s_add_u32 s16, s16, 0x40000
	s_addc_u32 s17, s17, 0
	global_load_ushort v31, v2, s[16:17]
	s_add_u32 s16, s16, 0x40000
	s_addc_u32 s17, s17, 0
	global_load_ushort v32, v2, s[16:17]
	s_add_u32 s16, s16, 0x40000
	s_addc_u32 s17, s17, 0
	global_load_ushort v33, v2, s[16:17]
	s_add_u32 s16, s16, 0x40000
	s_addc_u32 s17, s17, 0
	global_load_ushort v34, v2, s[16:17]
	s_add_u32 s16, s16, 0x40000
	s_addc_u32 s17, s17, 0
	global_load_ushort v35, v2, s[16:17]
	s_add_u32 s16, s16, 0x40000
	s_addc_u32 s17, s17, 0
	ds_read_b32 v76, v70 offset:32768
	ds_read_b32 v77, v70 offset:33280
	ds_read_b32 v78, v70 offset:33792
	ds_read_b32 v79, v70 offset:34304
	ds_read_b32 v80, v70 offset:34816
	ds_read_b32 v81, v70 offset:35328
	ds_read_b32 v82, v70 offset:35840
	ds_read_b32 v83, v70 offset:36352
	s_waitcnt vmcnt(63)
	s_waitcnt lgkmcnt(0)
; __device__ __forceinline__ int otid() { int t = threadIdx.x; asm volatile("" : "+v"(t)); return t; }
; __device__ __forceinline__ int obid() { int t = blockIdx.x; asm volatile("" : "+s"(t)); return t; }
; __device__ __forceinline__ int ogdim() { int t = gridDim.x; asm volatile("" : "+s"(t)); return t; }
; #define SLOAD(U_, D_, n0_) do { _Pragma("unroll") for (int j = 0; j < 16; ++j) { U_[j] = bf2f(sbuf[(size_t)((n0_) + j) * 131072 + e]); D_[j] = decg[(size_t)((n0_) + j) * 512 + dcol]; } } while (0)
; #define SPROC(U_, D_, n0_) do { _Pragma("unroll") for (int j = 0; j < 16; ++j) { sbuf[(size_t)((n0_) + j) * 131072 + e] = f2bf(st); st = D_[j] * st + U_[j]; } } while (0)
; __device__ __forceinline__ void gla_scan(const Params& p) {
;     ...
;     for (int e = obid() * NTHREADS + otid(); e < 4 * 256 * 128; e += ogdim() * NTHREADS) {
;         const int dcol = (e >> 15) * 128 + (e & 127); float st = 0.f;
;         float u0[16], d0[16], u1[16], d1[16];
;     ...
;         SLOAD(u0, d0, 0);
; #pragma unroll 1
;         for (int n0 = 0; n0 < 256; n0 += 32) {
;             SLOAD(u1, d1, n0 + 16);
;             SPROC(u0, d0, n0);
;             if (n0 + 32 < 256) SLOAD(u0, d0, n0 + 32);
;             SPROC(u1, d1, n0 + 16);
;         }
	v_cvt_pk_bf16_f32 v72, v71, v71
	v_lshlrev_b32_e32 v74, 16, v36
	global_store_short v2, v72, s[98:99]
	s_add_u32 s98, s98, 0x40000
	s_addc_u32 s99, s99, 0
	v_fma_f32 v71, v76, v71, v74
	v_cvt_pk_bf16_f32 v73, v71, v71
	v_lshlrev_b32_e32 v74, 16, v37
	global_store_short v2, v73, s[98:99]
	s_add_u32 s98, s98, 0x40000
	s_addc_u32 s99, s99, 0
	v_fma_f32 v71, v77, v71, v74
	v_cvt_pk_bf16_f32 v72, v71, v71
	v_lshlrev_b32_e32 v74, 16, v38
	global_store_short v2, v72, s[98:99]
	s_add_u32 s98, s98, 0x40000
	s_addc_u32 s99, s99, 0
	v_fma_f32 v71, v78, v71, v74
	v_cvt_pk_bf16_f32 v73, v71, v71
	v_lshlrev_b32_e32 v74, 16, v39
	global_store_short v2, v73, s[98:99]
	s_add_u32 s98, s98, 0x40000
	s_addc_u32 s99, s99, 0
	v_fma_f32 v71, v79, v71, v74
	v_cvt_pk_bf16_f32 v72, v71, v71
	v_lshlrev_b32_e32 v74, 16, v40
	global_store_short v2, v72, s[98:99]
	s_add_u32 s98, s98, 0x40000
	s_addc_u32 s99, s99, 0
	v_fma_f32 v71, v80, v71, v74
	v_cvt_pk_bf16_f32 v73, v71, v71
	v_lshlrev_b32_e32 v74, 16, v41
	global_store_short v2, v73, s[98:99]
	s_add_u32 s98, s98, 0x40000
	s_addc_u32 s99, s99, 0
	v_fma_f32 v71, v81, v71, v74
	v_cvt_pk_bf16_f32 v72, v71, v71
	v_lshlrev_b32_e32 v74, 16, v42
	global_store_short v2, v72, s[98:99]
	s_add_u32 s98, s98, 0x40000
	s_addc_u32 s99, s99, 0
	v_fma_f32 v71, v82, v71, v74
	v_cvt_pk_bf16_f32 v73, v71, v71
	v_lshlrev_b32_e32 v74, 16, v43
	global_store_short v2, v73, s[98:99]
	s_add_u32 s98, s98, 0x40000
	s_addc_u32 s99, s99, 0
	v_fma_f32 v71, v83, v71, v74
	global_load_ushort v36, v2, s[16:17]
	s_add_u32 s16, s16, 0x40000
	s_addc_u32 s17, s17, 0
	global_load_ushort v37, v2, s[16:17]
	s_add_u32 s16, s16, 0x40000
	s_addc_u32 s17, s17, 0
	global_load_ushort v38, v2, s[16:17]
	s_add_u32 s16, s16, 0x40000
	s_addc_u32 s17, s17, 0
	global_load_ushort v39, v2, s[16:17]
	s_add_u32 s16, s16, 0x40000
	s_addc_u32 s17, s17, 0
	global_load_ushort v40, v2, s[16:17]
	s_add_u32 s16, s16, 0x40000
	s_addc_u32 s17, s17, 0
	global_load_ushort v41, v2, s[16:17]
	s_add_u32 s16, s16, 0x40000
	s_addc_u32 s17, s17, 0
	global_load_ushort v42, v2, s[16:17]
	s_add_u32 s16, s16, 0x40000
	s_addc_u32 s17, s17, 0
	global_load_ushort v43, v2, s[16:17]
	s_add_u32 s16, s16, 0x40000
	s_addc_u32 s17, s17, 0
	ds_read_b32 v76, v70 offset:36864
	ds_read_b32 v77, v70 offset:37376
	ds_read_b32 v78, v70 offset:37888
	ds_read_b32 v79, v70 offset:38400
	ds_read_b32 v80, v70 offset:38912
	ds_read_b32 v81, v70 offset:39424
	ds_read_b32 v82, v70 offset:39936
	ds_read_b32 v83, v70 offset:40448
	s_waitcnt vmcnt(63)
	s_waitcnt lgkmcnt(0)
	v_cvt_pk_bf16_f32 v72, v71, v71
	v_lshlrev_b32_e32 v74, 16, v4
	global_store_short v2, v72, s[98:99]
	s_add_u32 s98, s98, 0x40000
	s_addc_u32 s99, s99, 0
	v_fma_f32 v71, v76, v71, v74
	v_cvt_pk_bf16_f32 v73, v71, v71
	v_lshlrev_b32_e32 v74, 16, v5
	global_store_short v2, v73, s[98:99]
	s_add_u32 s98, s98, 0x40000
	s_addc_u32 s99, s99, 0
	v_fma_f32 v71, v77, v71, v74
	v_cvt_pk_bf16_f32 v72, v71, v71
	v_lshlrev_b32_e32 v74, 16, v6
	global_store_short v2, v72, s[98:99]
	s_add_u32 s98, s98, 0x40000
	s_addc_u32 s99, s99, 0
	v_fma_f32 v71, v78, v71, v74
	v_cvt_pk_bf16_f32 v73, v71, v71
	v_lshlrev_b32_e32 v74, 16, v7
	global_store_short v2, v73, s[98:99]
	s_add_u32 s98, s98, 0x40000
	s_addc_u32 s99, s99, 0
	v_fma_f32 v71, v79, v71, v74
	v_cvt_pk_bf16_f32 v72, v71, v71
	v_lshlrev_b32_e32 v74, 16, v8
	global_store_short v2, v72, s[98:99]
	s_add_u32 s98, s98, 0x40000
	s_addc_u32 s99, s99, 0
	v_fma_f32 v71, v80, v71, v74
	v_cvt_pk_bf16_f32 v73, v71, v71
	v_lshlrev_b32_e32 v74, 16, v9
	global_store_short v2, v73, s[98:99]
	s_add_u32 s98, s98, 0x40000
	s_addc_u32 s99, s99, 0
	v_fma_f32 v71, v81, v71, v74
	v_cvt_pk_bf16_f32 v72, v71, v71
	v_lshlrev_b32_e32 v74, 16, v10
	global_store_short v2, v72, s[98:99]
	s_add_u32 s98, s98, 0x40000
	s_addc_u32 s99, s99, 0
	v_fma_f32 v71, v82, v71, v74
	v_cvt_pk_bf16_f32 v73, v71, v71
	v_lshlrev_b32_e32 v74, 16, v11
	global_store_short v2, v73, s[98:99]
	s_add_u32 s98, s98, 0x40000
	s_addc_u32 s99, s99, 0
	v_fma_f32 v71, v83, v71, v74
	global_load_ushort v4, v2, s[16:17]
	s_add_u32 s16, s16, 0x40000
	s_addc_u32 s17, s17, 0
	global_load_ushort v5, v2, s[16:17]
	s_add_u32 s16, s16, 0x40000
	s_addc_u32 s17, s17, 0
	global_load_ushort v6, v2, s[16:17]
	s_add_u32 s16, s16, 0x40000
	s_addc_u32 s17, s17, 0
	global_load_ushort v7, v2, s[16:17]
	s_add_u32 s16, s16, 0x40000
	s_addc_u32 s17, s17, 0
	global_load_ushort v8, v2, s[16:17]
	s_add_u32 s16, s16, 0x40000
	s_addc_u32 s17, s17, 0
	global_load_ushort v9, v2, s[16:17]
	s_add_u32 s16, s16, 0x40000
	s_addc_u32 s17, s17, 0
	global_load_ushort v10, v2, s[16:17]
	s_add_u32 s16, s16, 0x40000
	s_addc_u32 s17, s17, 0
	global_load_ushort v11, v2, s[16:17]
	s_add_u32 s16, s16, 0x40000
	s_addc_u32 s17, s17, 0
	ds_read_b32 v76, v70 offset:40960
	ds_read_b32 v77, v70 offset:41472
	ds_read_b32 v78, v70 offset:41984
	ds_read_b32 v79, v70 offset:42496
	ds_read_b32 v80, v70 offset:43008
	ds_read_b32 v81, v70 offset:43520
	ds_read_b32 v82, v70 offset:44032
	ds_read_b32 v83, v70 offset:44544
	s_waitcnt vmcnt(63)
	s_waitcnt lgkmcnt(0)
; __device__ __forceinline__ int otid() { int t = threadIdx.x; asm volatile("" : "+v"(t)); return t; }
; __device__ __forceinline__ int obid() { int t = blockIdx.x; asm volatile("" : "+s"(t)); return t; }
; __device__ __forceinline__ int ogdim() { int t = gridDim.x; asm volatile("" : "+s"(t)); return t; }
; #define SLOAD(U_, D_, n0_) do { _Pragma("unroll") for (int j = 0; j < 16; ++j) { U_[j] = bf2f(sbuf[(size_t)((n0_) + j) * 131072 + e]); D_[j] = decg[(size_t)((n0_) + j) * 512 + dcol]; } } while (0)
; #define SPROC(U_, D_, n0_) do { _Pragma("unroll") for (int j = 0; j < 16; ++j) { sbuf[(size_t)((n0_) + j) * 131072 + e] = f2bf(st); st = D_[j] * st + U_[j]; } } while (0)
; __device__ __forceinline__ void gla_scan(const Params& p) {
;     ...
;     for (int e = obid() * NTHREADS + otid(); e < 4 * 256 * 128; e += ogdim() * NTHREADS) {
;         const int dcol = (e >> 15) * 128 + (e & 127); float st = 0.f;
;         float u0[16], d0[16], u1[16], d1[16];
;     ...
;         SLOAD(u0, d0, 0);
; #pragma unroll 1
;         for (int n0 = 0; n0 < 256; n0 += 32) {
;             SLOAD(u1, d1, n0 + 16);
;             SPROC(u0, d0, n0);
;             if (n0 + 32 < 256) SLOAD(u0, d0, n0 + 32);
;             SPROC(u1, d1, n0 + 16);
;         }
	v_cvt_pk_bf16_f32 v72, v71, v71
	v_lshlrev_b32_e32 v74, 16, v12
	global_store_short v2, v72, s[98:99]
	s_add_u32 s98, s98, 0x40000
	s_addc_u32 s99, s99, 0
	v_fma_f32 v71, v76, v71, v74
	v_cvt_pk_bf16_f32 v73, v71, v71
	v_lshlrev_b32_e32 v74, 16, v13
	global_store_short v2, v73, s[98:99]
	s_add_u32 s98, s98, 0x40000
	s_addc_u32 s99, s99, 0
	v_fma_f32 v71, v77, v71, v74
	v_cvt_pk_bf16_f32 v72, v71, v71
	v_lshlrev_b32_e32 v74, 16, v14
	global_store_short v2, v72, s[98:99]
	s_add_u32 s98, s98, 0x40000
	s_addc_u32 s99, s99, 0
	v_fma_f32 v71, v78, v71, v74
	v_cvt_pk_bf16_f32 v73, v71, v71
	v_lshlrev_b32_e32 v74, 16, v15
	global_store_short v2, v73, s[98:99]
	s_add_u32 s98, s98, 0x40000
	s_addc_u32 s99, s99, 0
	v_fma_f32 v71, v79, v71, v74
	v_cvt_pk_bf16_f32 v72, v71, v71
	v_lshlrev_b32_e32 v74, 16, v16
	global_store_short v2, v72, s[98:99]
	s_add_u32 s98, s98, 0x40000
	s_addc_u32 s99, s99, 0
	v_fma_f32 v71, v80, v71, v74
	v_cvt_pk_bf16_f32 v73, v71, v71
	v_lshlrev_b32_e32 v74, 16, v17
	global_store_short v2, v73, s[98:99]
	s_add_u32 s98, s98, 0x40000
	s_addc_u32 s99, s99, 0
	v_fma_f32 v71, v81, v71, v74
	v_cvt_pk_bf16_f32 v72, v71, v71
	v_lshlrev_b32_e32 v74, 16, v18
	global_store_short v2, v72, s[98:99]
	s_add_u32 s98, s98, 0x40000
	s_addc_u32 s99, s99, 0
	v_fma_f32 v71, v82, v71, v74
	v_cvt_pk_bf16_f32 v73, v71, v71
	v_lshlrev_b32_e32 v74, 16, v19
	global_store_short v2, v73, s[98:99]
	s_add_u32 s98, s98, 0x40000
	s_addc_u32 s99, s99, 0
	v_fma_f32 v71, v83, v71, v74
	global_load_ushort v12, v2, s[16:17]
	s_add_u32 s16, s16, 0x40000
	s_addc_u32 s17, s17, 0
	global_load_ushort v13, v2, s[16:17]
	s_add_u32 s16, s16, 0x40000
	s_addc_u32 s17, s17, 0
	global_load_ushort v14, v2, s[16:17]
	s_add_u32 s16, s16, 0x40000
	s_addc_u32 s17, s17, 0
	global_load_ushort v15, v2, s[16:17]
	s_add_u32 s16, s16, 0x40000
	s_addc_u32 s17, s17, 0
	global_load_ushort v16, v2, s[16:17]
	s_add_u32 s16, s16, 0x40000
	s_addc_u32 s17, s17, 0
	global_load_ushort v17, v2, s[16:17]
	s_add_u32 s16, s16, 0x40000
	s_addc_u32 s17, s17, 0
	global_load_ushort v18, v2, s[16:17]
	s_add_u32 s16, s16, 0x40000
	s_addc_u32 s17, s17, 0
	global_load_ushort v19, v2, s[16:17]
	s_add_u32 s16, s16, 0x40000
	s_addc_u32 s17, s17, 0
	ds_read_b32 v76, v70 offset:45056
	ds_read_b32 v77, v70 offset:45568
	ds_read_b32 v78, v70 offset:46080
	ds_read_b32 v79, v70 offset:46592
	ds_read_b32 v80, v70 offset:47104
	ds_read_b32 v81, v70 offset:47616
	ds_read_b32 v82, v70 offset:48128
	ds_read_b32 v83, v70 offset:48640
	s_waitcnt vmcnt(63)
	s_waitcnt lgkmcnt(0)
	v_cvt_pk_bf16_f32 v72, v71, v71
	v_lshlrev_b32_e32 v74, 16, v20
	global_store_short v2, v72, s[98:99]
	s_add_u32 s98, s98, 0x40000
	s_addc_u32 s99, s99, 0
	v_fma_f32 v71, v76, v71, v74
	v_cvt_pk_bf16_f32 v73, v71, v71
	v_lshlrev_b32_e32 v74, 16, v21
	global_store_short v2, v73, s[98:99]
	s_add_u32 s98, s98, 0x40000
	s_addc_u32 s99, s99, 0
	v_fma_f32 v71, v77, v71, v74
	v_cvt_pk_bf16_f32 v72, v71, v71
	v_lshlrev_b32_e32 v74, 16, v22
	global_store_short v2, v72, s[98:99]
	s_add_u32 s98, s98, 0x40000
	s_addc_u32 s99, s99, 0
	v_fma_f32 v71, v78, v71, v74
	v_cvt_pk_bf16_f32 v73, v71, v71
	v_lshlrev_b32_e32 v74, 16, v23
	global_store_short v2, v73, s[98:99]
	s_add_u32 s98, s98, 0x40000
	s_addc_u32 s99, s99, 0
	v_fma_f32 v71, v79, v71, v74
	v_cvt_pk_bf16_f32 v72, v71, v71
	v_lshlrev_b32_e32 v74, 16, v24
	global_store_short v2, v72, s[98:99]
	s_add_u32 s98, s98, 0x40000
	s_addc_u32 s99, s99, 0
	v_fma_f32 v71, v80, v71, v74
	v_cvt_pk_bf16_f32 v73, v71, v71
	v_lshlrev_b32_e32 v74, 16, v25
	global_store_short v2, v73, s[98:99]
	s_add_u32 s98, s98, 0x40000
	s_addc_u32 s99, s99, 0
	v_fma_f32 v71, v81, v71, v74
	v_cvt_pk_bf16_f32 v72, v71, v71
	v_lshlrev_b32_e32 v74, 16, v26
	global_store_short v2, v72, s[98:99]
	s_add_u32 s98, s98, 0x40000
	s_addc_u32 s99, s99, 0
	v_fma_f32 v71, v82, v71, v74
	v_cvt_pk_bf16_f32 v73, v71, v71
	v_lshlrev_b32_e32 v74, 16, v27
	global_store_short v2, v73, s[98:99]
	s_add_u32 s98, s98, 0x40000
	s_addc_u32 s99, s99, 0
	v_fma_f32 v71, v83, v71, v74
	ds_read_b32 v76, v70 offset:49152
	ds_read_b32 v77, v70 offset:49664
	ds_read_b32 v78, v70 offset:50176
	ds_read_b32 v79, v70 offset:50688
	ds_read_b32 v80, v70 offset:51200
	ds_read_b32 v81, v70 offset:51712
	ds_read_b32 v82, v70 offset:52224
	ds_read_b32 v83, v70 offset:52736
	s_waitcnt vmcnt(56)
	s_waitcnt lgkmcnt(0)
	v_cvt_pk_bf16_f32 v72, v71, v71
	v_lshlrev_b32_e32 v74, 16, v28
	global_store_short v2, v72, s[98:99]
	s_add_u32 s98, s98, 0x40000
	s_addc_u32 s99, s99, 0
	v_fma_f32 v71, v76, v71, v74
	v_cvt_pk_bf16_f32 v73, v71, v71
	v_lshlrev_b32_e32 v74, 16, v29
	global_store_short v2, v73, s[98:99]
	s_add_u32 s98, s98, 0x40000
	s_addc_u32 s99, s99, 0
	v_fma_f32 v71, v77, v71, v74
	v_cvt_pk_bf16_f32 v72, v71, v71
	v_lshlrev_b32_e32 v74, 16, v30
	global_store_short v2, v72, s[98:99]
	s_add_u32 s98, s98, 0x40000
	s_addc_u32 s99, s99, 0
	v_fma_f32 v71, v78, v71, v74
	v_cvt_pk_bf16_f32 v73, v71, v71
	v_lshlrev_b32_e32 v74, 16, v31
	global_store_short v2, v73, s[98:99]
	s_add_u32 s98, s98, 0x40000
	s_addc_u32 s99, s99, 0
	v_fma_f32 v71, v79, v71, v74
	v_cvt_pk_bf16_f32 v72, v71, v71
	v_lshlrev_b32_e32 v74, 16, v32
	global_store_short v2, v72, s[98:99]
	s_add_u32 s98, s98, 0x40000
	s_addc_u32 s99, s99, 0
	v_fma_f32 v71, v80, v71, v74
	v_cvt_pk_bf16_f32 v73, v71, v71
	v_lshlrev_b32_e32 v74, 16, v33
	global_store_short v2, v73, s[98:99]
	s_add_u32 s98, s98, 0x40000
	s_addc_u32 s99, s99, 0
	v_fma_f32 v71, v81, v71, v74
	v_cvt_pk_bf16_f32 v72, v71, v71
	v_lshlrev_b32_e32 v74, 16, v34
	global_store_short v2, v72, s[98:99]
	s_add_u32 s98, s98, 0x40000
	s_addc_u32 s99, s99, 0
	v_fma_f32 v71, v82, v71, v74
	v_cvt_pk_bf16_f32 v73, v71, v71
	v_lshlrev_b32_e32 v74, 16, v35
	global_store_short v2, v73, s[98:99]
	s_add_u32 s98, s98, 0x40000
	s_addc_u32 s99, s99, 0
	v_fma_f32 v71, v83, v71, v74
	ds_read_b32 v76, v70 offset:53248
	ds_read_b32 v77, v70 offset:53760
	ds_read_b32 v78, v70 offset:54272
	ds_read_b32 v79, v70 offset:54784
	ds_read_b32 v80, v70 offset:55296
	ds_read_b32 v81, v70 offset:55808
	ds_read_b32 v82, v70 offset:56320
	ds_read_b32 v83, v70 offset:56832
	s_waitcnt vmcnt(48)
; __device__ __forceinline__ int otid() { int t = threadIdx.x; asm volatile("" : "+v"(t)); return t; }
; __device__ __forceinline__ int obid() { int t = blockIdx.x; asm volatile("" : "+s"(t)); return t; }
; __device__ __forceinline__ int ogdim() { int t = gridDim.x; asm volatile("" : "+s"(t)); return t; }
; #define SLOAD(U_, D_, n0_) do { _Pragma("unroll") for (int j = 0; j < 16; ++j) { U_[j] = bf2f(sbuf[(size_t)((n0_) + j) * 131072 + e]); D_[j] = decg[(size_t)((n0_) + j) * 512 + dcol]; } } while (0)
; #define SPROC(U_, D_, n0_) do { _Pragma("unroll") for (int j = 0; j < 16; ++j) { sbuf[(size_t)((n0_) + j) * 131072 + e] = f2bf(st); st = D_[j] * st + U_[j]; } } while (0)
; __device__ __forceinline__ void gla_scan(const Params& p) {
;     ...
;     for (int e = obid() * NTHREADS + otid(); e < 4 * 256 * 128; e += ogdim() * NTHREADS) {
;         const int dcol = (e >> 15) * 128 + (e & 127); float st = 0.f;
;         float u0[16], d0[16], u1[16], d1[16];
;     ...
;         SLOAD(u0, d0, 0);
; #pragma unroll 1
;         for (int n0 = 0; n0 < 256; n0 += 32) {
;             SLOAD(u1, d1, n0 + 16);
;             SPROC(u0, d0, n0);
;             if (n0 + 32 < 256) SLOAD(u0, d0, n0 + 32);
;             SPROC(u1, d1, n0 + 16);
;         }
	s_waitcnt lgkmcnt(0)
	v_cvt_pk_bf16_f32 v72, v71, v71
	v_lshlrev_b32_e32 v74, 16, v36
	global_store_short v2, v72, s[98:99]
	s_add_u32 s98, s98, 0x40000
	s_addc_u32 s99, s99, 0
	v_fma_f32 v71, v76, v71, v74
	v_cvt_pk_bf16_f32 v73, v71, v71
	v_lshlrev_b32_e32 v74, 16, v37
	global_store_short v2, v73, s[98:99]
	s_add_u32 s98, s98, 0x40000
	s_addc_u32 s99, s99, 0
	v_fma_f32 v71, v77, v71, v74
	v_cvt_pk_bf16_f32 v72, v71, v71
	v_lshlrev_b32_e32 v74, 16, v38
	global_store_short v2, v72, s[98:99]
	s_add_u32 s98, s98, 0x40000
	s_addc_u32 s99, s99, 0
	v_fma_f32 v71, v78, v71, v74
	v_cvt_pk_bf16_f32 v73, v71, v71
	v_lshlrev_b32_e32 v74, 16, v39
	global_store_short v2, v73, s[98:99]
	s_add_u32 s98, s98, 0x40000
	s_addc_u32 s99, s99, 0
	v_fma_f32 v71, v79, v71, v74
	v_cvt_pk_bf16_f32 v72, v71, v71
	v_lshlrev_b32_e32 v74, 16, v40
	global_store_short v2, v72, s[98:99]
	s_add_u32 s98, s98, 0x40000
	s_addc_u32 s99, s99, 0
	v_fma_f32 v71, v80, v71, v74
	v_cvt_pk_bf16_f32 v73, v71, v71
	v_lshlrev_b32_e32 v74, 16, v41
	global_store_short v2, v73, s[98:99]
	s_add_u32 s98, s98, 0x40000
	s_addc_u32 s99, s99, 0
	v_fma_f32 v71, v81, v71, v74
	v_cvt_pk_bf16_f32 v72, v71, v71
	v_lshlrev_b32_e32 v74, 16, v42
	global_store_short v2, v72, s[98:99]
	s_add_u32 s98, s98, 0x40000
	s_addc_u32 s99, s99, 0
	v_fma_f32 v71, v82, v71, v74
	v_cvt_pk_bf16_f32 v73, v71, v71
	v_lshlrev_b32_e32 v74, 16, v43
	global_store_short v2, v73, s[98:99]
	s_add_u32 s98, s98, 0x40000
	s_addc_u32 s99, s99, 0
	v_fma_f32 v71, v83, v71, v74
	ds_read_b32 v76, v70 offset:57344
	ds_read_b32 v77, v70 offset:57856
	ds_read_b32 v78, v70 offset:58368
	ds_read_b32 v79, v70 offset:58880
	ds_read_b32 v80, v70 offset:59392
	ds_read_b32 v81, v70 offset:59904
	ds_read_b32 v82, v70 offset:60416
	ds_read_b32 v83, v70 offset:60928
	s_waitcnt vmcnt(40)
	s_waitcnt lgkmcnt(0)
	v_cvt_pk_bf16_f32 v72, v71, v71
	v_lshlrev_b32_e32 v74, 16, v4
	global_store_short v2, v72, s[98:99]
	s_add_u32 s98, s98, 0x40000
	s_addc_u32 s99, s99, 0
	v_fma_f32 v71, v76, v71, v74
	v_cvt_pk_bf16_f32 v73, v71, v71
	v_lshlrev_b32_e32 v74, 16, v5
	global_store_short v2, v73, s[98:99]
	s_add_u32 s98, s98, 0x40000
	s_addc_u32 s99, s99, 0
	v_fma_f32 v71, v77, v71, v74
	v_cvt_pk_bf16_f32 v72, v71, v71
	v_lshlrev_b32_e32 v74, 16, v6
	global_store_short v2, v72, s[98:99]
	s_add_u32 s98, s98, 0x40000
	s_addc_u32 s99, s99, 0
	v_fma_f32 v71, v78, v71, v74
	v_cvt_pk_bf16_f32 v73, v71, v71
	v_lshlrev_b32_e32 v74, 16, v7
	global_store_short v2, v73, s[98:99]
	s_add_u32 s98, s98, 0x40000
	s_addc_u32 s99, s99, 0
	v_fma_f32 v71, v79, v71, v74
	v_cvt_pk_bf16_f32 v72, v71, v71
	v_lshlrev_b32_e32 v74, 16, v8
	global_store_short v2, v72, s[98:99]
	s_add_u32 s98, s98, 0x40000
	s_addc_u32 s99, s99, 0
	v_fma_f32 v71, v80, v71, v74
	v_cvt_pk_bf16_f32 v73, v71, v71
	v_lshlrev_b32_e32 v74, 16, v9
	global_store_short v2, v73, s[98:99]
	s_add_u32 s98, s98, 0x40000
	s_addc_u32 s99, s99, 0
	v_fma_f32 v71, v81, v71, v74
	v_cvt_pk_bf16_f32 v72, v71, v71
	v_lshlrev_b32_e32 v74, 16, v10
	global_store_short v2, v72, s[98:99]
	s_add_u32 s98, s98, 0x40000
	s_addc_u32 s99, s99, 0
	v_fma_f32 v71, v82, v71, v74
	v_cvt_pk_bf16_f32 v73, v71, v71
	v_lshlrev_b32_e32 v74, 16, v11
	global_store_short v2, v73, s[98:99]
	s_add_u32 s98, s98, 0x40000
	s_addc_u32 s99, s99, 0
	v_fma_f32 v71, v83, v71, v74
	ds_read_b32 v76, v70 offset:61440
	ds_read_b32 v77, v70 offset:61952
	ds_read_b32 v78, v70 offset:62464
	ds_read_b32 v79, v70 offset:62976
	ds_read_b32 v80, v70 offset:63488
	ds_read_b32 v81, v70 offset:64000
	ds_read_b32 v82, v70 offset:64512
	ds_read_b32 v83, v70 offset:65024
	s_waitcnt vmcnt(32)
	s_waitcnt lgkmcnt(0)
	v_cvt_pk_bf16_f32 v72, v71, v71
	v_lshlrev_b32_e32 v74, 16, v12
	global_store_short v2, v72, s[98:99]
	s_add_u32 s98, s98, 0x40000
	s_addc_u32 s99, s99, 0
	v_fma_f32 v71, v76, v71, v74
	v_cvt_pk_bf16_f32 v73, v71, v71
	v_lshlrev_b32_e32 v74, 16, v13
	global_store_short v2, v73, s[98:99]
	s_add_u32 s98, s98, 0x40000
	s_addc_u32 s99, s99, 0
	v_fma_f32 v71, v77, v71, v74
	v_cvt_pk_bf16_f32 v72, v71, v71
	v_lshlrev_b32_e32 v74, 16, v14
	global_store_short v2, v72, s[98:99]
	s_add_u32 s98, s98, 0x40000
	s_addc_u32 s99, s99, 0
	v_fma_f32 v71, v78, v71, v74
	v_cvt_pk_bf16_f32 v73, v71, v71
	v_lshlrev_b32_e32 v74, 16, v15
	global_store_short v2, v73, s[98:99]
	s_add_u32 s98, s98, 0x40000
	s_addc_u32 s99, s99, 0
	v_fma_f32 v71, v79, v71, v74
	v_cvt_pk_bf16_f32 v72, v71, v71
	v_lshlrev_b32_e32 v74, 16, v16
	global_store_short v2, v72, s[98:99]
	s_add_u32 s98, s98, 0x40000
	s_addc_u32 s99, s99, 0
	v_fma_f32 v71, v80, v71, v74
	v_cvt_pk_bf16_f32 v73, v71, v71
	v_lshlrev_b32_e32 v74, 16, v17
	global_store_short v2, v73, s[98:99]
	s_add_u32 s98, s98, 0x40000
	s_addc_u32 s99, s99, 0
	v_fma_f32 v71, v81, v71, v74
	v_cvt_pk_bf16_f32 v72, v71, v71
	v_lshlrev_b32_e32 v74, 16, v18
	global_store_short v2, v72, s[98:99]
	s_add_u32 s98, s98, 0x40000
	s_addc_u32 s99, s99, 0
	v_fma_f32 v71, v82, v71, v74
	v_cvt_pk_bf16_f32 v73, v71, v71
	v_lshlrev_b32_e32 v74, 16, v19
	global_store_short v2, v73, s[98:99]
	s_add_u32 s98, s98, 0x40000
	s_addc_u32 s99, s99, 0
	v_fma_f32 v71, v83, v71, v74
	s_waitcnt lgkmcnt(0)
	s_add_i32 s44, s44, s96
	s_barrier
	s_branch .Lmy_sc_blk
.Lmy_sc_done:
.LBB0_477:
	s_or_b64 exec, exec, s[12:13]

; #define LAS __attribute__((address_space(3)))
; #define LOAD_PARAMS(q_) const __attribute__((address_space(4))) Params* kq_##q_ = (const __attribute__((address_space(4))) Params*)__builtin_amdgcn_kernarg_segment_ptr(); asm volatile("" : "+s"(kq_##q_)); \
;     const Params q_ = *kq_##q_
; __global__ void __launch_bounds__(NTHREADS, 2) mega_fwd(Params p_unused) {
;     extern __shared__ __attribute__((aligned(16))) unsigned char smem[];
;     LAS unsigned char* lds = (LAS unsigned char*)smem;
;     cg::grid_group grid = cg::this_grid();
;     ...
;     volatile LAS unsigned* xst = (volatile LAS unsigned*)(lds + LDS_BYTES - 16);
;     if (threadIdx.x < 4) xst[threadIdx.x] = 0u;
;     __syncthreads();
;     XcdBarrier gbar; { LOAD_PARAMS(p0_); gbar = xcd_barrier_post((unsigned*)(p0_.ws + O_BAR), xst); }
	.amdhsa_kernel _Z8mega_fwd6Params
		.amdhsa_group_segment_fixed_size 0
		.amdhsa_private_segment_fixed_size 0
		.amdhsa_kernarg_size 408
		.amdhsa_user_sgpr_count 2
		.amdhsa_user_sgpr_dispatch_ptr 0
		.amdhsa_user_sgpr_queue_ptr 0
		.amdhsa_user_sgpr_kernarg_segment_ptr 1
		.amdhsa_user_sgpr_dispatch_id 0
		.amdhsa_user_sgpr_kernarg_preload_length 0
		.amdhsa_user_sgpr_kernarg_preload_offset 0
		.amdhsa_user_sgpr_private_segment_size 0
		.amdhsa_uses_dynamic_stack 0
		.amdhsa_enable_private_segment 0
		.amdhsa_system_sgpr_workgroup_id_x 1
		.amdhsa_system_sgpr_workgroup_id_y 0
		.amdhsa_system_sgpr_workgroup_id_z 0
		.amdhsa_system_sgpr_workgroup_info 0
		.amdhsa_system_vgpr_workitem_id 2
		.amdhsa_next_free_vgpr 256
		.amdhsa_next_free_sgpr 102
		.amdhsa_accum_offset 256
		.amdhsa_reserve_vcc 1
		.amdhsa_float_round_mode_32 0
		.amdhsa_float_round_mode_16_64 0
		.amdhsa_float_denorm_mode_32 3
		.amdhsa_float_denorm_mode_16_64 3
		.amdhsa_dx10_clamp 1
		.amdhsa_ieee_mode 1
		.amdhsa_fp16_overflow 0
		.amdhsa_tg_split 0
		.amdhsa_exception_fp_ieee_invalid_op 0
		.amdhsa_exception_fp_denorm_src 0
		.amdhsa_exception_fp_ieee_div_zero 0
		.amdhsa_exception_fp_ieee_overflow 0
		.amdhsa_exception_fp_ieee_underflow 0
		.amdhsa_exception_fp_ieee_inexact 0
		.amdhsa_exception_int_div_zero 0
	.end_amdhsa_kernel

; #define LAS __attribute__((address_space(3)))
; #define LOAD_PARAMS(q_) const __attribute__((address_space(4))) Params* kq_##q_ = (const __attribute__((address_space(4))) Params*)__builtin_amdgcn_kernarg_segment_ptr(); asm volatile("" : "+s"(kq_##q_)); \
;     const Params q_ = *kq_##q_
; __global__ void __launch_bounds__(NTHREADS, 2) mega_fwd(Params p_unused) {
;     extern __shared__ __attribute__((aligned(16))) unsigned char smem[];
;     LAS unsigned char* lds = (LAS unsigned char*)smem;
;     cg::grid_group grid = cg::this_grid();
;     ...
;     volatile LAS unsigned* xst = (volatile LAS unsigned*)(lds + LDS_BYTES - 16);
;     if (threadIdx.x < 4) xst[threadIdx.x] = 0u;
;     __syncthreads();
;     XcdBarrier gbar; { LOAD_PARAMS(p0_); gbar = xcd_barrier_post((unsigned*)(p0_.ws + O_BAR), xst); }
amdhsa.kernels:
  - .agpr_count:     0
    .args:
      - .offset:         0
        .size:           152
        .value_kind:     by_value
      - .offset:         152
        .size:           4
        .value_kind:     hidden_block_count_x
      - .offset:         156
        .size:           4
        .value_kind:     hidden_block_count_y
      - .offset:         160
        .size:           4
        .value_kind:     hidden_block_count_z
      - .offset:         164
        .size:           2
        .value_kind:     hidden_group_size_x
      - .offset:         166
        .size:           2
        .value_kind:     hidden_group_size_y
      - .offset:         168
        .size:           2
        .value_kind:     hidden_group_size_z
      - .offset:         170
        .size:           2
        .value_kind:     hidden_remainder_x
      - .offset:         172
        .size:           2
        .value_kind:     hidden_remainder_y
      - .offset:         174
        .size:           2
        .value_kind:     hidden_remainder_z
      - .offset:         192
        .size:           8
        .value_kind:     hidden_global_offset_x
      - .offset:         200
        .size:           8
        .value_kind:     hidden_global_offset_y
      - .offset:         208
        .size:           8
        .value_kind:     hidden_global_offset_z
      - .offset:         216
        .size:           2
        .value_kind:     hidden_grid_dims
      - .offset:         240
        .size:           8
        .value_kind:     hidden_multigrid_sync_arg
      - .offset:         272
        .size:           4
        .value_kind:     hidden_dynamic_lds_size
    .group_segment_fixed_size: 0
    .kernarg_segment_align: 8
    .kernarg_segment_size: 408
    .language:       OpenCL C
    .language_version:
      - 2
      - 0
    .max_flat_workgroup_size: 512
    .name:           _Z8mega_fwd6Params
    .private_segment_fixed_size: 0
    .sgpr_count:     108
    .sgpr_spill_count: 233
    .symbol:         _Z8mega_fwd6Params.kd
    .uniform_work_group_size: 1
    .uses_dynamic_stack: false
    .vgpr_count:     256
    .vgpr_spill_count: 0
    .wavefront_size: 64
